# EpiResid: f32 residual-stream stores issued non-temporal (nt), bf16 copies stay default
# speedup vs baseline: 1.0164x; 1.0079x over previous
; #define PG8_STAGE(bufoff, gbase, voff) do { _Pragma("unroll") for (int _i = 0; _i < 2; ++_i) \
;         __builtin_amdgcn_global_load_lds((const unsigned*)((const char*)(gbase) + (voff)[_i]), (LAS unsigned*)(lds + (bufoff) + ldsw + _i * 8192), 16, 0, 0); } while (0)
; #define PG8_LDA(dst, b, h) do { _Pragma("unroll") for (int m = 0; m < 4; ++m) _Pragma("unroll") for (int k = 0; k < 2; ++k) dst[m][k] = *(const LAS bf16x8*)(lds + PG8_SA(b, h) + aoff + m * 2048 + k * 1024); } while (0)
; #define PG8_LDB(dst, b, h) do { _Pragma("unroll") for (int n = 0; n < 2; ++n) _Pragma("unroll") for (int k = 0; k < 2; ++k) dst[n][k] = *(const LAS bf16x8*)(lds + PG8_SB(b, h) + boff + n * 2048 + k * 1024); } while (0)
; #define PG8_MMA(ai, bj, At, Bt) do { __builtin_amdgcn_s_setprio(1); _Pragma("unroll") for (int m = 0; m < 4; ++m) _Pragma("unroll") for (int n = 0; n < 2; ++n) _Pragma("unroll") for (int k = 0; k < 2; ++k) \
;         acc[ai][bj][m][n] = __builtin_amdgcn_mfma_f32_16x16x32_bf16(Bt[n][k], At[m][k], acc[ai][bj][m][n], 0, 0, 0); __builtin_amdgcn_s_setprio(0); } while (0)
; #define PG8_WAIT_L(n) asm volatile("s_waitcnt lgkmcnt(" #n ")" ::: "memory")
; #define PG8_BAR __builtin_amdgcn_s_barrier()
; #define PG8_SCHED __builtin_amdgcn_sched_barrier(0)
; template <class Epi>
; DEVI void gemm_phase(LAS unsigned char* lds, const Gemm g, const Epi& E) {
;     ...
;             PG8_LDB(B0, 0, 0); PG8_SCHED; PG8_LDA(At, 0, 0); PG8_STAGE(PG8_SA(1, 1), a1 + hstepA, voffA);
;             PG8_WAIT_L(8); PG8_BAR; PG8_WAIT_L(0); PG8_MMA(0, 0, At, B0); PG8_BAR; PG8_SCHED;
;             PG8_LDB(B1, 0, 1); PG8_STAGE(PG8_SB(0, 0), b2, voffB);
;             PG8_BAR; PG8_WAIT_L(0); PG8_MMA(0, 1, At, B1); PG8_BAR;
;             PG8_LDA(At, 0, 1); PG8_STAGE(PG8_SA(0, 0), a2, voffA);
;             PG8_BAR; PG8_WAIT_L(0); PG8_MMA(1, 0, At, B0); PG8_BAR; PG8_SCHED;
.LBB0_968:
	s_add_u32 s26, s68, 0xfffc0080
	s_addc_u32 s27, s69, -1
	s_add_i32 s38, 0, 0x10000
	v_add_u32_e32 v142, s38, v193
	ds_read_b128 v[130:133], v142
	ds_read_b128 v[134:137], v142 offset:1024
	ds_read_b128 v[138:141], v142 offset:2048
	ds_read_b128 v[142:145], v142 offset:3072
	s_cmp_eq_u32 s19, 12
	s_cselect_b32 s83, s0, s27
	s_cselect_b32 s82, s1, s26
	s_cselect_b32 s81, s9, s18
	s_cselect_b32 s80, s13, s15
	v_lshl_add_u64 v[162:163], s[68:69], 0, v[178:179]
	s_add_i32 m0, s85, 0xc000
	ds_read_b128 v[146:149], v198
	ds_read_b128 v[182:185], v198 offset:1024
	ds_read_b128 v[186:189], v198 offset:2048
	ds_read_b128 v[200:203], v198 offset:3072
	ds_read_b128 v[204:207], v198 offset:4096
	ds_read_b128 v[214:217], v198 offset:5120
	ds_read_b128 v[218:221], v198 offset:6144
	ds_read_b128 v[222:225], v198 offset:7168
	global_load_lds_dwordx4 v[162:163], off
	s_add_i32 m0, s85, 0xe000
	v_lshl_add_u64 v[162:163], s[68:69], 0, v[180:181]
	global_load_lds_dwordx4 v[162:163], off
	s_waitcnt lgkmcnt(8)
	s_barrier
	s_waitcnt lgkmcnt(0)
	v_mfma_f32_16x16x32_bf16 v[126:129], v[130:133], v[146:149], v[126:129]
	v_mfma_f32_16x16x32_bf16 v[122:125], v[138:141], v[146:149], v[122:125]
	v_mfma_f32_16x16x32_bf16 v[110:113], v[130:133], v[186:189], v[110:113]
	v_mfma_f32_16x16x32_bf16 v[106:109], v[138:141], v[186:189], v[106:109]
	v_mfma_f32_16x16x32_bf16 v[94:97], v[130:133], v[204:207], v[94:97]
	v_mfma_f32_16x16x32_bf16 v[90:93], v[138:141], v[204:207], v[90:93]
	v_mfma_f32_16x16x32_bf16 v[78:81], v[130:133], v[218:221], v[78:81]
	v_mfma_f32_16x16x32_bf16 v[74:77], v[138:141], v[218:221], v[74:77]
	v_mfma_f32_16x16x32_bf16 v[126:129], v[134:137], v[182:185], v[126:129]
	v_mfma_f32_16x16x32_bf16 v[122:125], v[142:145], v[182:185], v[122:125]
	v_mfma_f32_16x16x32_bf16 v[110:113], v[134:137], v[200:203], v[110:113]
	v_mfma_f32_16x16x32_bf16 v[106:109], v[142:145], v[200:203], v[106:109]
	v_mfma_f32_16x16x32_bf16 v[94:97], v[134:137], v[214:217], v[94:97]
	v_mfma_f32_16x16x32_bf16 v[90:93], v[142:145], v[214:217], v[90:93]
	v_mfma_f32_16x16x32_bf16 v[78:81], v[134:137], v[222:225], v[78:81]
	v_mfma_f32_16x16x32_bf16 v[74:77], v[142:145], v[222:225], v[74:77]
	s_barrier
	s_add_i32 s39, 0, 0x14000
	v_add_u32_e32 v162, s39, v193
	s_add_i32 s26, s38, s84
	ds_read_b128 v[226:229], v162
	ds_read_b128 v[230:233], v162 offset:1024
	ds_read_b128 v[234:237], v162 offset:2048
	ds_read_b128 v[238:241], v162 offset:3072
	v_lshl_add_u64 v[162:163], s[80:81], 0, v[8:9]
	s_mov_b32 m0, s26
	v_lshl_add_u64 v[164:165], s[80:81], 0, v[176:177]
	global_load_lds_dwordx4 v[162:163], off
	s_add_i32 m0, s26, 0x2000
	s_nop 0
	global_load_lds_dwordx4 v[164:165], off
	s_barrier
	s_waitcnt lgkmcnt(0)
	v_mfma_f32_16x16x32_bf16 v[118:121], v[226:229], v[146:149], v[118:121]
	v_mfma_f32_16x16x32_bf16 v[114:117], v[234:237], v[146:149], v[114:117]
	v_mfma_f32_16x16x32_bf16 v[102:105], v[226:229], v[186:189], v[102:105]
	v_mfma_f32_16x16x32_bf16 v[98:101], v[234:237], v[186:189], v[98:101]
	v_mfma_f32_16x16x32_bf16 v[86:89], v[226:229], v[204:207], v[86:89]
	v_mfma_f32_16x16x32_bf16 v[82:85], v[234:237], v[204:207], v[82:85]
	v_mfma_f32_16x16x32_bf16 v[70:73], v[226:229], v[218:221], v[70:73]
	v_mfma_f32_16x16x32_bf16 v[66:69], v[234:237], v[218:221], v[66:69]
	v_mfma_f32_16x16x32_bf16 v[118:121], v[230:233], v[182:185], v[118:121]
	v_mfma_f32_16x16x32_bf16 v[114:117], v[238:241], v[182:185], v[114:117]
	v_mfma_f32_16x16x32_bf16 v[102:105], v[230:233], v[200:203], v[102:105]
	v_mfma_f32_16x16x32_bf16 v[98:101], v[238:241], v[200:203], v[98:101]
	v_mfma_f32_16x16x32_bf16 v[86:89], v[230:233], v[214:217], v[86:89]
	v_mfma_f32_16x16x32_bf16 v[82:85], v[238:241], v[214:217], v[82:85]
	v_mfma_f32_16x16x32_bf16 v[70:73], v[230:233], v[222:225], v[70:73]
	v_mfma_f32_16x16x32_bf16 v[66:69], v[238:241], v[222:225], v[66:69]
	s_mov_b32 m0, s85
	v_lshl_add_u64 v[190:191], s[82:83], 0, v[150:151]
	s_barrier
	ds_read_b128 v[146:149], v198 offset:16384
	ds_read_b128 v[182:185], v198 offset:17408
	ds_read_b128 v[186:189], v198 offset:18432
	ds_read_b128 v[200:203], v198 offset:19456
	ds_read_b128 v[204:207], v198 offset:20480
	ds_read_b128 v[214:217], v198 offset:21504
	ds_read_b128 v[218:221], v198 offset:22528
	ds_read_b128 v[222:225], v198 offset:23552
	global_load_lds_dwordx4 v[190:191], off
	s_mov_b32 m0, s86
	v_lshl_add_u64 v[208:209], s[82:83], 0, v[152:153]
	global_load_lds_dwordx4 v[208:209], off
	s_barrier
	s_waitcnt lgkmcnt(0)
	v_mfma_f32_16x16x32_bf16 v[62:65], v[130:133], v[146:149], v[62:65]
	v_mfma_f32_16x16x32_bf16 v[58:61], v[138:141], v[146:149], v[58:61]
	v_mfma_f32_16x16x32_bf16 v[46:49], v[130:133], v[186:189], v[46:49]
	v_mfma_f32_16x16x32_bf16 v[42:45], v[138:141], v[186:189], v[42:45]
	v_mfma_f32_16x16x32_bf16 v[30:33], v[130:133], v[204:207], v[30:33]
	v_mfma_f32_16x16x32_bf16 v[26:29], v[138:141], v[204:207], v[26:29]
	v_mfma_f32_16x16x32_bf16 v[14:17], v[130:133], v[218:221], v[14:17]
	v_mfma_f32_16x16x32_bf16 v[10:13], v[138:141], v[218:221], v[10:13]
	v_mfma_f32_16x16x32_bf16 v[62:65], v[134:137], v[182:185], v[62:65]
	v_mfma_f32_16x16x32_bf16 v[58:61], v[142:145], v[182:185], v[58:61]
	v_mfma_f32_16x16x32_bf16 v[46:49], v[134:137], v[200:203], v[46:49]
	v_mfma_f32_16x16x32_bf16 v[42:45], v[142:145], v[200:203], v[42:45]
	v_mfma_f32_16x16x32_bf16 v[30:33], v[134:137], v[214:217], v[30:33]
	v_mfma_f32_16x16x32_bf16 v[26:29], v[142:145], v[214:217], v[26:29]
	v_mfma_f32_16x16x32_bf16 v[14:17], v[134:137], v[222:225], v[14:17]
	v_mfma_f32_16x16x32_bf16 v[10:13], v[142:145], v[222:225], v[10:13]
	s_barrier
; #define PG8_STAGE(bufoff, gbase, voff) do { _Pragma("unroll") for (int _i = 0; _i < 2; ++_i) \
;         __builtin_amdgcn_global_load_lds((const unsigned*)((const char*)(gbase) + (voff)[_i]), (LAS unsigned*)(lds + (bufoff) + ldsw + _i * 8192), 16, 0, 0); } while (0)
; #define PG8_LDA(dst, b, h) do { _Pragma("unroll") for (int m = 0; m < 4; ++m) _Pragma("unroll") for (int k = 0; k < 2; ++k) dst[m][k] = *(const LAS bf16x8*)(lds + PG8_SA(b, h) + aoff + m * 2048 + k * 1024); } while (0)
; #define PG8_LDB(dst, b, h) do { _Pragma("unroll") for (int n = 0; n < 2; ++n) _Pragma("unroll") for (int k = 0; k < 2; ++k) dst[n][k] = *(const LAS bf16x8*)(lds + PG8_SB(b, h) + boff + n * 2048 + k * 1024); } while (0)
; #define PG8_MMA(ai, bj, At, Bt) do { __builtin_amdgcn_s_setprio(1); _Pragma("unroll") for (int m = 0; m < 4; ++m) _Pragma("unroll") for (int n = 0; n < 2; ++n) _Pragma("unroll") for (int k = 0; k < 2; ++k) \
;         acc[ai][bj][m][n] = __builtin_amdgcn_mfma_f32_16x16x32_bf16(Bt[n][k], At[m][k], acc[ai][bj][m][n], 0, 0, 0); __builtin_amdgcn_s_setprio(0); } while (0)
; #define PG8_WAIT_V(n) asm volatile("s_waitcnt vmcnt(" #n ")" ::: "memory")
; #define PG8_WAIT_L(n) asm volatile("s_waitcnt lgkmcnt(" #n ")" ::: "memory")
; #define PG8_BAR __builtin_amdgcn_s_barrier()
; #define PG8_SCHED __builtin_amdgcn_sched_barrier(0)
; template <class Epi>
; DEVI void gemm_phase(LAS unsigned char* lds, const Gemm g, const Epi& E) {
;     ...
;             PG8_STAGE(PG8_SB(0, 1), b2 + hstepB, voffB);
;             PG8_WAIT_V(6); PG8_BAR; PG8_MMA(1, 1, At, B1); PG8_BAR;
;             PG8_LDB(B0, 1, 0); PG8_SCHED; PG8_LDA(At, 1, 0); PG8_STAGE(PG8_SA(0, 1), a2 + hstepA, voffA);
;             PG8_WAIT_L(8); PG8_BAR; PG8_WAIT_L(0); PG8_MMA(0, 0, At, B0); PG8_BAR; PG8_SCHED;
;             PG8_LDB(B1, 1, 1); PG8_STAGE(PG8_SB(1, 0), b3, voffB);
;             PG8_BAR; PG8_WAIT_L(0); PG8_MMA(0, 1, At, B1); PG8_BAR;
;             PG8_LDA(At, 1, 1); PG8_STAGE(PG8_SA(1, 0), a3, voffA);
	s_add_u32 s26, s80, 0x40000
	s_addc_u32 s27, s81, 0
	s_add_i32 s38, s39, s84
	s_mov_b32 m0, s38
	v_lshl_add_u64 v[130:131], s[26:27], 0, v[8:9]
	global_load_lds_dwordx4 v[130:131], off
	s_add_i32 m0, s38, 0x2000
	v_lshl_add_u64 v[130:131], s[26:27], 0, v[176:177]
	global_load_lds_dwordx4 v[130:131], off
	s_waitcnt vmcnt(6)
	s_barrier
	v_mfma_f32_16x16x32_bf16 v[54:57], v[226:229], v[146:149], v[54:57]
	v_mfma_f32_16x16x32_bf16 v[50:53], v[234:237], v[146:149], v[50:53]
	v_mfma_f32_16x16x32_bf16 v[38:41], v[226:229], v[186:189], v[38:41]
	v_mfma_f32_16x16x32_bf16 v[34:37], v[234:237], v[186:189], v[34:37]
	v_mfma_f32_16x16x32_bf16 v[22:25], v[226:229], v[204:207], v[22:25]
	v_mfma_f32_16x16x32_bf16 v[18:21], v[234:237], v[204:207], v[18:21]
	v_mfma_f32_16x16x32_bf16 v[4:7], v[226:229], v[218:221], v[4:7]
	v_mfma_f32_16x16x32_bf16 v[0:3], v[234:237], v[218:221], v[0:3]
	v_mfma_f32_16x16x32_bf16 v[54:57], v[230:233], v[182:185], v[54:57]
	v_mfma_f32_16x16x32_bf16 v[50:53], v[238:241], v[182:185], v[50:53]
	v_mfma_f32_16x16x32_bf16 v[38:41], v[230:233], v[200:203], v[38:41]
	v_mfma_f32_16x16x32_bf16 v[34:37], v[238:241], v[200:203], v[34:37]
	v_mfma_f32_16x16x32_bf16 v[22:25], v[230:233], v[214:217], v[22:25]
	v_mfma_f32_16x16x32_bf16 v[18:21], v[238:241], v[214:217], v[18:21]
	v_mfma_f32_16x16x32_bf16 v[4:7], v[230:233], v[222:225], v[4:7]
	v_mfma_f32_16x16x32_bf16 v[0:3], v[238:241], v[222:225], v[0:3]
	s_add_i32 s38, 0, 0x18000
	v_add_u32_e32 v142, s38, v193
	s_barrier
	ds_read_b128 v[130:133], v142
	ds_read_b128 v[134:137], v142 offset:1024
	ds_read_b128 v[138:141], v142 offset:2048
	ds_read_b128 v[142:145], v142 offset:3072
	s_add_u32 s26, s82, 0x40000
	s_addc_u32 s27, s83, 0
	s_mov_b32 m0, s87
	v_lshl_add_u64 v[226:227], s[26:27], 0, v[150:151]
	ds_read_b128 v[146:149], v198 offset:32768
	ds_read_b128 v[182:185], v198 offset:33792
	ds_read_b128 v[186:189], v198 offset:34816
	ds_read_b128 v[200:203], v198 offset:35840
	ds_read_b128 v[204:207], v198 offset:36864
	ds_read_b128 v[214:217], v198 offset:37888
	ds_read_b128 v[218:221], v198 offset:38912
	ds_read_b128 v[222:225], v198 offset:39936
	global_load_lds_dwordx4 v[226:227], off
	s_mov_b32 m0, s88
	v_lshl_add_u64 v[226:227], s[26:27], 0, v[152:153]
	global_load_lds_dwordx4 v[226:227], off
	s_waitcnt lgkmcnt(8)
	s_barrier
	s_waitcnt lgkmcnt(0)
	v_mfma_f32_16x16x32_bf16 v[126:129], v[130:133], v[146:149], v[126:129]
	v_mfma_f32_16x16x32_bf16 v[122:125], v[138:141], v[146:149], v[122:125]
	v_mfma_f32_16x16x32_bf16 v[110:113], v[130:133], v[186:189], v[110:113]
	v_mfma_f32_16x16x32_bf16 v[106:109], v[138:141], v[186:189], v[106:109]
	v_mfma_f32_16x16x32_bf16 v[94:97], v[130:133], v[204:207], v[94:97]
	v_mfma_f32_16x16x32_bf16 v[90:93], v[138:141], v[204:207], v[90:93]
	v_mfma_f32_16x16x32_bf16 v[78:81], v[130:133], v[218:221], v[78:81]
	v_mfma_f32_16x16x32_bf16 v[74:77], v[138:141], v[218:221], v[74:77]
	v_mfma_f32_16x16x32_bf16 v[126:129], v[134:137], v[182:185], v[126:129]
	v_mfma_f32_16x16x32_bf16 v[122:125], v[142:145], v[182:185], v[122:125]
	v_mfma_f32_16x16x32_bf16 v[110:113], v[134:137], v[200:203], v[110:113]
	v_mfma_f32_16x16x32_bf16 v[106:109], v[142:145], v[200:203], v[106:109]
	v_mfma_f32_16x16x32_bf16 v[94:97], v[134:137], v[214:217], v[94:97]
	v_mfma_f32_16x16x32_bf16 v[90:93], v[142:145], v[214:217], v[90:93]
	v_mfma_f32_16x16x32_bf16 v[78:81], v[134:137], v[222:225], v[78:81]
	v_mfma_f32_16x16x32_bf16 v[74:77], v[142:145], v[222:225], v[74:77]
	s_barrier
	s_add_i32 s39, 0, 0x1c000
	s_add_i32 s26, s38, s84
	v_add_u32_e32 v199, s39, v193
	v_lshl_add_u64 v[162:163], v[162:163], 0, s[70:71]
	s_mov_b32 m0, s26
	ds_read_b128 v[226:229], v199
	ds_read_b128 v[230:233], v199 offset:1024
	ds_read_b128 v[234:237], v199 offset:2048
	ds_read_b128 v[238:241], v199 offset:3072
	global_load_lds_dwordx4 v[162:163], off
	s_add_i32 m0, s26, 0x2000
	v_lshl_add_u64 v[162:163], v[164:165], 0, s[70:71]
	global_load_lds_dwordx4 v[162:163], off
	s_barrier
	s_waitcnt lgkmcnt(0)
	v_mfma_f32_16x16x32_bf16 v[118:121], v[226:229], v[146:149], v[118:121]
	v_mfma_f32_16x16x32_bf16 v[114:117], v[234:237], v[146:149], v[114:117]
	v_mfma_f32_16x16x32_bf16 v[102:105], v[226:229], v[186:189], v[102:105]
	v_mfma_f32_16x16x32_bf16 v[98:101], v[234:237], v[186:189], v[98:101]
	v_mfma_f32_16x16x32_bf16 v[86:89], v[226:229], v[204:207], v[86:89]
	v_mfma_f32_16x16x32_bf16 v[82:85], v[234:237], v[204:207], v[82:85]
	v_mfma_f32_16x16x32_bf16 v[70:73], v[226:229], v[218:221], v[70:73]
	v_mfma_f32_16x16x32_bf16 v[66:69], v[234:237], v[218:221], v[66:69]
	v_mfma_f32_16x16x32_bf16 v[118:121], v[230:233], v[182:185], v[118:121]
	v_mfma_f32_16x16x32_bf16 v[114:117], v[238:241], v[182:185], v[114:117]
	v_mfma_f32_16x16x32_bf16 v[102:105], v[230:233], v[200:203], v[102:105]
	v_mfma_f32_16x16x32_bf16 v[98:101], v[238:241], v[200:203], v[98:101]
	v_mfma_f32_16x16x32_bf16 v[86:89], v[230:233], v[214:217], v[86:89]
	v_mfma_f32_16x16x32_bf16 v[82:85], v[238:241], v[214:217], v[82:85]
	v_mfma_f32_16x16x32_bf16 v[70:73], v[230:233], v[222:225], v[70:73]
	v_mfma_f32_16x16x32_bf16 v[66:69], v[238:241], v[222:225], v[66:69]
	s_mov_b32 m0, s89
	v_lshl_add_u64 v[162:163], v[190:191], 0, s[70:71]
	s_barrier
	ds_read_b128 v[146:149], v198 offset:49152
	ds_read_b128 v[182:185], v198 offset:50176
	ds_read_b128 v[186:189], v198 offset:51200
	ds_read_b128 v[200:203], v198 offset:52224
	ds_read_b128 v[204:207], v198 offset:53248
	ds_read_b128 v[214:217], v198 offset:54272
	ds_read_b128 v[218:221], v198 offset:55296
	ds_read_b128 v[222:225], v198 offset:56320
	global_load_lds_dwordx4 v[162:163], off
	s_mov_b32 m0, s90
	v_lshl_add_u64 v[162:163], v[208:209], 0, s[70:71]
	global_load_lds_dwordx4 v[162:163], off
	s_barrier
; #define LAS __attribute__((address_space(3)))
;     DEVI f32x4 load(int r, int c) const { const bf16x4 y = *(const bf16x4*)(Y + (size_t)r * DM + c); return (f32x4){bf2f((u16)y[0]), bf2f((u16)y[1]), bf2f((u16)y[2]), bf2f((u16)y[3])}; }
; template <class Epi>
; DEVI void gemm_phase(LAS unsigned char* lds, const Gemm g, const Epi& E) {
;     ...
;             for (int am = 0; am < 4; ++am) {
;                 const int ai = am >> 1, m0 = (am & 1) * 2;
;                 f32x4 pre[2][2][2];
;                 if constexpr (Epi::PRE) {
; #pragma unroll
;                     for (int m = 0; m < 2; ++m)
; #pragma unroll
;                         for (int bj = 0; bj < 2; ++bj)
; #pragma unroll
;                             for (int n = 0; n < 2; ++n) pre[m][bj][n] = E.load(row0 + ai * HALF + (m0 + m) * 16, col0 + bj * HALF + n * NST);
;                 }
; #pragma unroll
;                 for (int mm = 0; mm < 2; ++mm) {
;                     const int m = m0 + mm;
;                     const int r = row0 + ai * HALF + m * 16; float rs = 1.f, part = 0.f;
;                     if constexpr (Epi::RS) rs = rsv[ai * 4 + m];
;                     if constexpr (Epi::PAIR) E.pair8(cur.b, r, cur.pn * HALF + wc * 32 + 8 * fq, acc[ai][0][m][0] * rs, acc[ai][0][m][1] * rs, acc[ai][1][m][0] * rs, acc[ai][1][m][1] * rs);
;                     else
; #pragma unroll
;                     for (int bj = 0; bj < 2; ++bj) {
;                         const int c = col0 + bj * HALF; f32x4 v0 = acc[ai][bj][m][0], v1 = acc[ai][bj][m][1];
;                         if constexpr (Epi::RS) { v0 = v0 * rs; v1 = v1 * rs; }
;                         if constexpr (Epi::PRE) part += E.frag_pre8(cur.b, r, c, v0, v1, pre[mm][bj][0], pre[mm][bj][1]);
;                         else if constexpr (Epi::PERM) E.frag8(cur.b, r, c, v0, v1);
;                         else { E.frag(cur.b, r, c, v0); E.frag(cur.b, r, c + 16, v1); }
;                     }
;                     if constexpr (Epi::SSQ) { part += __shfl_xor(part, 16); part += __shfl_xor(part, 32); if (fq == 0) ((LAS float*)(lds + 131072))[(wr * 4 + wc) * 128 + ai * 64 + m * 16 + fr] = part; }
	s_waitcnt lgkmcnt(0)
	v_mfma_f32_16x16x32_bf16 v[62:65], v[130:133], v[146:149], v[62:65]
	v_mfma_f32_16x16x32_bf16 v[58:61], v[138:141], v[146:149], v[58:61]
	v_mfma_f32_16x16x32_bf16 v[46:49], v[130:133], v[186:189], v[46:49]
	v_mfma_f32_16x16x32_bf16 v[42:45], v[138:141], v[186:189], v[42:45]
	v_mfma_f32_16x16x32_bf16 v[30:33], v[130:133], v[204:207], v[30:33]
	v_mfma_f32_16x16x32_bf16 v[26:29], v[138:141], v[204:207], v[26:29]
	v_mfma_f32_16x16x32_bf16 v[14:17], v[130:133], v[218:221], v[14:17]
	v_mfma_f32_16x16x32_bf16 v[10:13], v[138:141], v[218:221], v[10:13]
	v_mfma_f32_16x16x32_bf16 v[62:65], v[134:137], v[182:185], v[62:65]
	v_mfma_f32_16x16x32_bf16 v[58:61], v[142:145], v[182:185], v[58:61]
	v_mfma_f32_16x16x32_bf16 v[46:49], v[134:137], v[200:203], v[46:49]
	v_mfma_f32_16x16x32_bf16 v[42:45], v[142:145], v[200:203], v[42:45]
	v_mfma_f32_16x16x32_bf16 v[30:33], v[134:137], v[214:217], v[30:33]
	v_mfma_f32_16x16x32_bf16 v[26:29], v[142:145], v[214:217], v[26:29]
	v_mfma_f32_16x16x32_bf16 v[14:17], v[134:137], v[222:225], v[14:17]
	v_mfma_f32_16x16x32_bf16 v[10:13], v[142:145], v[222:225], v[10:13]
	s_barrier
	s_add_u32 s26, s80, 0x40080
	s_addc_u32 s27, s81, 0
	s_add_i32 s38, s39, s84
	s_mov_b32 m0, s38
	v_lshl_add_u64 v[130:131], s[26:27], 0, v[8:9]
	global_load_lds_dwordx4 v[130:131], off
	s_add_i32 m0, s38, 0x2000
	v_lshl_add_u64 v[130:131], s[26:27], 0, v[176:177]
	global_load_lds_dwordx4 v[130:131], off
	s_waitcnt vmcnt(6)
	s_barrier
	v_mfma_f32_16x16x32_bf16 v[54:57], v[226:229], v[146:149], v[54:57]
	v_mfma_f32_16x16x32_bf16 v[50:53], v[234:237], v[146:149], v[50:53]
	v_mfma_f32_16x16x32_bf16 v[38:41], v[226:229], v[186:189], v[38:41]
	v_mfma_f32_16x16x32_bf16 v[34:37], v[234:237], v[186:189], v[34:37]
	v_mfma_f32_16x16x32_bf16 v[22:25], v[226:229], v[204:207], v[22:25]
	v_mfma_f32_16x16x32_bf16 v[18:21], v[234:237], v[204:207], v[18:21]
	v_mfma_f32_16x16x32_bf16 v[4:7], v[226:229], v[218:221], v[4:7]
	v_mfma_f32_16x16x32_bf16 v[0:3], v[234:237], v[218:221], v[0:3]
	v_mfma_f32_16x16x32_bf16 v[54:57], v[230:233], v[182:185], v[54:57]
	v_mfma_f32_16x16x32_bf16 v[50:53], v[238:241], v[182:185], v[50:53]
	v_mfma_f32_16x16x32_bf16 v[38:41], v[230:233], v[200:203], v[38:41]
	v_mfma_f32_16x16x32_bf16 v[34:37], v[238:241], v[200:203], v[34:37]
	v_mfma_f32_16x16x32_bf16 v[22:25], v[230:233], v[214:217], v[22:25]
	v_mfma_f32_16x16x32_bf16 v[18:21], v[238:241], v[214:217], v[18:21]
	v_mfma_f32_16x16x32_bf16 v[4:7], v[230:233], v[222:225], v[4:7]
	v_mfma_f32_16x16x32_bf16 v[0:3], v[238:241], v[222:225], v[0:3]
	s_add_i32 s19, s19, 2
	s_add_u32 s68, s68, 0x100
	s_addc_u32 s69, s69, 0
	s_add_u32 s15, s15, 0x100
	s_addc_u32 s18, s18, 0
	s_cmp_gt_u32 s19, 13
	s_barrier
	s_cbranch_scc0 .LBB0_968
	s_setprio 0
	v_and_b32_e32 v131, 64, v155
	v_xor_b32_e32 v130, 16, v155
	v_add_u32_e32 v131, 64, v131
	v_cmp_lt_i32_e32 vcc, v130, v131
	s_lshl_b32 s9, s46, 8
	v_add_u32_e32 v186, s9, v192
	v_cndmask_b32_e32 v130, v155, v130, vcc
	v_lshlrev_b32_e32 v200, 2, v130
	v_xor_b32_e32 v130, 32, v155
	v_cmp_lt_i32_e32 vcc, v130, v131
	v_lshl_or_b32 v184, s8, 8, v197
	v_ashrrev_i32_e32 v187, 31, v186
	v_cndmask_b32_e32 v130, v155, v130, vcc
	v_lshlrev_b32_e32 v199, 2, v130
	v_lshlrev_b64 v[130:131], 12, v[186:187]
	v_ashrrev_i32_e32 v185, 31, v184
	v_lshl_add_u64 v[130:131], s[78:79], 0, v[130:131]
	v_lshlrev_b64 v[188:189], 2, v[184:185]
	v_lshl_add_u64 v[130:131], v[130:131], 0, v[188:189]
	global_load_dwordx4 v[202:205], v[130:131], off offset:16
	global_load_dwordx4 v[206:209], v[130:131], off
	global_load_dwordx4 v[146:149], v[130:131], off offset:528
	global_load_dwordx4 v[214:217], v[130:131], off offset:512
	v_or_b32_e32 v190, 16, v186
	v_ashrrev_i32_e32 v191, 31, v190
	v_lshlrev_b64 v[130:131], 12, v[190:191]
	v_lshl_add_u64 v[130:131], s[78:79], 0, v[130:131]
	v_lshl_add_u64 v[134:135], v[130:131], 0, v[188:189]
	global_load_dwordx4 v[138:141], v[134:135], off offset:16
	global_load_dwordx4 v[142:145], v[134:135], off
	global_load_dwordx4 v[130:133], v[134:135], off offset:528
	s_nop 0
	global_load_dwordx4 v[134:137], v[134:135], off offset:512
	v_lshlrev_b64 v[162:163], 10, v[186:187]
	v_lshl_add_u64 v[164:165], v[162:163], 0, v[184:185]
	v_or_b32_e32 v182, 0x80, v184
	v_ashrrev_i32_e32 v183, 31, v182
	s_waitcnt vmcnt(0)
	v_pk_add_f32 v[122:123], v[122:123], v[202:203]
	v_pk_add_f32 v[128:129], v[128:129], v[208:209]
	v_pk_add_f32 v[126:127], v[126:127], v[206:207]
	v_lshl_add_u64 v[206:207], v[164:165], 2, s[30:31]
	v_pk_add_f32 v[124:125], v[124:125], v[204:205]
	global_store_dwordx4 v[206:207], v[126:129], off nt
	global_store_dwordx4 v[206:207], v[122:125], off offset:16 nt
	v_cvt_pk_bf16_f32 v202, v126, v127
	v_cvt_pk_bf16_f32 v204, v122, v123
	v_mul_f32_e32 v127, v127, v127
	v_mul_f32_e32 v123, v123, v123
	v_fmac_f32_e32 v127, v126, v126
	v_mul_f32_e32 v126, v129, v129
	v_fmac_f32_e32 v123, v122, v122
	v_mul_f32_e32 v122, v125, v125
	v_fmac_f32_e32 v126, v128, v128
	v_fmac_f32_e32 v122, v124, v124
	v_cvt_pk_bf16_f32 v203, v128, v129
	v_cvt_pk_bf16_f32 v205, v124, v125
	v_lshl_add_u64 v[164:165], v[164:165], 1, s[28:29]
	v_add_f32_e32 v126, v127, v126
	v_add_f32_e32 v122, v123, v122
	v_pk_add_f32 v[120:121], v[120:121], v[216:217]
	v_pk_add_f32 v[118:119], v[118:119], v[214:215]
	v_pk_add_f32 v[114:115], v[114:115], v[146:147]
	global_store_dwordx4 v[164:165], v[202:205], off
	v_add_f32_e32 v128, v126, v122
	v_pk_add_f32 v[116:117], v[116:117], v[148:149]
	global_store_dwordx4 v[206:207], v[118:121], off offset:512 nt
	global_store_dwordx4 v[206:207], v[114:117], off offset:528 nt
	v_cvt_pk_bf16_f32 v122, v118, v119
	v_cvt_pk_bf16_f32 v124, v114, v115
	v_mul_f32_e32 v119, v119, v119
	v_mul_f32_e32 v115, v115, v115
	v_fmac_f32_e32 v119, v118, v118
	v_mul_f32_e32 v118, v121, v121
	v_fmac_f32_e32 v115, v114, v114
	v_mul_f32_e32 v114, v117, v117
	v_fmac_f32_e32 v118, v120, v120
	v_fmac_f32_e32 v114, v116, v116
	v_add_f32_e32 v118, v119, v118
	v_add_f32_e32 v114, v115, v114
	v_add_f32_e32 v114, v118, v114
	v_add_f32_e32 v114, v128, v114
	ds_bpermute_b32 v115, v200, v114
	v_lshl_add_u64 v[126:127], v[162:163], 0, v[182:183]
	v_cvt_pk_bf16_f32 v123, v120, v121
	v_cvt_pk_bf16_f32 v125, v116, v117
	v_lshl_add_u64 v[126:127], v[126:127], 1, s[28:29]
	s_waitcnt lgkmcnt(0)
	v_add_f32_e32 v114, v114, v115
	ds_bpermute_b32 v115, v199, v114
	global_store_dwordx4 v[126:127], v[122:125], off
	s_and_saveexec_b64 s[46:47], s[2:3]
	s_cbranch_execz .LBB0_971
	s_waitcnt lgkmcnt(0)
	v_add_f32_e32 v114, v114, v115
	ds_write_b32 v194, v114
; #define LAS __attribute__((address_space(3)))
; template <class Epi>
; DEVI void gemm_phase(LAS unsigned char* lds, const Gemm g, const Epi& E) {
;     ...
; #pragma unroll
;                 for (int mm = 0; mm < 2; ++mm) {
;                     const int m = m0 + mm;
;                     const int r = row0 + ai * HALF + m * 16; float rs = 1.f, part = 0.f;
;                     if constexpr (Epi::RS) rs = rsv[ai * 4 + m];
;                     if constexpr (Epi::PAIR) E.pair8(cur.b, r, cur.pn * HALF + wc * 32 + 8 * fq, acc[ai][0][m][0] * rs, acc[ai][0][m][1] * rs, acc[ai][1][m][0] * rs, acc[ai][1][m][1] * rs);
;                     else
; #pragma unroll
;                     for (int bj = 0; bj < 2; ++bj) {
;                         const int c = col0 + bj * HALF; f32x4 v0 = acc[ai][bj][m][0], v1 = acc[ai][bj][m][1];
;                         if constexpr (Epi::RS) { v0 = v0 * rs; v1 = v1 * rs; }
;                         if constexpr (Epi::PRE) part += E.frag_pre8(cur.b, r, c, v0, v1, pre[mm][bj][0], pre[mm][bj][1]);
;                         else if constexpr (Epi::PERM) E.frag8(cur.b, r, c, v0, v1);
;                         else { E.frag(cur.b, r, c, v0); E.frag(cur.b, r, c + 16, v1); }
;                     }
;                     if constexpr (Epi::SSQ) { part += __shfl_xor(part, 16); part += __shfl_xor(part, 32); if (fq == 0) ((LAS float*)(lds + 131072))[(wr * 4 + wc) * 128 + ai * 64 + m * 16 + fr] = part; }
.LBB0_971:
	s_or_b64 exec, exec, s[46:47]
	v_lshlrev_b64 v[118:119], 10, v[190:191]
	v_lshl_add_u64 v[120:121], v[118:119], 0, v[184:185]
	v_pk_add_f32 v[112:113], v[112:113], v[144:145]
	v_pk_add_f32 v[110:111], v[110:111], v[142:143]
	v_pk_add_f32 v[106:107], v[106:107], v[138:139]
	v_lshl_add_u64 v[122:123], v[120:121], 2, s[30:31]
	v_pk_add_f32 v[108:109], v[108:109], v[140:141]
	global_store_dwordx4 v[122:123], v[110:113], off nt
	global_store_dwordx4 v[122:123], v[106:109], off offset:16 nt
	v_cvt_pk_bf16_f32 v114, v110, v111
	v_cvt_pk_bf16_f32 v116, v106, v107
	v_mul_f32_e32 v111, v111, v111
	v_mul_f32_e32 v107, v107, v107
	v_fmac_f32_e32 v111, v110, v110
	v_mul_f32_e32 v110, v113, v113
	v_fmac_f32_e32 v107, v106, v106
	v_mul_f32_e32 v106, v109, v109
	v_fmac_f32_e32 v110, v112, v112
	v_fmac_f32_e32 v106, v108, v108
	v_add_f32_e32 v110, v111, v110
	v_add_f32_e32 v106, v107, v106
	v_pk_add_f32 v[104:105], v[104:105], v[136:137]
	v_pk_add_f32 v[102:103], v[102:103], v[134:135]
	s_waitcnt lgkmcnt(0)
	v_cvt_pk_bf16_f32 v115, v112, v113
	v_add_f32_e32 v112, v110, v106
	v_pk_add_f32 v[106:107], v[98:99], v[130:131]
	v_mul_f32_e32 v98, v103, v103
	v_mul_f32_e32 v99, v105, v105
	v_cvt_pk_bf16_f32 v117, v108, v109
	v_pk_add_f32 v[108:109], v[100:101], v[132:133]
	v_fmac_f32_e32 v98, v102, v102
	v_fmac_f32_e32 v99, v104, v104
	v_add_f32_e32 v98, v98, v99
	v_mul_f32_e32 v99, v107, v107
	v_mul_f32_e32 v100, v109, v109
	v_fmac_f32_e32 v99, v106, v106
	v_fmac_f32_e32 v100, v108, v108
	v_add_f32_e32 v99, v99, v100
	v_add_f32_e32 v98, v98, v99
	v_add_f32_e32 v98, v112, v98
	ds_bpermute_b32 v99, v200, v98
	v_lshl_add_u64 v[120:121], v[120:121], 1, s[28:29]
	v_lshl_add_u64 v[110:111], v[118:119], 0, v[182:183]
	global_store_dwordx4 v[120:121], v[114:117], off
	global_store_dwordx4 v[122:123], v[102:105], off offset:512 nt
	global_store_dwordx4 v[122:123], v[106:109], off offset:528 nt
	s_waitcnt lgkmcnt(0)
	v_add_f32_e32 v98, v98, v99
	ds_bpermute_b32 v99, v199, v98
	v_cvt_pk_bf16_f32 v100, v102, v103
	v_cvt_pk_bf16_f32 v101, v104, v105
	v_cvt_pk_bf16_f32 v102, v106, v107
	v_cvt_pk_bf16_f32 v103, v108, v109
	v_lshl_add_u64 v[104:105], v[110:111], 1, s[28:29]
	global_store_dwordx4 v[104:105], v[100:103], off
	s_and_saveexec_b64 s[46:47], s[2:3]
	s_cbranch_execz .LBB0_973
	s_waitcnt lgkmcnt(0)
	v_add_f32_e32 v98, v98, v99
	ds_write_b32 v194, v98 offset:64
.LBB0_973:
	s_or_b64 exec, exec, s[46:47]
	v_or_b32_e32 v132, 32, v186
	v_ashrrev_i32_e32 v133, 31, v132
	s_waitcnt lgkmcnt(0)
	v_lshlrev_b64 v[98:99], 12, v[132:133]
	v_lshl_add_u64 v[98:99], s[78:79], 0, v[98:99]
	v_lshl_add_u64 v[98:99], v[98:99], 0, v[188:189]
	global_load_dwordx4 v[116:119], v[98:99], off offset:16
	global_load_dwordx4 v[120:123], v[98:99], off
	global_load_dwordx4 v[124:127], v[98:99], off offset:528
	global_load_dwordx4 v[128:131], v[98:99], off offset:512
	v_or_b32_e32 v114, 48, v186
	v_ashrrev_i32_e32 v115, 31, v114
	v_lshlrev_b64 v[98:99], 12, v[114:115]
	v_lshl_add_u64 v[98:99], s[78:79], 0, v[98:99]
	v_lshl_add_u64 v[102:103], v[98:99], 0, v[188:189]
	global_load_dwordx4 v[106:109], v[102:103], off offset:16
	global_load_dwordx4 v[110:113], v[102:103], off
	global_load_dwordx4 v[98:101], v[102:103], off offset:528
	s_nop 0
	global_load_dwordx4 v[102:105], v[102:103], off offset:512
	v_lshlrev_b64 v[132:133], 10, v[132:133]
	v_lshl_add_u64 v[134:135], v[132:133], 0, v[184:185]
	s_waitcnt vmcnt(7)
	v_pk_add_f32 v[90:91], v[90:91], v[116:117]
	s_waitcnt vmcnt(6)
	v_pk_add_f32 v[96:97], v[96:97], v[122:123]
	v_pk_add_f32 v[94:95], v[94:95], v[120:121]
	v_lshl_add_u64 v[120:121], v[134:135], 2, s[30:31]
	v_pk_add_f32 v[92:93], v[92:93], v[118:119]
	global_store_dwordx4 v[120:121], v[94:97], off nt
	global_store_dwordx4 v[120:121], v[90:93], off offset:16 nt
	v_cvt_pk_bf16_f32 v116, v94, v95
	v_cvt_pk_bf16_f32 v118, v90, v91
	v_mul_f32_e32 v95, v95, v95
	v_mul_f32_e32 v91, v91, v91
	v_fmac_f32_e32 v95, v94, v94
	v_mul_f32_e32 v94, v97, v97
	v_fmac_f32_e32 v91, v90, v90
	v_mul_f32_e32 v90, v93, v93
	v_fmac_f32_e32 v94, v96, v96
	v_fmac_f32_e32 v90, v92, v92
	v_cvt_pk_bf16_f32 v117, v96, v97
	v_cvt_pk_bf16_f32 v119, v92, v93
	v_lshl_add_u64 v[122:123], v[134:135], 1, s[28:29]
	v_add_f32_e32 v94, v95, v94
	v_add_f32_e32 v90, v91, v90
	s_waitcnt vmcnt(6)
	v_pk_add_f32 v[88:89], v[88:89], v[130:131]
	v_pk_add_f32 v[86:87], v[86:87], v[128:129]
	v_pk_add_f32 v[82:83], v[82:83], v[124:125]
	global_store_dwordx4 v[122:123], v[116:119], off
	v_add_f32_e32 v96, v94, v90
	v_pk_add_f32 v[84:85], v[84:85], v[126:127]
	global_store_dwordx4 v[120:121], v[86:89], off offset:512 nt
	global_store_dwordx4 v[120:121], v[82:85], off offset:528 nt
	v_cvt_pk_bf16_f32 v90, v86, v87
	v_cvt_pk_bf16_f32 v92, v82, v83
	v_mul_f32_e32 v87, v87, v87
	v_mul_f32_e32 v83, v83, v83
	v_fmac_f32_e32 v87, v86, v86
	v_mul_f32_e32 v86, v89, v89
	v_fmac_f32_e32 v83, v82, v82
	v_mul_f32_e32 v82, v85, v85
	v_fmac_f32_e32 v86, v88, v88
	v_fmac_f32_e32 v82, v84, v84
	v_add_f32_e32 v86, v87, v86
	v_add_f32_e32 v82, v83, v82
	v_add_f32_e32 v82, v86, v82
	v_add_f32_e32 v82, v96, v82
	ds_bpermute_b32 v83, v200, v82
	v_lshl_add_u64 v[94:95], v[132:133], 0, v[182:183]
	v_cvt_pk_bf16_f32 v91, v88, v89
	v_cvt_pk_bf16_f32 v93, v84, v85
	v_lshl_add_u64 v[94:95], v[94:95], 1, s[28:29]
	s_waitcnt lgkmcnt(0)
	v_add_f32_e32 v82, v82, v83
	ds_bpermute_b32 v83, v199, v82
	global_store_dwordx4 v[94:95], v[90:93], off
	s_and_saveexec_b64 s[46:47], s[2:3]
	s_cbranch_execz .LBB0_975
	s_waitcnt lgkmcnt(0)
	v_add_f32_e32 v82, v82, v83
	ds_write_b32 v194, v82 offset:128
; #define LAS __attribute__((address_space(3)))
; template <class Epi>
; DEVI void gemm_phase(LAS unsigned char* lds, const Gemm g, const Epi& E) {
;     ...
; #pragma unroll
;                 for (int mm = 0; mm < 2; ++mm) {
;                     const int m = m0 + mm;
;                     const int r = row0 + ai * HALF + m * 16; float rs = 1.f, part = 0.f;
;                     if constexpr (Epi::RS) rs = rsv[ai * 4 + m];
;                     if constexpr (Epi::PAIR) E.pair8(cur.b, r, cur.pn * HALF + wc * 32 + 8 * fq, acc[ai][0][m][0] * rs, acc[ai][0][m][1] * rs, acc[ai][1][m][0] * rs, acc[ai][1][m][1] * rs);
;                     else
; #pragma unroll
;                     for (int bj = 0; bj < 2; ++bj) {
;                         const int c = col0 + bj * HALF; f32x4 v0 = acc[ai][bj][m][0], v1 = acc[ai][bj][m][1];
;                         if constexpr (Epi::RS) { v0 = v0 * rs; v1 = v1 * rs; }
;                         if constexpr (Epi::PRE) part += E.frag_pre8(cur.b, r, c, v0, v1, pre[mm][bj][0], pre[mm][bj][1]);
;                         else if constexpr (Epi::PERM) E.frag8(cur.b, r, c, v0, v1);
;                         else { E.frag(cur.b, r, c, v0); E.frag(cur.b, r, c + 16, v1); }
;                     }
;                     if constexpr (Epi::SSQ) { part += __shfl_xor(part, 16); part += __shfl_xor(part, 32); if (fq == 0) ((LAS float*)(lds + 131072))[(wr * 4 + wc) * 128 + ai * 64 + m * 16 + fr] = part; }
.LBB0_975:
	s_or_b64 exec, exec, s[46:47]
	v_lshlrev_b64 v[86:87], 10, v[114:115]
	v_lshl_add_u64 v[88:89], v[86:87], 0, v[184:185]
	s_waitcnt vmcnt(8)
	v_pk_add_f32 v[80:81], v[80:81], v[112:113]
	v_pk_add_f32 v[78:79], v[78:79], v[110:111]
	v_pk_add_f32 v[74:75], v[74:75], v[106:107]
	v_lshl_add_u64 v[90:91], v[88:89], 2, s[30:31]
	v_pk_add_f32 v[76:77], v[76:77], v[108:109]
	global_store_dwordx4 v[90:91], v[78:81], off nt
	global_store_dwordx4 v[90:91], v[74:77], off offset:16 nt
	v_cvt_pk_bf16_f32 v82, v78, v79
	v_cvt_pk_bf16_f32 v84, v74, v75
	v_mul_f32_e32 v79, v79, v79
	v_mul_f32_e32 v75, v75, v75
	v_fmac_f32_e32 v79, v78, v78
	v_mul_f32_e32 v78, v81, v81
	v_fmac_f32_e32 v75, v74, v74
	v_mul_f32_e32 v74, v77, v77
	v_fmac_f32_e32 v78, v80, v80
	v_fmac_f32_e32 v74, v76, v76
	v_add_f32_e32 v78, v79, v78
	v_add_f32_e32 v74, v75, v74
	s_waitcnt vmcnt(8)
	v_pk_add_f32 v[72:73], v[72:73], v[104:105]
	v_pk_add_f32 v[70:71], v[70:71], v[102:103]
	s_waitcnt lgkmcnt(0)
	v_cvt_pk_bf16_f32 v83, v80, v81
	v_add_f32_e32 v80, v78, v74
	v_pk_add_f32 v[74:75], v[66:67], v[98:99]
	v_mul_f32_e32 v66, v71, v71
	v_mul_f32_e32 v67, v73, v73
	v_cvt_pk_bf16_f32 v85, v76, v77
	v_pk_add_f32 v[76:77], v[68:69], v[100:101]
	v_fmac_f32_e32 v66, v70, v70
	v_fmac_f32_e32 v67, v72, v72
	v_add_f32_e32 v66, v66, v67
	v_mul_f32_e32 v67, v75, v75
	v_mul_f32_e32 v68, v77, v77
	v_fmac_f32_e32 v67, v74, v74
	v_fmac_f32_e32 v68, v76, v76
	v_add_f32_e32 v67, v67, v68
	v_add_f32_e32 v66, v66, v67
	v_add_f32_e32 v66, v80, v66
	ds_bpermute_b32 v67, v200, v66
	v_lshl_add_u64 v[88:89], v[88:89], 1, s[28:29]
	v_lshl_add_u64 v[78:79], v[86:87], 0, v[182:183]
	global_store_dwordx4 v[88:89], v[82:85], off
	global_store_dwordx4 v[90:91], v[70:73], off offset:512 nt
	global_store_dwordx4 v[90:91], v[74:77], off offset:528 nt
	s_waitcnt lgkmcnt(0)
	v_add_f32_e32 v66, v66, v67
	ds_bpermute_b32 v67, v199, v66
	v_cvt_pk_bf16_f32 v68, v70, v71
	v_cvt_pk_bf16_f32 v69, v72, v73
	v_cvt_pk_bf16_f32 v70, v74, v75
	v_cvt_pk_bf16_f32 v71, v76, v77
	v_lshl_add_u64 v[72:73], v[78:79], 1, s[28:29]
	global_store_dwordx4 v[72:73], v[68:71], off
	s_and_saveexec_b64 s[46:47], s[2:3]
	s_cbranch_execz .LBB0_977
	s_waitcnt lgkmcnt(0)
	v_add_f32_e32 v66, v66, v67
	ds_write_b32 v194, v66 offset:192
.LBB0_977:
	s_or_b64 exec, exec, s[46:47]
	v_add_u32_e32 v100, 0x80, v186
	v_ashrrev_i32_e32 v101, 31, v100
	s_waitcnt lgkmcnt(0)
	v_lshlrev_b64 v[66:67], 12, v[100:101]
	v_lshl_add_u64 v[66:67], s[78:79], 0, v[66:67]
	v_lshl_add_u64 v[66:67], v[66:67], 0, v[188:189]
	global_load_dwordx4 v[84:87], v[66:67], off offset:16
	global_load_dwordx4 v[88:91], v[66:67], off
	global_load_dwordx4 v[92:95], v[66:67], off offset:528
	global_load_dwordx4 v[96:99], v[66:67], off offset:512
	v_add_u32_e32 v82, 0x90, v186
	v_ashrrev_i32_e32 v83, 31, v82
	v_lshlrev_b64 v[66:67], 12, v[82:83]
	v_lshl_add_u64 v[66:67], s[78:79], 0, v[66:67]
	v_lshl_add_u64 v[70:71], v[66:67], 0, v[188:189]
	global_load_dwordx4 v[74:77], v[70:71], off offset:16
	global_load_dwordx4 v[78:81], v[70:71], off
	global_load_dwordx4 v[66:69], v[70:71], off offset:528
	s_nop 0
	global_load_dwordx4 v[70:73], v[70:71], off offset:512
	v_lshlrev_b64 v[100:101], 10, v[100:101]
	v_lshl_add_u64 v[102:103], v[100:101], 0, v[184:185]
	s_waitcnt vmcnt(7)
	v_pk_add_f32 v[58:59], v[58:59], v[84:85]
	s_waitcnt vmcnt(6)
	v_pk_add_f32 v[64:65], v[64:65], v[90:91]
	v_pk_add_f32 v[62:63], v[62:63], v[88:89]
	v_lshl_add_u64 v[88:89], v[102:103], 2, s[30:31]
	v_pk_add_f32 v[60:61], v[60:61], v[86:87]
	global_store_dwordx4 v[88:89], v[62:65], off nt
	global_store_dwordx4 v[88:89], v[58:61], off offset:16 nt
	v_cvt_pk_bf16_f32 v84, v62, v63
	v_cvt_pk_bf16_f32 v86, v58, v59
	v_mul_f32_e32 v63, v63, v63
	v_mul_f32_e32 v59, v59, v59
	v_fmac_f32_e32 v63, v62, v62
	v_mul_f32_e32 v62, v65, v65
	v_fmac_f32_e32 v59, v58, v58
	v_mul_f32_e32 v58, v61, v61
	v_fmac_f32_e32 v62, v64, v64
	v_fmac_f32_e32 v58, v60, v60
	v_cvt_pk_bf16_f32 v85, v64, v65
	v_cvt_pk_bf16_f32 v87, v60, v61
	v_lshl_add_u64 v[90:91], v[102:103], 1, s[28:29]
	v_add_f32_e32 v62, v63, v62
	v_add_f32_e32 v58, v59, v58
	s_waitcnt vmcnt(6)
	v_pk_add_f32 v[56:57], v[56:57], v[98:99]
	v_pk_add_f32 v[54:55], v[54:55], v[96:97]
	v_pk_add_f32 v[50:51], v[50:51], v[92:93]
	global_store_dwordx4 v[90:91], v[84:87], off
	v_add_f32_e32 v64, v62, v58
	v_pk_add_f32 v[52:53], v[52:53], v[94:95]
	global_store_dwordx4 v[88:89], v[54:57], off offset:512 nt
	global_store_dwordx4 v[88:89], v[50:53], off offset:528 nt
	v_cvt_pk_bf16_f32 v58, v54, v55
	v_cvt_pk_bf16_f32 v60, v50, v51
	v_mul_f32_e32 v55, v55, v55
	v_mul_f32_e32 v51, v51, v51
	v_fmac_f32_e32 v55, v54, v54
	v_mul_f32_e32 v54, v57, v57
	v_fmac_f32_e32 v51, v50, v50
	v_mul_f32_e32 v50, v53, v53
	v_fmac_f32_e32 v54, v56, v56
	v_fmac_f32_e32 v50, v52, v52
	v_add_f32_e32 v54, v55, v54
	v_add_f32_e32 v50, v51, v50
	v_add_f32_e32 v50, v54, v50
	v_add_f32_e32 v50, v64, v50
	ds_bpermute_b32 v51, v200, v50
	v_lshl_add_u64 v[62:63], v[100:101], 0, v[182:183]
	v_cvt_pk_bf16_f32 v59, v56, v57
	v_cvt_pk_bf16_f32 v61, v52, v53
	v_lshl_add_u64 v[62:63], v[62:63], 1, s[28:29]
	s_waitcnt lgkmcnt(0)
	v_add_f32_e32 v50, v50, v51
	ds_bpermute_b32 v51, v199, v50
	global_store_dwordx4 v[62:63], v[58:61], off
	s_and_saveexec_b64 s[46:47], s[2:3]
	s_cbranch_execz .LBB0_979
	s_waitcnt lgkmcnt(0)
	v_add_f32_e32 v50, v50, v51
	ds_write_b32 v194, v50 offset:256
; #define LAS __attribute__((address_space(3)))
; template <class Epi>
; DEVI void gemm_phase(LAS unsigned char* lds, const Gemm g, const Epi& E) {
;     ...
; #pragma unroll
;                 for (int mm = 0; mm < 2; ++mm) {
;                     const int m = m0 + mm;
;                     const int r = row0 + ai * HALF + m * 16; float rs = 1.f, part = 0.f;
;                     if constexpr (Epi::RS) rs = rsv[ai * 4 + m];
;                     if constexpr (Epi::PAIR) E.pair8(cur.b, r, cur.pn * HALF + wc * 32 + 8 * fq, acc[ai][0][m][0] * rs, acc[ai][0][m][1] * rs, acc[ai][1][m][0] * rs, acc[ai][1][m][1] * rs);
;                     else
; #pragma unroll
;                     for (int bj = 0; bj < 2; ++bj) {
;                         const int c = col0 + bj * HALF; f32x4 v0 = acc[ai][bj][m][0], v1 = acc[ai][bj][m][1];
;                         if constexpr (Epi::RS) { v0 = v0 * rs; v1 = v1 * rs; }
;                         if constexpr (Epi::PRE) part += E.frag_pre8(cur.b, r, c, v0, v1, pre[mm][bj][0], pre[mm][bj][1]);
;                         else if constexpr (Epi::PERM) E.frag8(cur.b, r, c, v0, v1);
;                         else { E.frag(cur.b, r, c, v0); E.frag(cur.b, r, c + 16, v1); }
;                     }
;                     if constexpr (Epi::SSQ) { part += __shfl_xor(part, 16); part += __shfl_xor(part, 32); if (fq == 0) ((LAS float*)(lds + 131072))[(wr * 4 + wc) * 128 + ai * 64 + m * 16 + fr] = part; }
.LBB0_979:
	s_or_b64 exec, exec, s[46:47]
	v_lshlrev_b64 v[54:55], 10, v[82:83]
	v_lshl_add_u64 v[56:57], v[54:55], 0, v[184:185]
	s_waitcnt vmcnt(8)
	v_pk_add_f32 v[48:49], v[48:49], v[80:81]
	v_pk_add_f32 v[46:47], v[46:47], v[78:79]
	v_pk_add_f32 v[42:43], v[42:43], v[74:75]
	v_lshl_add_u64 v[58:59], v[56:57], 2, s[30:31]
	v_pk_add_f32 v[44:45], v[44:45], v[76:77]
	global_store_dwordx4 v[58:59], v[46:49], off nt
	global_store_dwordx4 v[58:59], v[42:45], off offset:16 nt
	v_cvt_pk_bf16_f32 v50, v46, v47
	v_cvt_pk_bf16_f32 v52, v42, v43
	v_mul_f32_e32 v47, v47, v47
	v_mul_f32_e32 v43, v43, v43
	v_fmac_f32_e32 v47, v46, v46
	v_mul_f32_e32 v46, v49, v49
	v_fmac_f32_e32 v43, v42, v42
	v_mul_f32_e32 v42, v45, v45
	v_fmac_f32_e32 v46, v48, v48
	v_fmac_f32_e32 v42, v44, v44
	v_add_f32_e32 v46, v47, v46
	v_add_f32_e32 v42, v43, v42
	s_waitcnt vmcnt(8)
	v_pk_add_f32 v[40:41], v[40:41], v[72:73]
	v_pk_add_f32 v[38:39], v[38:39], v[70:71]
	s_waitcnt lgkmcnt(0)
	v_cvt_pk_bf16_f32 v51, v48, v49
	v_add_f32_e32 v48, v46, v42
	v_pk_add_f32 v[42:43], v[34:35], v[66:67]
	v_mul_f32_e32 v34, v39, v39
	v_mul_f32_e32 v35, v41, v41
	v_cvt_pk_bf16_f32 v53, v44, v45
	v_pk_add_f32 v[44:45], v[36:37], v[68:69]
	v_fmac_f32_e32 v34, v38, v38
	v_fmac_f32_e32 v35, v40, v40
	v_add_f32_e32 v34, v34, v35
	v_mul_f32_e32 v35, v43, v43
	v_mul_f32_e32 v36, v45, v45
	v_fmac_f32_e32 v35, v42, v42
	v_fmac_f32_e32 v36, v44, v44
	v_add_f32_e32 v35, v35, v36
	v_add_f32_e32 v34, v34, v35
	v_add_f32_e32 v34, v48, v34
	ds_bpermute_b32 v35, v200, v34
	v_lshl_add_u64 v[56:57], v[56:57], 1, s[28:29]
	v_lshl_add_u64 v[46:47], v[54:55], 0, v[182:183]
	global_store_dwordx4 v[56:57], v[50:53], off
	global_store_dwordx4 v[58:59], v[38:41], off offset:512 nt
	global_store_dwordx4 v[58:59], v[42:45], off offset:528 nt
	s_waitcnt lgkmcnt(0)
	v_add_f32_e32 v34, v34, v35
	ds_bpermute_b32 v35, v199, v34
	v_cvt_pk_bf16_f32 v36, v38, v39
	v_cvt_pk_bf16_f32 v37, v40, v41
	v_cvt_pk_bf16_f32 v38, v42, v43
	v_cvt_pk_bf16_f32 v39, v44, v45
	v_lshl_add_u64 v[40:41], v[46:47], 1, s[28:29]
	global_store_dwordx4 v[40:41], v[36:39], off
	s_and_saveexec_b64 s[46:47], s[2:3]
	s_cbranch_execz .LBB0_981
	s_waitcnt lgkmcnt(0)
	v_add_f32_e32 v34, v34, v35
	ds_write_b32 v194, v34 offset:320
; #define LAS __attribute__((address_space(3)))
;     DEVI f32x4 load(int r, int c) const { const bf16x4 y = *(const bf16x4*)(Y + (size_t)r * DM + c); return (f32x4){bf2f((u16)y[0]), bf2f((u16)y[1]), bf2f((u16)y[2]), bf2f((u16)y[3])}; }
; template <class Epi>
; DEVI void gemm_phase(LAS unsigned char* lds, const Gemm g, const Epi& E) {
;     ...
;                             for (int n = 0; n < 2; ++n) pre[m][bj][n] = E.load(row0 + ai * HALF + (m0 + m) * 16, col0 + bj * HALF + n * NST);
;                 }
; #pragma unroll
;                 for (int mm = 0; mm < 2; ++mm) {
;                     const int m = m0 + mm;
;                     const int r = row0 + ai * HALF + m * 16; float rs = 1.f, part = 0.f;
;                     if constexpr (Epi::RS) rs = rsv[ai * 4 + m];
;                     if constexpr (Epi::PAIR) E.pair8(cur.b, r, cur.pn * HALF + wc * 32 + 8 * fq, acc[ai][0][m][0] * rs, acc[ai][0][m][1] * rs, acc[ai][1][m][0] * rs, acc[ai][1][m][1] * rs);
;                     else
; #pragma unroll
;                     for (int bj = 0; bj < 2; ++bj) {
;                         const int c = col0 + bj * HALF; f32x4 v0 = acc[ai][bj][m][0], v1 = acc[ai][bj][m][1];
;                         if constexpr (Epi::RS) { v0 = v0 * rs; v1 = v1 * rs; }
;                         if constexpr (Epi::PRE) part += E.frag_pre8(cur.b, r, c, v0, v1, pre[mm][bj][0], pre[mm][bj][1]);
;                         else if constexpr (Epi::PERM) E.frag8(cur.b, r, c, v0, v1);
;                         else { E.frag(cur.b, r, c, v0); E.frag(cur.b, r, c + 16, v1); }
;                     }
;                     if constexpr (Epi::SSQ) { part += __shfl_xor(part, 16); part += __shfl_xor(part, 32); if (fq == 0) ((LAS float*)(lds + 131072))[(wr * 4 + wc) * 128 + ai * 64 + m * 16 + fr] = part; }
.LBB0_981:
	s_or_b64 exec, exec, s[46:47]
	v_add_u32_e32 v68, 0xa0, v186
	v_ashrrev_i32_e32 v69, 31, v68
	s_waitcnt lgkmcnt(0)
	v_lshlrev_b64 v[34:35], 12, v[68:69]
	v_lshl_add_u64 v[34:35], s[78:79], 0, v[34:35]
	v_lshl_add_u64 v[34:35], v[34:35], 0, v[188:189]
	global_load_dwordx4 v[52:55], v[34:35], off offset:16
	global_load_dwordx4 v[56:59], v[34:35], off
	global_load_dwordx4 v[60:63], v[34:35], off offset:528
	global_load_dwordx4 v[64:67], v[34:35], off offset:512
	v_add_u32_e32 v50, 0xb0, v186
	v_ashrrev_i32_e32 v51, 31, v50
	v_lshlrev_b64 v[34:35], 12, v[50:51]
	v_lshl_add_u64 v[34:35], s[78:79], 0, v[34:35]
	v_lshl_add_u64 v[38:39], v[34:35], 0, v[188:189]
	global_load_dwordx4 v[42:45], v[38:39], off offset:16
	global_load_dwordx4 v[46:49], v[38:39], off
	global_load_dwordx4 v[34:37], v[38:39], off offset:528
	s_nop 0
	global_load_dwordx4 v[38:41], v[38:39], off offset:512
	v_lshlrev_b64 v[68:69], 10, v[68:69]
	v_lshl_add_u64 v[70:71], v[68:69], 0, v[184:185]
	s_waitcnt vmcnt(7)
	v_pk_add_f32 v[26:27], v[26:27], v[52:53]
	s_waitcnt vmcnt(6)
	v_pk_add_f32 v[32:33], v[32:33], v[58:59]
	v_pk_add_f32 v[30:31], v[30:31], v[56:57]
	v_lshl_add_u64 v[56:57], v[70:71], 2, s[30:31]
	v_pk_add_f32 v[28:29], v[28:29], v[54:55]
	global_store_dwordx4 v[56:57], v[30:33], off nt
	global_store_dwordx4 v[56:57], v[26:29], off offset:16 nt
	v_cvt_pk_bf16_f32 v52, v30, v31
	v_cvt_pk_bf16_f32 v54, v26, v27
	v_mul_f32_e32 v31, v31, v31
	v_mul_f32_e32 v27, v27, v27
	v_fmac_f32_e32 v31, v30, v30
	v_mul_f32_e32 v30, v33, v33
	v_fmac_f32_e32 v27, v26, v26
	v_mul_f32_e32 v26, v29, v29
	v_fmac_f32_e32 v30, v32, v32
	v_fmac_f32_e32 v26, v28, v28
	v_cvt_pk_bf16_f32 v53, v32, v33
	v_cvt_pk_bf16_f32 v55, v28, v29
	v_lshl_add_u64 v[58:59], v[70:71], 1, s[28:29]
	v_add_f32_e32 v30, v31, v30
	v_add_f32_e32 v26, v27, v26
	s_waitcnt vmcnt(6)
	v_pk_add_f32 v[24:25], v[24:25], v[66:67]
	v_pk_add_f32 v[22:23], v[22:23], v[64:65]
	v_pk_add_f32 v[18:19], v[18:19], v[60:61]
	global_store_dwordx4 v[58:59], v[52:55], off
	v_add_f32_e32 v32, v30, v26
	v_pk_add_f32 v[20:21], v[20:21], v[62:63]
	global_store_dwordx4 v[56:57], v[22:25], off offset:512 nt
	global_store_dwordx4 v[56:57], v[18:21], off offset:528 nt
	v_cvt_pk_bf16_f32 v26, v22, v23
	v_cvt_pk_bf16_f32 v28, v18, v19
	v_mul_f32_e32 v23, v23, v23
	v_mul_f32_e32 v19, v19, v19
	v_fmac_f32_e32 v23, v22, v22
	v_mul_f32_e32 v22, v25, v25
	v_fmac_f32_e32 v19, v18, v18
	v_mul_f32_e32 v18, v21, v21
	v_fmac_f32_e32 v22, v24, v24
	v_fmac_f32_e32 v18, v20, v20
	v_add_f32_e32 v22, v23, v22
	v_add_f32_e32 v18, v19, v18
	v_add_f32_e32 v18, v22, v18
	v_add_f32_e32 v18, v32, v18
	ds_bpermute_b32 v19, v200, v18
	v_lshl_add_u64 v[30:31], v[68:69], 0, v[182:183]
	v_cvt_pk_bf16_f32 v27, v24, v25
	v_cvt_pk_bf16_f32 v29, v20, v21
	v_lshl_add_u64 v[30:31], v[30:31], 1, s[28:29]
	s_waitcnt lgkmcnt(0)
	v_add_f32_e32 v18, v18, v19
	ds_bpermute_b32 v19, v199, v18
	global_store_dwordx4 v[30:31], v[26:29], off
	s_and_saveexec_b64 s[46:47], s[2:3]
	s_cbranch_execz .LBB0_983
	s_waitcnt lgkmcnt(0)
	v_add_f32_e32 v18, v18, v19
	ds_write_b32 v194, v18 offset:384
.LBB0_983:
	s_or_b64 exec, exec, s[46:47]
	v_lshlrev_b64 v[22:23], 10, v[50:51]
	v_lshl_add_u64 v[24:25], v[22:23], 0, v[184:185]
	s_waitcnt vmcnt(8)
	v_pk_add_f32 v[16:17], v[16:17], v[48:49]
	v_pk_add_f32 v[14:15], v[14:15], v[46:47]
	v_pk_add_f32 v[10:11], v[10:11], v[42:43]
	v_lshl_add_u64 v[26:27], v[24:25], 2, s[30:31]
	v_pk_add_f32 v[12:13], v[12:13], v[44:45]
	global_store_dwordx4 v[26:27], v[14:17], off nt
	global_store_dwordx4 v[26:27], v[10:13], off offset:16 nt
	v_cvt_pk_bf16_f32 v18, v14, v15
	v_cvt_pk_bf16_f32 v20, v10, v11
	v_mul_f32_e32 v15, v15, v15
	v_mul_f32_e32 v11, v11, v11
	v_fmac_f32_e32 v15, v14, v14
	v_mul_f32_e32 v14, v17, v17
	v_fmac_f32_e32 v11, v10, v10
	v_mul_f32_e32 v10, v13, v13
	v_fmac_f32_e32 v14, v16, v16
	v_fmac_f32_e32 v10, v12, v12
	v_add_f32_e32 v14, v15, v14
	v_add_f32_e32 v10, v11, v10
	s_waitcnt vmcnt(8)
	v_pk_add_f32 v[6:7], v[6:7], v[40:41]
	v_pk_add_f32 v[4:5], v[4:5], v[38:39]
	s_waitcnt lgkmcnt(0)
	v_cvt_pk_bf16_f32 v19, v16, v17
	v_add_f32_e32 v16, v14, v10
	v_pk_add_f32 v[10:11], v[0:1], v[34:35]
	v_mul_f32_e32 v0, v5, v5
	v_mul_f32_e32 v1, v7, v7
	v_cvt_pk_bf16_f32 v21, v12, v13
	v_pk_add_f32 v[12:13], v[2:3], v[36:37]
	v_fmac_f32_e32 v0, v4, v4
	v_fmac_f32_e32 v1, v6, v6
	v_add_f32_e32 v0, v0, v1
	v_mul_f32_e32 v1, v11, v11
	v_mul_f32_e32 v2, v13, v13
	v_fmac_f32_e32 v1, v10, v10
	v_fmac_f32_e32 v2, v12, v12
	v_add_f32_e32 v1, v1, v2
	v_add_f32_e32 v0, v0, v1
	v_add_f32_e32 v0, v16, v0
	ds_bpermute_b32 v1, v200, v0
	v_lshl_add_u64 v[24:25], v[24:25], 1, s[28:29]
	v_lshl_add_u64 v[14:15], v[22:23], 0, v[182:183]
	global_store_dwordx4 v[24:25], v[18:21], off
	global_store_dwordx4 v[26:27], v[4:7], off offset:512 nt
	global_store_dwordx4 v[26:27], v[10:13], off offset:528 nt
	s_waitcnt lgkmcnt(0)
	v_add_f32_e32 v0, v0, v1
	ds_bpermute_b32 v1, v199, v0
	v_cvt_pk_bf16_f32 v2, v4, v5
	v_cvt_pk_bf16_f32 v3, v6, v7
	v_cvt_pk_bf16_f32 v4, v10, v11
	v_cvt_pk_bf16_f32 v5, v12, v13
	v_lshl_add_u64 v[6:7], v[14:15], 1, s[28:29]
	global_store_dwordx4 v[6:7], v[2:5], off
	s_and_saveexec_b64 s[46:47], s[2:3]
	s_cbranch_execz .LBB0_985
	s_waitcnt lgkmcnt(0)
	v_add_f32_e32 v0, v0, v1
	ds_write_b32 v194, v0 offset:448

; #define PG8_STAGE(bufoff, gbase, voff) do { _Pragma("unroll") for (int _i = 0; _i < 2; ++_i) \
;         __builtin_amdgcn_global_load_lds((const unsigned*)((const char*)(gbase) + (voff)[_i]), (LAS unsigned*)(lds + (bufoff) + ldsw + _i * 8192), 16, 0, 0); } while (0)
; #define PG8_LDA(dst, b, h) do { _Pragma("unroll") for (int m = 0; m < 4; ++m) _Pragma("unroll") for (int k = 0; k < 2; ++k) dst[m][k] = *(const LAS bf16x8*)(lds + PG8_SA(b, h) + aoff + m * 2048 + k * 1024); } while (0)
; #define PG8_LDB(dst, b, h) do { _Pragma("unroll") for (int n = 0; n < 2; ++n) _Pragma("unroll") for (int k = 0; k < 2; ++k) dst[n][k] = *(const LAS bf16x8*)(lds + PG8_SB(b, h) + boff + n * 2048 + k * 1024); } while (0)
; #define PG8_MMA(ai, bj, At, Bt) do { __builtin_amdgcn_s_setprio(1); _Pragma("unroll") for (int m = 0; m < 4; ++m) _Pragma("unroll") for (int n = 0; n < 2; ++n) _Pragma("unroll") for (int k = 0; k < 2; ++k) \
;         acc[ai][bj][m][n] = __builtin_amdgcn_mfma_f32_16x16x32_bf16(Bt[n][k], At[m][k], acc[ai][bj][m][n], 0, 0, 0); __builtin_amdgcn_s_setprio(0); } while (0)
; #define PG8_WAIT_L(n) asm volatile("s_waitcnt lgkmcnt(" #n ")" ::: "memory")
; #define PG8_BAR __builtin_amdgcn_s_barrier()
; #define PG8_SCHED __builtin_amdgcn_sched_barrier(0)
; template <class Epi>
; DEVI void gemm_phase(LAS unsigned char* lds, const Gemm g, const Epi& E) {
;     ...
;             PG8_LDB(B0, 0, 0); PG8_SCHED; PG8_LDA(At, 0, 0); PG8_STAGE(PG8_SA(1, 1), a1 + hstepA, voffA);
;             PG8_WAIT_L(8); PG8_BAR; PG8_WAIT_L(0); PG8_MMA(0, 0, At, B0); PG8_BAR; PG8_SCHED;
;             PG8_LDB(B1, 0, 1); PG8_STAGE(PG8_SB(0, 0), b2, voffB);
;             PG8_BAR; PG8_WAIT_L(0); PG8_MMA(0, 1, At, B1); PG8_BAR;
;             PG8_LDA(At, 0, 1); PG8_STAGE(PG8_SA(0, 0), a2, voffA);
;             PG8_BAR; PG8_WAIT_L(0); PG8_MMA(1, 0, At, B0); PG8_BAR; PG8_SCHED;
.LBB0_1595:
	s_add_u32 s18, s8, 0xfffc0080
	s_addc_u32 s19, s9, -1
	s_add_i32 s26, 0, 0x10000
	v_add_u32_e32 v142, s26, v191
	ds_read_b128 v[130:133], v142
	ds_read_b128 v[134:137], v142 offset:1024
	ds_read_b128 v[138:141], v142 offset:2048
	ds_read_b128 v[142:145], v142 offset:3072
	s_cmp_eq_u32 s17, 12
	s_cselect_b32 s81, s0, s19
	s_cselect_b32 s80, s1, s18
	s_cselect_b32 s79, s37, s15
	s_cselect_b32 s78, s36, s13
	v_lshl_add_u64 v[162:163], s[8:9], 0, v[152:153]
	s_add_i32 m0, s69, 0xc000
	ds_read_b128 v[178:181], v196
	ds_read_b128 v[182:185], v196 offset:1024
	ds_read_b128 v[186:189], v196 offset:2048
	ds_read_b128 v[198:201], v196 offset:3072
	ds_read_b128 v[202:205], v196 offset:4096
	ds_read_b128 v[206:209], v196 offset:5120
	ds_read_b128 v[214:217], v196 offset:6144
	ds_read_b128 v[218:221], v196 offset:7168
	global_load_lds_dwordx4 v[162:163], off
	s_add_i32 m0, s69, 0xe000
	v_lshl_add_u64 v[162:163], s[8:9], 0, v[176:177]
	global_load_lds_dwordx4 v[162:163], off
	s_waitcnt lgkmcnt(8)
	s_barrier
	s_waitcnt lgkmcnt(0)
	v_mfma_f32_16x16x32_bf16 v[126:129], v[130:133], v[178:181], v[126:129]
	v_mfma_f32_16x16x32_bf16 v[122:125], v[138:141], v[178:181], v[122:125]
	v_mfma_f32_16x16x32_bf16 v[110:113], v[130:133], v[186:189], v[110:113]
	v_mfma_f32_16x16x32_bf16 v[106:109], v[138:141], v[186:189], v[106:109]
	v_mfma_f32_16x16x32_bf16 v[94:97], v[130:133], v[202:205], v[94:97]
	v_mfma_f32_16x16x32_bf16 v[90:93], v[138:141], v[202:205], v[90:93]
	v_mfma_f32_16x16x32_bf16 v[78:81], v[130:133], v[214:217], v[78:81]
	v_mfma_f32_16x16x32_bf16 v[74:77], v[138:141], v[214:217], v[74:77]
	v_mfma_f32_16x16x32_bf16 v[126:129], v[134:137], v[182:185], v[126:129]
	v_mfma_f32_16x16x32_bf16 v[122:125], v[142:145], v[182:185], v[122:125]
	v_mfma_f32_16x16x32_bf16 v[110:113], v[134:137], v[198:201], v[110:113]
	v_mfma_f32_16x16x32_bf16 v[106:109], v[142:145], v[198:201], v[106:109]
	v_mfma_f32_16x16x32_bf16 v[94:97], v[134:137], v[206:209], v[94:97]
	v_mfma_f32_16x16x32_bf16 v[90:93], v[142:145], v[206:209], v[90:93]
	v_mfma_f32_16x16x32_bf16 v[78:81], v[134:137], v[218:221], v[78:81]
	v_mfma_f32_16x16x32_bf16 v[74:77], v[142:145], v[218:221], v[74:77]
	s_barrier
	s_add_i32 s27, 0, 0x14000
	v_add_u32_e32 v162, s27, v191
	s_add_i32 s18, s26, s82
	ds_read_b128 v[222:225], v162
	ds_read_b128 v[226:229], v162 offset:1024
	ds_read_b128 v[230:233], v162 offset:2048
	ds_read_b128 v[234:237], v162 offset:3072
	v_lshl_add_u64 v[162:163], s[78:79], 0, v[8:9]
	s_mov_b32 m0, s18
	v_lshl_add_u64 v[164:165], s[78:79], 0, v[150:151]
	global_load_lds_dwordx4 v[162:163], off
	s_add_i32 m0, s18, 0x2000
	s_nop 0
	global_load_lds_dwordx4 v[164:165], off
	s_barrier
	s_waitcnt lgkmcnt(0)
	v_mfma_f32_16x16x32_bf16 v[118:121], v[222:225], v[178:181], v[118:121]
	v_mfma_f32_16x16x32_bf16 v[114:117], v[230:233], v[178:181], v[114:117]
	v_mfma_f32_16x16x32_bf16 v[102:105], v[222:225], v[186:189], v[102:105]
	v_mfma_f32_16x16x32_bf16 v[98:101], v[230:233], v[186:189], v[98:101]
	v_mfma_f32_16x16x32_bf16 v[86:89], v[222:225], v[202:205], v[86:89]
	v_mfma_f32_16x16x32_bf16 v[82:85], v[230:233], v[202:205], v[82:85]
	v_mfma_f32_16x16x32_bf16 v[70:73], v[222:225], v[214:217], v[70:73]
	v_mfma_f32_16x16x32_bf16 v[66:69], v[230:233], v[214:217], v[66:69]
	v_mfma_f32_16x16x32_bf16 v[118:121], v[226:229], v[182:185], v[118:121]
	v_mfma_f32_16x16x32_bf16 v[114:117], v[234:237], v[182:185], v[114:117]
	v_mfma_f32_16x16x32_bf16 v[102:105], v[226:229], v[198:201], v[102:105]
	v_mfma_f32_16x16x32_bf16 v[98:101], v[234:237], v[198:201], v[98:101]
	v_mfma_f32_16x16x32_bf16 v[86:89], v[226:229], v[206:209], v[86:89]
	v_mfma_f32_16x16x32_bf16 v[82:85], v[234:237], v[206:209], v[82:85]
	v_mfma_f32_16x16x32_bf16 v[70:73], v[226:229], v[218:221], v[70:73]
	v_mfma_f32_16x16x32_bf16 v[66:69], v[234:237], v[218:221], v[66:69]
	s_mov_b32 m0, s69
	v_lshl_add_u64 v[238:239], s[80:81], 0, v[146:147]
	s_barrier
	ds_read_b128 v[178:181], v196 offset:16384
	ds_read_b128 v[182:185], v196 offset:17408
	ds_read_b128 v[186:189], v196 offset:18432
	ds_read_b128 v[198:201], v196 offset:19456
	ds_read_b128 v[202:205], v196 offset:20480
	ds_read_b128 v[206:209], v196 offset:21504
	ds_read_b128 v[214:217], v196 offset:22528
	ds_read_b128 v[218:221], v196 offset:23552
	global_load_lds_dwordx4 v[238:239], off
	s_mov_b32 m0, s83
	v_lshl_add_u64 v[240:241], s[80:81], 0, v[148:149]
	global_load_lds_dwordx4 v[240:241], off
	s_barrier
	s_waitcnt lgkmcnt(0)
	v_mfma_f32_16x16x32_bf16 v[62:65], v[130:133], v[178:181], v[62:65]
	v_mfma_f32_16x16x32_bf16 v[58:61], v[138:141], v[178:181], v[58:61]
	v_mfma_f32_16x16x32_bf16 v[46:49], v[130:133], v[186:189], v[46:49]
	v_mfma_f32_16x16x32_bf16 v[42:45], v[138:141], v[186:189], v[42:45]
	v_mfma_f32_16x16x32_bf16 v[30:33], v[130:133], v[202:205], v[30:33]
	v_mfma_f32_16x16x32_bf16 v[26:29], v[138:141], v[202:205], v[26:29]
	v_mfma_f32_16x16x32_bf16 v[14:17], v[130:133], v[214:217], v[14:17]
	v_mfma_f32_16x16x32_bf16 v[10:13], v[138:141], v[214:217], v[10:13]
	v_mfma_f32_16x16x32_bf16 v[62:65], v[134:137], v[182:185], v[62:65]
	v_mfma_f32_16x16x32_bf16 v[58:61], v[142:145], v[182:185], v[58:61]
	v_mfma_f32_16x16x32_bf16 v[46:49], v[134:137], v[198:201], v[46:49]
	v_mfma_f32_16x16x32_bf16 v[42:45], v[142:145], v[198:201], v[42:45]
	v_mfma_f32_16x16x32_bf16 v[30:33], v[134:137], v[206:209], v[30:33]
	v_mfma_f32_16x16x32_bf16 v[26:29], v[142:145], v[206:209], v[26:29]
	v_mfma_f32_16x16x32_bf16 v[14:17], v[134:137], v[218:221], v[14:17]
	v_mfma_f32_16x16x32_bf16 v[10:13], v[142:145], v[218:221], v[10:13]
	s_barrier
; #define PG8_STAGE(bufoff, gbase, voff) do { _Pragma("unroll") for (int _i = 0; _i < 2; ++_i) \
;         __builtin_amdgcn_global_load_lds((const unsigned*)((const char*)(gbase) + (voff)[_i]), (LAS unsigned*)(lds + (bufoff) + ldsw + _i * 8192), 16, 0, 0); } while (0)
; #define PG8_LDA(dst, b, h) do { _Pragma("unroll") for (int m = 0; m < 4; ++m) _Pragma("unroll") for (int k = 0; k < 2; ++k) dst[m][k] = *(const LAS bf16x8*)(lds + PG8_SA(b, h) + aoff + m * 2048 + k * 1024); } while (0)
; #define PG8_LDB(dst, b, h) do { _Pragma("unroll") for (int n = 0; n < 2; ++n) _Pragma("unroll") for (int k = 0; k < 2; ++k) dst[n][k] = *(const LAS bf16x8*)(lds + PG8_SB(b, h) + boff + n * 2048 + k * 1024); } while (0)
; #define PG8_MMA(ai, bj, At, Bt) do { __builtin_amdgcn_s_setprio(1); _Pragma("unroll") for (int m = 0; m < 4; ++m) _Pragma("unroll") for (int n = 0; n < 2; ++n) _Pragma("unroll") for (int k = 0; k < 2; ++k) \
;         acc[ai][bj][m][n] = __builtin_amdgcn_mfma_f32_16x16x32_bf16(Bt[n][k], At[m][k], acc[ai][bj][m][n], 0, 0, 0); __builtin_amdgcn_s_setprio(0); } while (0)
; #define PG8_WAIT_V(n) asm volatile("s_waitcnt vmcnt(" #n ")" ::: "memory")
; #define PG8_WAIT_L(n) asm volatile("s_waitcnt lgkmcnt(" #n ")" ::: "memory")
; #define PG8_BAR __builtin_amdgcn_s_barrier()
; #define PG8_SCHED __builtin_amdgcn_sched_barrier(0)
; template <class Epi>
; DEVI void gemm_phase(LAS unsigned char* lds, const Gemm g, const Epi& E) {
;     ...
;             PG8_STAGE(PG8_SB(0, 1), b2 + hstepB, voffB);
;             PG8_WAIT_V(6); PG8_BAR; PG8_MMA(1, 1, At, B1); PG8_BAR;
;             PG8_LDB(B0, 1, 0); PG8_SCHED; PG8_LDA(At, 1, 0); PG8_STAGE(PG8_SA(0, 1), a2 + hstepA, voffA);
;             PG8_WAIT_L(8); PG8_BAR; PG8_WAIT_L(0); PG8_MMA(0, 0, At, B0); PG8_BAR; PG8_SCHED;
;             PG8_LDB(B1, 1, 1); PG8_STAGE(PG8_SB(1, 0), b3, voffB);
;             PG8_BAR; PG8_WAIT_L(0); PG8_MMA(0, 1, At, B1); PG8_BAR;
;             PG8_LDA(At, 1, 1); PG8_STAGE(PG8_SA(1, 0), a3, voffA);
	s_add_u32 s18, s78, 0x40000
	s_addc_u32 s19, s79, 0
	s_add_i32 s26, s27, s82
	s_mov_b32 m0, s26
	v_lshl_add_u64 v[130:131], s[18:19], 0, v[8:9]
	global_load_lds_dwordx4 v[130:131], off
	s_add_i32 m0, s26, 0x2000
	v_lshl_add_u64 v[130:131], s[18:19], 0, v[150:151]
	global_load_lds_dwordx4 v[130:131], off
	s_waitcnt vmcnt(6)
	s_barrier
	v_mfma_f32_16x16x32_bf16 v[54:57], v[222:225], v[178:181], v[54:57]
	v_mfma_f32_16x16x32_bf16 v[50:53], v[230:233], v[178:181], v[50:53]
	v_mfma_f32_16x16x32_bf16 v[38:41], v[222:225], v[186:189], v[38:41]
	v_mfma_f32_16x16x32_bf16 v[34:37], v[230:233], v[186:189], v[34:37]
	v_mfma_f32_16x16x32_bf16 v[22:25], v[222:225], v[202:205], v[22:25]
	v_mfma_f32_16x16x32_bf16 v[18:21], v[230:233], v[202:205], v[18:21]
	v_mfma_f32_16x16x32_bf16 v[4:7], v[222:225], v[214:217], v[4:7]
	v_mfma_f32_16x16x32_bf16 v[0:3], v[230:233], v[214:217], v[0:3]
	v_mfma_f32_16x16x32_bf16 v[54:57], v[226:229], v[182:185], v[54:57]
	v_mfma_f32_16x16x32_bf16 v[50:53], v[234:237], v[182:185], v[50:53]
	v_mfma_f32_16x16x32_bf16 v[38:41], v[226:229], v[198:201], v[38:41]
	v_mfma_f32_16x16x32_bf16 v[34:37], v[234:237], v[198:201], v[34:37]
	v_mfma_f32_16x16x32_bf16 v[22:25], v[226:229], v[206:209], v[22:25]
	v_mfma_f32_16x16x32_bf16 v[18:21], v[234:237], v[206:209], v[18:21]
	v_mfma_f32_16x16x32_bf16 v[4:7], v[226:229], v[218:221], v[4:7]
	v_mfma_f32_16x16x32_bf16 v[0:3], v[234:237], v[218:221], v[0:3]
	s_add_i32 s26, 0, 0x18000
	v_add_u32_e32 v142, s26, v191
	s_barrier
	ds_read_b128 v[130:133], v142
	ds_read_b128 v[134:137], v142 offset:1024
	ds_read_b128 v[138:141], v142 offset:2048
	ds_read_b128 v[142:145], v142 offset:3072
	s_add_u32 s18, s80, 0x40000
	s_addc_u32 s19, s81, 0
	s_mov_b32 m0, s84
	v_lshl_add_u64 v[222:223], s[18:19], 0, v[146:147]
	ds_read_b128 v[178:181], v196 offset:32768
	ds_read_b128 v[182:185], v196 offset:33792
	ds_read_b128 v[186:189], v196 offset:34816
	ds_read_b128 v[198:201], v196 offset:35840
	ds_read_b128 v[202:205], v196 offset:36864
	ds_read_b128 v[206:209], v196 offset:37888
	ds_read_b128 v[214:217], v196 offset:38912
	ds_read_b128 v[218:221], v196 offset:39936
	global_load_lds_dwordx4 v[222:223], off
	s_mov_b32 m0, s85
	v_lshl_add_u64 v[222:223], s[18:19], 0, v[148:149]
	global_load_lds_dwordx4 v[222:223], off
	s_waitcnt lgkmcnt(8)
	s_barrier
	s_waitcnt lgkmcnt(0)
	v_mfma_f32_16x16x32_bf16 v[126:129], v[130:133], v[178:181], v[126:129]
	v_mfma_f32_16x16x32_bf16 v[122:125], v[138:141], v[178:181], v[122:125]
	v_mfma_f32_16x16x32_bf16 v[110:113], v[130:133], v[186:189], v[110:113]
	v_mfma_f32_16x16x32_bf16 v[106:109], v[138:141], v[186:189], v[106:109]
	v_mfma_f32_16x16x32_bf16 v[94:97], v[130:133], v[202:205], v[94:97]
	v_mfma_f32_16x16x32_bf16 v[90:93], v[138:141], v[202:205], v[90:93]
	v_mfma_f32_16x16x32_bf16 v[78:81], v[130:133], v[214:217], v[78:81]
	v_mfma_f32_16x16x32_bf16 v[74:77], v[138:141], v[214:217], v[74:77]
	v_mfma_f32_16x16x32_bf16 v[126:129], v[134:137], v[182:185], v[126:129]
	v_mfma_f32_16x16x32_bf16 v[122:125], v[142:145], v[182:185], v[122:125]
	v_mfma_f32_16x16x32_bf16 v[110:113], v[134:137], v[198:201], v[110:113]
	v_mfma_f32_16x16x32_bf16 v[106:109], v[142:145], v[198:201], v[106:109]
	v_mfma_f32_16x16x32_bf16 v[94:97], v[134:137], v[206:209], v[94:97]
	v_mfma_f32_16x16x32_bf16 v[90:93], v[142:145], v[206:209], v[90:93]
	v_mfma_f32_16x16x32_bf16 v[78:81], v[134:137], v[218:221], v[78:81]
	v_mfma_f32_16x16x32_bf16 v[74:77], v[142:145], v[218:221], v[74:77]
	s_barrier
	s_add_i32 s27, 0, 0x1c000
	s_add_i32 s18, s26, s82
	v_add_u32_e32 v197, s27, v191
	v_lshl_add_u64 v[162:163], v[162:163], 0, s[70:71]
	s_mov_b32 m0, s18
	ds_read_b128 v[222:225], v197
	ds_read_b128 v[226:229], v197 offset:1024
	ds_read_b128 v[230:233], v197 offset:2048
	ds_read_b128 v[234:237], v197 offset:3072
	global_load_lds_dwordx4 v[162:163], off
	s_add_i32 m0, s18, 0x2000
	v_lshl_add_u64 v[162:163], v[164:165], 0, s[70:71]
	global_load_lds_dwordx4 v[162:163], off
	s_barrier
	s_waitcnt lgkmcnt(0)
	v_mfma_f32_16x16x32_bf16 v[118:121], v[222:225], v[178:181], v[118:121]
	v_mfma_f32_16x16x32_bf16 v[114:117], v[230:233], v[178:181], v[114:117]
	v_mfma_f32_16x16x32_bf16 v[102:105], v[222:225], v[186:189], v[102:105]
	v_mfma_f32_16x16x32_bf16 v[98:101], v[230:233], v[186:189], v[98:101]
	v_mfma_f32_16x16x32_bf16 v[86:89], v[222:225], v[202:205], v[86:89]
	v_mfma_f32_16x16x32_bf16 v[82:85], v[230:233], v[202:205], v[82:85]
	v_mfma_f32_16x16x32_bf16 v[70:73], v[222:225], v[214:217], v[70:73]
	v_mfma_f32_16x16x32_bf16 v[66:69], v[230:233], v[214:217], v[66:69]
	v_mfma_f32_16x16x32_bf16 v[118:121], v[226:229], v[182:185], v[118:121]
	v_mfma_f32_16x16x32_bf16 v[114:117], v[234:237], v[182:185], v[114:117]
	v_mfma_f32_16x16x32_bf16 v[102:105], v[226:229], v[198:201], v[102:105]
	v_mfma_f32_16x16x32_bf16 v[98:101], v[234:237], v[198:201], v[98:101]
	v_mfma_f32_16x16x32_bf16 v[86:89], v[226:229], v[206:209], v[86:89]
	v_mfma_f32_16x16x32_bf16 v[82:85], v[234:237], v[206:209], v[82:85]
	v_mfma_f32_16x16x32_bf16 v[70:73], v[226:229], v[218:221], v[70:73]
	v_mfma_f32_16x16x32_bf16 v[66:69], v[234:237], v[218:221], v[66:69]
	s_mov_b32 m0, s86
	v_lshl_add_u64 v[162:163], v[238:239], 0, s[70:71]
	s_barrier
	ds_read_b128 v[178:181], v196 offset:49152
	ds_read_b128 v[182:185], v196 offset:50176
	ds_read_b128 v[186:189], v196 offset:51200
	ds_read_b128 v[198:201], v196 offset:52224
	ds_read_b128 v[202:205], v196 offset:53248
	ds_read_b128 v[206:209], v196 offset:54272
	ds_read_b128 v[214:217], v196 offset:55296
	ds_read_b128 v[218:221], v196 offset:56320
	global_load_lds_dwordx4 v[162:163], off
	s_mov_b32 m0, s87
	v_lshl_add_u64 v[162:163], v[240:241], 0, s[70:71]
	global_load_lds_dwordx4 v[162:163], off
	s_barrier
; #define LAS __attribute__((address_space(3)))
; #define PG8_STAGE(bufoff, gbase, voff) do { _Pragma("unroll") for (int _i = 0; _i < 2; ++_i) \
;         __builtin_amdgcn_global_load_lds((const unsigned*)((const char*)(gbase) + (voff)[_i]), (LAS unsigned*)(lds + (bufoff) + ldsw + _i * 8192), 16, 0, 0); } while (0)
; #define PG8_WAIT_V(n) asm volatile("s_waitcnt vmcnt(" #n ")" ::: "memory")
; template <class Epi>
; DEVI void gemm_phase(LAS unsigned char* lds, const Gemm g, const Epi& E) {
;     ...
;             PG8_BAR; PG8_WAIT_L(0); PG8_MMA(1, 0, At, B0); PG8_BAR; PG8_SCHED;
;             PG8_STAGE(PG8_SB(1, 1), b3 + hstepB, voffB);
;             PG8_WAIT_V(6); PG8_BAR; PG8_MMA(1, 1, At, B1); PG8_BAR;
;     ...
;                 if constexpr (Epi::PRE) {
; #pragma unroll
;                     for (int m = 0; m < 2; ++m)
; #pragma unroll
;                         for (int bj = 0; bj < 2; ++bj)
; #pragma unroll
;                             for (int n = 0; n < 2; ++n) pre[m][bj][n] = E.load(row0 + ai * HALF + (m0 + m) * 16, col0 + bj * HALF + n * NST);
;                 }
; #pragma unroll
;                 for (int mm = 0; mm < 2; ++mm) {
;                     const int m = m0 + mm;
;                     const int r = row0 + ai * HALF + m * 16; float rs = 1.f, part = 0.f;
;                     if constexpr (Epi::RS) rs = rsv[ai * 4 + m];
;                     if constexpr (Epi::PAIR) E.pair8(cur.b, r, cur.pn * HALF + wc * 32 + 8 * fq, acc[ai][0][m][0] * rs, acc[ai][0][m][1] * rs, acc[ai][1][m][0] * rs, acc[ai][1][m][1] * rs);
;                     else
; #pragma unroll
;                     for (int bj = 0; bj < 2; ++bj) {
;                         const int c = col0 + bj * HALF; f32x4 v0 = acc[ai][bj][m][0], v1 = acc[ai][bj][m][1];
;                         if constexpr (Epi::RS) { v0 = v0 * rs; v1 = v1 * rs; }
;                         if constexpr (Epi::PRE) part += E.frag_pre8(cur.b, r, c, v0, v1, pre[mm][bj][0], pre[mm][bj][1]);
;                         else if constexpr (Epi::PERM) E.frag8(cur.b, r, c, v0, v1);
;                         else { E.frag(cur.b, r, c, v0); E.frag(cur.b, r, c + 16, v1); }
;                     }
;                     if constexpr (Epi::SSQ) { part += __shfl_xor(part, 16); part += __shfl_xor(part, 32); if (fq == 0) ((LAS float*)(lds + 131072))[(wr * 4 + wc) * 128 + ai * 64 + m * 16 + fr] = part; }
	s_waitcnt lgkmcnt(0)
	v_mfma_f32_16x16x32_bf16 v[62:65], v[130:133], v[178:181], v[62:65]
	v_mfma_f32_16x16x32_bf16 v[58:61], v[138:141], v[178:181], v[58:61]
	v_mfma_f32_16x16x32_bf16 v[46:49], v[130:133], v[186:189], v[46:49]
	v_mfma_f32_16x16x32_bf16 v[42:45], v[138:141], v[186:189], v[42:45]
	v_mfma_f32_16x16x32_bf16 v[30:33], v[130:133], v[202:205], v[30:33]
	v_mfma_f32_16x16x32_bf16 v[26:29], v[138:141], v[202:205], v[26:29]
	v_mfma_f32_16x16x32_bf16 v[14:17], v[130:133], v[214:217], v[14:17]
	v_mfma_f32_16x16x32_bf16 v[10:13], v[138:141], v[214:217], v[10:13]
	v_mfma_f32_16x16x32_bf16 v[62:65], v[134:137], v[182:185], v[62:65]
	v_mfma_f32_16x16x32_bf16 v[58:61], v[142:145], v[182:185], v[58:61]
	v_mfma_f32_16x16x32_bf16 v[46:49], v[134:137], v[198:201], v[46:49]
	v_mfma_f32_16x16x32_bf16 v[42:45], v[142:145], v[198:201], v[42:45]
	v_mfma_f32_16x16x32_bf16 v[30:33], v[134:137], v[206:209], v[30:33]
	v_mfma_f32_16x16x32_bf16 v[26:29], v[142:145], v[206:209], v[26:29]
	v_mfma_f32_16x16x32_bf16 v[14:17], v[134:137], v[218:221], v[14:17]
	v_mfma_f32_16x16x32_bf16 v[10:13], v[142:145], v[218:221], v[10:13]
	s_barrier
	s_add_u32 s18, s78, 0x40080
	s_addc_u32 s19, s79, 0
	s_add_i32 s26, s27, s82
	s_mov_b32 m0, s26
	v_lshl_add_u64 v[130:131], s[18:19], 0, v[8:9]
	global_load_lds_dwordx4 v[130:131], off
	s_add_i32 m0, s26, 0x2000
	v_lshl_add_u64 v[130:131], s[18:19], 0, v[150:151]
	global_load_lds_dwordx4 v[130:131], off
	s_waitcnt vmcnt(6)
	s_barrier
	v_mfma_f32_16x16x32_bf16 v[54:57], v[222:225], v[178:181], v[54:57]
	v_mfma_f32_16x16x32_bf16 v[50:53], v[230:233], v[178:181], v[50:53]
	v_mfma_f32_16x16x32_bf16 v[38:41], v[222:225], v[186:189], v[38:41]
	v_mfma_f32_16x16x32_bf16 v[34:37], v[230:233], v[186:189], v[34:37]
	v_mfma_f32_16x16x32_bf16 v[22:25], v[222:225], v[202:205], v[22:25]
	v_mfma_f32_16x16x32_bf16 v[18:21], v[230:233], v[202:205], v[18:21]
	v_mfma_f32_16x16x32_bf16 v[4:7], v[222:225], v[214:217], v[4:7]
	v_mfma_f32_16x16x32_bf16 v[0:3], v[230:233], v[214:217], v[0:3]
	v_mfma_f32_16x16x32_bf16 v[54:57], v[226:229], v[182:185], v[54:57]
	v_mfma_f32_16x16x32_bf16 v[50:53], v[234:237], v[182:185], v[50:53]
	v_mfma_f32_16x16x32_bf16 v[38:41], v[226:229], v[198:201], v[38:41]
	v_mfma_f32_16x16x32_bf16 v[34:37], v[234:237], v[198:201], v[34:37]
	v_mfma_f32_16x16x32_bf16 v[22:25], v[226:229], v[206:209], v[22:25]
	v_mfma_f32_16x16x32_bf16 v[18:21], v[234:237], v[206:209], v[18:21]
	v_mfma_f32_16x16x32_bf16 v[4:7], v[226:229], v[218:221], v[4:7]
	v_mfma_f32_16x16x32_bf16 v[0:3], v[234:237], v[218:221], v[0:3]
	s_add_i32 s17, s17, 2
	s_add_u32 s8, s8, 0x100
	s_addc_u32 s9, s9, 0
	s_add_u32 s13, s13, 0x100
	s_addc_u32 s15, s15, 0
	s_cmp_gt_u32 s17, 13
	s_barrier
	s_cbranch_scc0 .LBB0_1595
	s_setprio 0
	s_lshl_b32 s0, s68, 8
	v_add_u32_e32 v182, s0, v190
	v_lshl_or_b32 v180, s12, 8, v195
	v_ashrrev_i32_e32 v183, 31, v182
	v_lshlrev_b64 v[130:131], 12, v[182:183]
	v_ashrrev_i32_e32 v181, 31, v180
	v_lshl_add_u64 v[130:131], s[30:31], 0, v[130:131]
	v_lshlrev_b64 v[184:185], 2, v[180:181]
	v_lshl_add_u64 v[162:163], v[130:131], 0, v[184:185]
	global_load_dwordx4 v[200:203], v[162:163], off
	global_load_dwordx4 v[204:207], v[162:163], off offset:16
	global_load_dwordx4 v[214:217], v[162:163], off offset:512
	global_load_dwordx4 v[218:221], v[162:163], off offset:528
	v_or_b32_e32 v188, 16, v182
	v_ashrrev_i32_e32 v189, 31, v188
	v_lshlrev_b64 v[130:131], 12, v[188:189]
	v_lshl_add_u64 v[130:131], s[30:31], 0, v[130:131]
	v_lshl_add_u64 v[186:187], v[130:131], 0, v[184:185]
	global_load_dwordx4 v[138:141], v[186:187], off offset:16
	global_load_dwordx4 v[142:145], v[186:187], off
	global_load_dwordx4 v[130:133], v[186:187], off offset:528
	global_load_dwordx4 v[134:137], v[186:187], off offset:512
	v_and_b32_e32 v165, 64, v155
	v_xor_b32_e32 v164, 16, v155
	v_add_u32_e32 v165, 64, v165
	v_xor_b32_e32 v179, 32, v155
	v_cmp_lt_i32_e32 vcc, v164, v165
	v_or_b32_e32 v178, 0x80, v180
	s_waitcnt vmcnt(0)
	v_pk_add_f32 v[128:129], v[128:129], v[202:203]
	v_cndmask_b32_e32 v164, v155, v164, vcc
	v_cmp_lt_i32_e32 vcc, v179, v165
	v_lshlrev_b32_e32 v198, 2, v164
	v_pk_add_f32 v[126:127], v[126:127], v[200:201]
	v_cndmask_b32_e32 v165, v155, v179, vcc
	v_lshlrev_b32_e32 v197, 2, v165
	v_lshlrev_b64 v[164:165], 10, v[182:183]
	v_pk_add_f32 v[124:125], v[124:125], v[206:207]
	v_pk_add_f32 v[122:123], v[122:123], v[204:205]
	v_pk_add_f32 v[120:121], v[120:121], v[216:217]
	v_pk_add_f32 v[118:119], v[118:119], v[214:215]
	v_pk_add_f32 v[202:203], v[116:117], v[220:221]
	v_pk_add_f32 v[200:201], v[114:115], v[218:219]
	v_lshl_add_u64 v[208:209], v[164:165], 0, v[180:181]
	global_store_dwordx4 v[162:163], v[126:129], off nt
	global_store_dwordx4 v[162:163], v[122:125], off offset:16 nt
	v_cvt_pk_bf16_f32 v114, v126, v127
	v_cvt_pk_bf16_f32 v115, v128, v129
	v_cvt_pk_bf16_f32 v116, v122, v123
	v_cvt_pk_bf16_f32 v117, v124, v125
	v_mul_f32_e32 v127, v127, v127
	v_mul_f32_e32 v129, v129, v129
	v_mul_f32_e32 v123, v123, v123
	v_mul_f32_e32 v125, v125, v125
	v_mul_f32_e32 v183, v119, v119
	v_mul_f32_e32 v199, v121, v121
	v_mul_f32_e32 v204, v201, v201
	v_mul_f32_e32 v205, v203, v203
	v_lshl_add_u64 v[208:209], v[208:209], 1, s[24:25]
	v_fmac_f32_e32 v127, v126, v126
	v_fmac_f32_e32 v129, v128, v128
	v_fmac_f32_e32 v123, v122, v122
	v_fmac_f32_e32 v125, v124, v124
	v_fmac_f32_e32 v183, v118, v118
	v_fmac_f32_e32 v199, v120, v120
	v_fmac_f32_e32 v204, v200, v200
	v_fmac_f32_e32 v205, v202, v202
	global_store_dwordx4 v[208:209], v[114:117], off
	v_ashrrev_i32_e32 v179, 31, v178
	v_lshl_add_u64 v[164:165], v[164:165], 0, v[178:179]
	v_add_f32_e32 v114, v127, v129
	v_add_f32_e32 v115, v123, v125
	v_add_f32_e32 v116, v183, v199
	v_add_f32_e32 v117, v204, v205
	v_add_f32_e32 v114, v114, v115
	v_add_f32_e32 v115, v116, v117
	v_add_f32_e32 v114, v114, v115
	ds_bpermute_b32 v115, v198, v114
	global_store_dwordx4 v[162:163], v[118:121], off offset:512 nt
	global_store_dwordx4 v[162:163], v[200:203], off offset:528 nt
	v_cvt_pk_bf16_f32 v116, v118, v119
	v_cvt_pk_bf16_f32 v117, v120, v121
	v_cvt_pk_bf16_f32 v118, v200, v201
	s_waitcnt lgkmcnt(0)
	v_add_f32_e32 v114, v114, v115
	ds_bpermute_b32 v115, v197, v114
	v_cvt_pk_bf16_f32 v119, v202, v203
	v_lshl_add_u64 v[120:121], v[164:165], 1, s[24:25]
	global_store_dwordx4 v[120:121], v[116:119], off
	s_and_saveexec_b64 s[8:9], s[2:3]
	s_cbranch_execz .LBB0_1598
	s_waitcnt lgkmcnt(0)
	v_add_f32_e32 v114, v114, v115
	ds_write_b32 v192, v114
; #define LAS __attribute__((address_space(3)))
;     DEVI f32x4 load(int r, int c) const { const bf16x4 y = *(const bf16x4*)(Y + (size_t)r * DM + c); return (f32x4){bf2f((u16)y[0]), bf2f((u16)y[1]), bf2f((u16)y[2]), bf2f((u16)y[3])}; }
; template <class Epi>
; DEVI void gemm_phase(LAS unsigned char* lds, const Gemm g, const Epi& E) {
;     ...
;                             for (int n = 0; n < 2; ++n) pre[m][bj][n] = E.load(row0 + ai * HALF + (m0 + m) * 16, col0 + bj * HALF + n * NST);
;                 }
; #pragma unroll
;                 for (int mm = 0; mm < 2; ++mm) {
;                     const int m = m0 + mm;
;                     const int r = row0 + ai * HALF + m * 16; float rs = 1.f, part = 0.f;
;                     if constexpr (Epi::RS) rs = rsv[ai * 4 + m];
;                     if constexpr (Epi::PAIR) E.pair8(cur.b, r, cur.pn * HALF + wc * 32 + 8 * fq, acc[ai][0][m][0] * rs, acc[ai][0][m][1] * rs, acc[ai][1][m][0] * rs, acc[ai][1][m][1] * rs);
;                     else
; #pragma unroll
;                     for (int bj = 0; bj < 2; ++bj) {
;                         const int c = col0 + bj * HALF; f32x4 v0 = acc[ai][bj][m][0], v1 = acc[ai][bj][m][1];
;                         if constexpr (Epi::RS) { v0 = v0 * rs; v1 = v1 * rs; }
;                         if constexpr (Epi::PRE) part += E.frag_pre8(cur.b, r, c, v0, v1, pre[mm][bj][0], pre[mm][bj][1]);
;                         else if constexpr (Epi::PERM) E.frag8(cur.b, r, c, v0, v1);
;                         else { E.frag(cur.b, r, c, v0); E.frag(cur.b, r, c + 16, v1); }
;                     }
;                     if constexpr (Epi::SSQ) { part += __shfl_xor(part, 16); part += __shfl_xor(part, 32); if (fq == 0) ((LAS float*)(lds + 131072))[(wr * 4 + wc) * 128 + ai * 64 + m * 16 + fr] = part; }
.LBB0_1598:
	s_or_b64 exec, exec, s[8:9]
	v_pk_add_f32 v[112:113], v[112:113], v[144:145]
	v_pk_add_f32 v[110:111], v[110:111], v[142:143]
	v_pk_add_f32 v[106:107], v[106:107], v[138:139]
	v_pk_add_f32 v[108:109], v[108:109], v[140:141]
	global_store_dwordx4 v[186:187], v[110:113], off nt
	global_store_dwordx4 v[186:187], v[106:109], off offset:16 nt
	v_cvt_pk_bf16_f32 v114, v110, v111
	v_cvt_pk_bf16_f32 v116, v106, v107
	v_mul_f32_e32 v111, v111, v111
	v_mul_f32_e32 v107, v107, v107
	v_fmac_f32_e32 v111, v110, v110
	v_mul_f32_e32 v110, v113, v113
	v_fmac_f32_e32 v107, v106, v106
	v_mul_f32_e32 v106, v109, v109
	v_fmac_f32_e32 v110, v112, v112
	v_fmac_f32_e32 v106, v108, v108
	v_add_f32_e32 v110, v111, v110
	v_add_f32_e32 v106, v107, v106
	v_pk_add_f32 v[104:105], v[104:105], v[136:137]
	v_pk_add_f32 v[102:103], v[102:103], v[134:135]
	s_waitcnt lgkmcnt(0)
	v_cvt_pk_bf16_f32 v115, v112, v113
	v_add_f32_e32 v112, v110, v106
	v_pk_add_f32 v[106:107], v[98:99], v[130:131]
	v_mul_f32_e32 v98, v103, v103
	v_mul_f32_e32 v99, v105, v105
	v_cvt_pk_bf16_f32 v117, v108, v109
	v_pk_add_f32 v[108:109], v[100:101], v[132:133]
	v_fmac_f32_e32 v98, v102, v102
	v_fmac_f32_e32 v99, v104, v104
	v_add_f32_e32 v98, v98, v99
	v_mul_f32_e32 v99, v107, v107
	v_mul_f32_e32 v100, v109, v109
	v_fmac_f32_e32 v99, v106, v106
	v_fmac_f32_e32 v100, v108, v108
	v_add_f32_e32 v99, v99, v100
	v_add_f32_e32 v98, v98, v99
	v_add_f32_e32 v98, v112, v98
	ds_bpermute_b32 v99, v198, v98
	v_lshlrev_b64 v[118:119], 10, v[188:189]
	v_lshl_add_u64 v[120:121], v[118:119], 0, v[180:181]
	v_lshl_add_u64 v[120:121], v[120:121], 1, s[24:25]
	v_lshl_add_u64 v[110:111], v[118:119], 0, v[178:179]
	s_waitcnt lgkmcnt(0)
	v_add_f32_e32 v98, v98, v99
	ds_bpermute_b32 v99, v197, v98
	global_store_dwordx4 v[120:121], v[114:117], off
	global_store_dwordx4 v[186:187], v[102:105], off offset:512 nt
	global_store_dwordx4 v[186:187], v[106:109], off offset:528 nt
	v_cvt_pk_bf16_f32 v100, v102, v103
	v_cvt_pk_bf16_f32 v101, v104, v105
	v_cvt_pk_bf16_f32 v102, v106, v107
	v_cvt_pk_bf16_f32 v103, v108, v109
	v_lshl_add_u64 v[104:105], v[110:111], 1, s[24:25]
	global_store_dwordx4 v[104:105], v[100:103], off
	s_and_saveexec_b64 s[8:9], s[2:3]
	s_cbranch_execz .LBB0_1600
	s_waitcnt lgkmcnt(0)
	v_add_f32_e32 v98, v98, v99
	ds_write_b32 v192, v98 offset:64
.LBB0_1600:
	s_or_b64 exec, exec, s[8:9]
	v_or_b32_e32 v134, 32, v182
	v_ashrrev_i32_e32 v135, 31, v134
	s_waitcnt lgkmcnt(0)
	v_lshlrev_b64 v[98:99], 12, v[134:135]
	v_lshl_add_u64 v[98:99], s[30:31], 0, v[98:99]
	v_lshl_add_u64 v[136:137], v[98:99], 0, v[184:185]
	global_load_dwordx4 v[118:121], v[136:137], off
	global_load_dwordx4 v[122:125], v[136:137], off offset:16
	global_load_dwordx4 v[126:129], v[136:137], off offset:512
	global_load_dwordx4 v[130:133], v[136:137], off offset:528
	v_or_b32_e32 v116, 48, v182
	v_ashrrev_i32_e32 v117, 31, v116
	v_lshlrev_b64 v[98:99], 12, v[116:117]
	v_lshl_add_u64 v[98:99], s[30:31], 0, v[98:99]
	v_lshl_add_u64 v[114:115], v[98:99], 0, v[184:185]
	global_load_dwordx4 v[106:109], v[114:115], off offset:16
	global_load_dwordx4 v[110:113], v[114:115], off
	global_load_dwordx4 v[98:101], v[114:115], off offset:528
	global_load_dwordx4 v[102:105], v[114:115], off offset:512
	v_lshlrev_b64 v[134:135], 10, v[134:135]
	v_lshl_add_u64 v[138:139], v[134:135], 0, v[180:181]
	v_lshl_add_u64 v[138:139], v[138:139], 1, s[24:25]
	v_lshl_add_u64 v[134:135], v[134:135], 0, v[178:179]
	s_waitcnt vmcnt(7)
	v_pk_add_f32 v[96:97], v[96:97], v[120:121]
	v_pk_add_f32 v[94:95], v[94:95], v[118:119]
	s_waitcnt vmcnt(6)
	v_pk_add_f32 v[92:93], v[92:93], v[124:125]
	v_pk_add_f32 v[90:91], v[90:91], v[122:123]
	s_waitcnt vmcnt(5)
	v_pk_add_f32 v[88:89], v[88:89], v[128:129]
	v_pk_add_f32 v[86:87], v[86:87], v[126:127]
	s_waitcnt vmcnt(4)
	v_pk_add_f32 v[120:121], v[84:85], v[132:133]
	v_pk_add_f32 v[118:119], v[82:83], v[130:131]
	global_store_dwordx4 v[136:137], v[94:97], off nt
	global_store_dwordx4 v[136:137], v[90:93], off offset:16 nt
	v_cvt_pk_bf16_f32 v82, v94, v95
	v_cvt_pk_bf16_f32 v83, v96, v97
	v_cvt_pk_bf16_f32 v84, v90, v91
	v_cvt_pk_bf16_f32 v85, v92, v93
	v_mul_f32_e32 v95, v95, v95
	v_mul_f32_e32 v97, v97, v97
	v_mul_f32_e32 v91, v91, v91
	v_mul_f32_e32 v93, v93, v93
	v_mul_f32_e32 v122, v87, v87
	v_mul_f32_e32 v123, v89, v89
	v_mul_f32_e32 v124, v119, v119
	v_mul_f32_e32 v125, v121, v121
	v_fmac_f32_e32 v95, v94, v94
	v_fmac_f32_e32 v97, v96, v96
	v_fmac_f32_e32 v91, v90, v90
	v_fmac_f32_e32 v93, v92, v92
	v_fmac_f32_e32 v122, v86, v86
	v_fmac_f32_e32 v123, v88, v88
	v_fmac_f32_e32 v124, v118, v118
	v_fmac_f32_e32 v125, v120, v120
	global_store_dwordx4 v[138:139], v[82:85], off
	global_store_dwordx4 v[136:137], v[86:89], off offset:512 nt
	global_store_dwordx4 v[136:137], v[118:121], off offset:528 nt
	v_add_f32_e32 v82, v95, v97
	v_add_f32_e32 v83, v91, v93
	v_add_f32_e32 v84, v122, v123
	v_add_f32_e32 v85, v124, v125
	v_add_f32_e32 v82, v82, v83
	v_add_f32_e32 v83, v84, v85
	v_add_f32_e32 v82, v82, v83
	ds_bpermute_b32 v83, v198, v82
	v_cvt_pk_bf16_f32 v84, v86, v87
	v_cvt_pk_bf16_f32 v85, v88, v89
	v_cvt_pk_bf16_f32 v86, v118, v119
	v_cvt_pk_bf16_f32 v87, v120, v121
	s_waitcnt lgkmcnt(0)
	v_add_f32_e32 v82, v82, v83
	ds_bpermute_b32 v83, v197, v82
	v_lshl_add_u64 v[88:89], v[134:135], 1, s[24:25]
	global_store_dwordx4 v[88:89], v[84:87], off
	s_and_saveexec_b64 s[8:9], s[2:3]
	s_cbranch_execz .LBB0_1602
	s_waitcnt lgkmcnt(0)
	v_add_f32_e32 v82, v82, v83
	ds_write_b32 v192, v82 offset:128
; #define LAS __attribute__((address_space(3)))
;     DEVI f32x4 load(int r, int c) const { const bf16x4 y = *(const bf16x4*)(Y + (size_t)r * DM + c); return (f32x4){bf2f((u16)y[0]), bf2f((u16)y[1]), bf2f((u16)y[2]), bf2f((u16)y[3])}; }
; template <class Epi>
; DEVI void gemm_phase(LAS unsigned char* lds, const Gemm g, const Epi& E) {
;     ...
;                             for (int n = 0; n < 2; ++n) pre[m][bj][n] = E.load(row0 + ai * HALF + (m0 + m) * 16, col0 + bj * HALF + n * NST);
;                 }
; #pragma unroll
;                 for (int mm = 0; mm < 2; ++mm) {
;                     const int m = m0 + mm;
;                     const int r = row0 + ai * HALF + m * 16; float rs = 1.f, part = 0.f;
;                     if constexpr (Epi::RS) rs = rsv[ai * 4 + m];
;                     if constexpr (Epi::PAIR) E.pair8(cur.b, r, cur.pn * HALF + wc * 32 + 8 * fq, acc[ai][0][m][0] * rs, acc[ai][0][m][1] * rs, acc[ai][1][m][0] * rs, acc[ai][1][m][1] * rs);
;                     else
; #pragma unroll
;                     for (int bj = 0; bj < 2; ++bj) {
;                         const int c = col0 + bj * HALF; f32x4 v0 = acc[ai][bj][m][0], v1 = acc[ai][bj][m][1];
;                         if constexpr (Epi::RS) { v0 = v0 * rs; v1 = v1 * rs; }
;                         if constexpr (Epi::PRE) part += E.frag_pre8(cur.b, r, c, v0, v1, pre[mm][bj][0], pre[mm][bj][1]);
;                         else if constexpr (Epi::PERM) E.frag8(cur.b, r, c, v0, v1);
;                         else { E.frag(cur.b, r, c, v0); E.frag(cur.b, r, c + 16, v1); }
;                     }
;                     if constexpr (Epi::SSQ) { part += __shfl_xor(part, 16); part += __shfl_xor(part, 32); if (fq == 0) ((LAS float*)(lds + 131072))[(wr * 4 + wc) * 128 + ai * 64 + m * 16 + fr] = part; }
.LBB0_1602:
	s_or_b64 exec, exec, s[8:9]
	s_waitcnt vmcnt(8)
	v_pk_add_f32 v[80:81], v[80:81], v[112:113]
	v_pk_add_f32 v[78:79], v[78:79], v[110:111]
	v_pk_add_f32 v[74:75], v[74:75], v[106:107]
	v_pk_add_f32 v[76:77], v[76:77], v[108:109]
	global_store_dwordx4 v[114:115], v[78:81], off nt
	global_store_dwordx4 v[114:115], v[74:77], off offset:16 nt
	v_cvt_pk_bf16_f32 v82, v78, v79
	v_cvt_pk_bf16_f32 v84, v74, v75
	v_mul_f32_e32 v79, v79, v79
	v_mul_f32_e32 v75, v75, v75
	v_fmac_f32_e32 v79, v78, v78
	v_mul_f32_e32 v78, v81, v81
	v_fmac_f32_e32 v75, v74, v74
	v_mul_f32_e32 v74, v77, v77
	v_fmac_f32_e32 v78, v80, v80
	v_fmac_f32_e32 v74, v76, v76
	v_add_f32_e32 v78, v79, v78
	v_add_f32_e32 v74, v75, v74
	s_waitcnt vmcnt(8)
	v_pk_add_f32 v[72:73], v[72:73], v[104:105]
	v_pk_add_f32 v[70:71], v[70:71], v[102:103]
	s_waitcnt lgkmcnt(0)
	v_cvt_pk_bf16_f32 v83, v80, v81
	v_add_f32_e32 v80, v78, v74
	v_pk_add_f32 v[74:75], v[66:67], v[98:99]
	v_mul_f32_e32 v66, v71, v71
	v_mul_f32_e32 v67, v73, v73
	v_cvt_pk_bf16_f32 v85, v76, v77
	v_pk_add_f32 v[76:77], v[68:69], v[100:101]
	v_fmac_f32_e32 v66, v70, v70
	v_fmac_f32_e32 v67, v72, v72
	v_add_f32_e32 v66, v66, v67
	v_mul_f32_e32 v67, v75, v75
	v_mul_f32_e32 v68, v77, v77
	v_fmac_f32_e32 v67, v74, v74
	v_fmac_f32_e32 v68, v76, v76
	v_add_f32_e32 v67, v67, v68
	v_add_f32_e32 v66, v66, v67
	v_add_f32_e32 v66, v80, v66
	ds_bpermute_b32 v67, v198, v66
	v_lshlrev_b64 v[86:87], 10, v[116:117]
	v_lshl_add_u64 v[88:89], v[86:87], 0, v[180:181]
	v_lshl_add_u64 v[88:89], v[88:89], 1, s[24:25]
	v_lshl_add_u64 v[78:79], v[86:87], 0, v[178:179]
	s_waitcnt lgkmcnt(0)
	v_add_f32_e32 v66, v66, v67
	ds_bpermute_b32 v67, v197, v66
	global_store_dwordx4 v[88:89], v[82:85], off
	global_store_dwordx4 v[114:115], v[70:73], off offset:512 nt
	global_store_dwordx4 v[114:115], v[74:77], off offset:528 nt
	v_cvt_pk_bf16_f32 v68, v70, v71
	v_cvt_pk_bf16_f32 v69, v72, v73
	v_cvt_pk_bf16_f32 v70, v74, v75
	v_cvt_pk_bf16_f32 v71, v76, v77
	v_lshl_add_u64 v[72:73], v[78:79], 1, s[24:25]
	global_store_dwordx4 v[72:73], v[68:71], off
	s_and_saveexec_b64 s[8:9], s[2:3]
	s_cbranch_execz .LBB0_1604
	s_waitcnt lgkmcnt(0)
	v_add_f32_e32 v66, v66, v67
	ds_write_b32 v192, v66 offset:192
.LBB0_1604:
	s_or_b64 exec, exec, s[8:9]
	v_add_u32_e32 v102, 0x80, v182
	v_ashrrev_i32_e32 v103, 31, v102
	s_waitcnt lgkmcnt(0)
	v_lshlrev_b64 v[66:67], 12, v[102:103]
	v_lshl_add_u64 v[66:67], s[30:31], 0, v[66:67]
	v_lshl_add_u64 v[104:105], v[66:67], 0, v[184:185]
	global_load_dwordx4 v[86:89], v[104:105], off
	global_load_dwordx4 v[90:93], v[104:105], off offset:16
	global_load_dwordx4 v[94:97], v[104:105], off offset:512
	global_load_dwordx4 v[98:101], v[104:105], off offset:528
	v_add_u32_e32 v84, 0x90, v182
	v_ashrrev_i32_e32 v85, 31, v84
	v_lshlrev_b64 v[66:67], 12, v[84:85]
	v_lshl_add_u64 v[66:67], s[30:31], 0, v[66:67]
	v_lshl_add_u64 v[82:83], v[66:67], 0, v[184:185]
	global_load_dwordx4 v[74:77], v[82:83], off offset:16
	global_load_dwordx4 v[78:81], v[82:83], off
	global_load_dwordx4 v[66:69], v[82:83], off offset:528
	global_load_dwordx4 v[70:73], v[82:83], off offset:512
	v_lshlrev_b64 v[102:103], 10, v[102:103]
	v_lshl_add_u64 v[106:107], v[102:103], 0, v[180:181]
	v_lshl_add_u64 v[106:107], v[106:107], 1, s[24:25]
	v_lshl_add_u64 v[102:103], v[102:103], 0, v[178:179]
	s_waitcnt vmcnt(7)
	v_pk_add_f32 v[64:65], v[64:65], v[88:89]
	v_pk_add_f32 v[62:63], v[62:63], v[86:87]
	s_waitcnt vmcnt(6)
	v_pk_add_f32 v[60:61], v[60:61], v[92:93]
	v_pk_add_f32 v[58:59], v[58:59], v[90:91]
	s_waitcnt vmcnt(5)
	v_pk_add_f32 v[56:57], v[56:57], v[96:97]
	v_pk_add_f32 v[54:55], v[54:55], v[94:95]
	s_waitcnt vmcnt(4)
	v_pk_add_f32 v[88:89], v[52:53], v[100:101]
	v_pk_add_f32 v[86:87], v[50:51], v[98:99]
	global_store_dwordx4 v[104:105], v[62:65], off nt
	global_store_dwordx4 v[104:105], v[58:61], off offset:16 nt
	v_cvt_pk_bf16_f32 v50, v62, v63
	v_cvt_pk_bf16_f32 v51, v64, v65
	v_cvt_pk_bf16_f32 v52, v58, v59
	v_cvt_pk_bf16_f32 v53, v60, v61
	v_mul_f32_e32 v63, v63, v63
	v_mul_f32_e32 v65, v65, v65
	v_mul_f32_e32 v59, v59, v59
	v_mul_f32_e32 v61, v61, v61
	v_mul_f32_e32 v90, v55, v55
	v_mul_f32_e32 v91, v57, v57
	v_mul_f32_e32 v92, v87, v87
	v_mul_f32_e32 v93, v89, v89
	v_fmac_f32_e32 v63, v62, v62
	v_fmac_f32_e32 v65, v64, v64
	v_fmac_f32_e32 v59, v58, v58
	v_fmac_f32_e32 v61, v60, v60
	v_fmac_f32_e32 v90, v54, v54
	v_fmac_f32_e32 v91, v56, v56
	v_fmac_f32_e32 v92, v86, v86
	v_fmac_f32_e32 v93, v88, v88
	global_store_dwordx4 v[106:107], v[50:53], off
	global_store_dwordx4 v[104:105], v[54:57], off offset:512 nt
	global_store_dwordx4 v[104:105], v[86:89], off offset:528 nt
	v_add_f32_e32 v50, v63, v65
	v_add_f32_e32 v51, v59, v61
	v_add_f32_e32 v52, v90, v91
	v_add_f32_e32 v53, v92, v93
	v_add_f32_e32 v50, v50, v51
	v_add_f32_e32 v51, v52, v53
	v_add_f32_e32 v50, v50, v51
	ds_bpermute_b32 v51, v198, v50
	v_cvt_pk_bf16_f32 v52, v54, v55
	v_cvt_pk_bf16_f32 v53, v56, v57
	v_cvt_pk_bf16_f32 v54, v86, v87
	v_cvt_pk_bf16_f32 v55, v88, v89
	s_waitcnt lgkmcnt(0)
	v_add_f32_e32 v50, v50, v51
	ds_bpermute_b32 v51, v197, v50
	v_lshl_add_u64 v[56:57], v[102:103], 1, s[24:25]
	global_store_dwordx4 v[56:57], v[52:55], off
	s_and_saveexec_b64 s[8:9], s[2:3]
	s_cbranch_execz .LBB0_1606
	s_waitcnt lgkmcnt(0)
	v_add_f32_e32 v50, v50, v51
	ds_write_b32 v192, v50 offset:256
; #define LAS __attribute__((address_space(3)))
; template <class Epi>
; DEVI void gemm_phase(LAS unsigned char* lds, const Gemm g, const Epi& E) {
;     ...
;                 for (int mm = 0; mm < 2; ++mm) {
;                     const int m = m0 + mm;
;                     const int r = row0 + ai * HALF + m * 16; float rs = 1.f, part = 0.f;
;                     if constexpr (Epi::RS) rs = rsv[ai * 4 + m];
;                     if constexpr (Epi::PAIR) E.pair8(cur.b, r, cur.pn * HALF + wc * 32 + 8 * fq, acc[ai][0][m][0] * rs, acc[ai][0][m][1] * rs, acc[ai][1][m][0] * rs, acc[ai][1][m][1] * rs);
;                     else
; #pragma unroll
;                     for (int bj = 0; bj < 2; ++bj) {
;                         const int c = col0 + bj * HALF; f32x4 v0 = acc[ai][bj][m][0], v1 = acc[ai][bj][m][1];
;                         if constexpr (Epi::RS) { v0 = v0 * rs; v1 = v1 * rs; }
;                         if constexpr (Epi::PRE) part += E.frag_pre8(cur.b, r, c, v0, v1, pre[mm][bj][0], pre[mm][bj][1]);
;                         else if constexpr (Epi::PERM) E.frag8(cur.b, r, c, v0, v1);
;                         else { E.frag(cur.b, r, c, v0); E.frag(cur.b, r, c + 16, v1); }
;                     }
;                     if constexpr (Epi::SSQ) { part += __shfl_xor(part, 16); part += __shfl_xor(part, 32); if (fq == 0) ((LAS float*)(lds + 131072))[(wr * 4 + wc) * 128 + ai * 64 + m * 16 + fr] = part; }
.LBB0_1606:
	s_or_b64 exec, exec, s[8:9]
	s_waitcnt vmcnt(8)
	v_pk_add_f32 v[48:49], v[48:49], v[80:81]
	v_pk_add_f32 v[46:47], v[46:47], v[78:79]
	v_pk_add_f32 v[42:43], v[42:43], v[74:75]
	v_pk_add_f32 v[44:45], v[44:45], v[76:77]
	global_store_dwordx4 v[82:83], v[46:49], off nt
	global_store_dwordx4 v[82:83], v[42:45], off offset:16 nt
	v_cvt_pk_bf16_f32 v50, v46, v47
	v_cvt_pk_bf16_f32 v52, v42, v43
	v_mul_f32_e32 v47, v47, v47
	v_mul_f32_e32 v43, v43, v43
	v_fmac_f32_e32 v47, v46, v46
	v_mul_f32_e32 v46, v49, v49
	v_fmac_f32_e32 v43, v42, v42
	v_mul_f32_e32 v42, v45, v45
	v_fmac_f32_e32 v46, v48, v48
	v_fmac_f32_e32 v42, v44, v44
	v_add_f32_e32 v46, v47, v46
	v_add_f32_e32 v42, v43, v42
	s_waitcnt vmcnt(8)
	v_pk_add_f32 v[40:41], v[40:41], v[72:73]
	v_pk_add_f32 v[38:39], v[38:39], v[70:71]
	s_waitcnt lgkmcnt(0)
	v_cvt_pk_bf16_f32 v51, v48, v49
	v_add_f32_e32 v48, v46, v42
	v_pk_add_f32 v[42:43], v[34:35], v[66:67]
	v_mul_f32_e32 v34, v39, v39
	v_mul_f32_e32 v35, v41, v41
	v_cvt_pk_bf16_f32 v53, v44, v45
	v_pk_add_f32 v[44:45], v[36:37], v[68:69]
	v_fmac_f32_e32 v34, v38, v38
	v_fmac_f32_e32 v35, v40, v40
	v_add_f32_e32 v34, v34, v35
	v_mul_f32_e32 v35, v43, v43
	v_mul_f32_e32 v36, v45, v45
	v_fmac_f32_e32 v35, v42, v42
	v_fmac_f32_e32 v36, v44, v44
	v_add_f32_e32 v35, v35, v36
	v_add_f32_e32 v34, v34, v35
	v_add_f32_e32 v34, v48, v34
	ds_bpermute_b32 v35, v198, v34
	v_lshlrev_b64 v[54:55], 10, v[84:85]
	v_lshl_add_u64 v[56:57], v[54:55], 0, v[180:181]
	v_lshl_add_u64 v[56:57], v[56:57], 1, s[24:25]
	v_lshl_add_u64 v[46:47], v[54:55], 0, v[178:179]
	s_waitcnt lgkmcnt(0)
	v_add_f32_e32 v34, v34, v35
	ds_bpermute_b32 v35, v197, v34
	global_store_dwordx4 v[56:57], v[50:53], off
	global_store_dwordx4 v[82:83], v[38:41], off offset:512 nt
	global_store_dwordx4 v[82:83], v[42:45], off offset:528 nt
	v_cvt_pk_bf16_f32 v36, v38, v39
	v_cvt_pk_bf16_f32 v37, v40, v41
	v_cvt_pk_bf16_f32 v38, v42, v43
	v_cvt_pk_bf16_f32 v39, v44, v45
	v_lshl_add_u64 v[40:41], v[46:47], 1, s[24:25]
	global_store_dwordx4 v[40:41], v[36:39], off
	s_and_saveexec_b64 s[8:9], s[2:3]
	s_cbranch_execz .LBB0_1608
	s_waitcnt lgkmcnt(0)
	v_add_f32_e32 v34, v34, v35
	ds_write_b32 v192, v34 offset:320
; #define LAS __attribute__((address_space(3)))
;     DEVI f32x4 load(int r, int c) const { const bf16x4 y = *(const bf16x4*)(Y + (size_t)r * DM + c); return (f32x4){bf2f((u16)y[0]), bf2f((u16)y[1]), bf2f((u16)y[2]), bf2f((u16)y[3])}; }
; template <class Epi>
; DEVI void gemm_phase(LAS unsigned char* lds, const Gemm g, const Epi& E) {
;     ...
;                 if constexpr (Epi::PRE) {
; #pragma unroll
;                     for (int m = 0; m < 2; ++m)
; #pragma unroll
;                         for (int bj = 0; bj < 2; ++bj)
; #pragma unroll
;                             for (int n = 0; n < 2; ++n) pre[m][bj][n] = E.load(row0 + ai * HALF + (m0 + m) * 16, col0 + bj * HALF + n * NST);
;                 }
; #pragma unroll
;                 for (int mm = 0; mm < 2; ++mm) {
;                     const int m = m0 + mm;
;                     const int r = row0 + ai * HALF + m * 16; float rs = 1.f, part = 0.f;
;                     if constexpr (Epi::RS) rs = rsv[ai * 4 + m];
;                     if constexpr (Epi::PAIR) E.pair8(cur.b, r, cur.pn * HALF + wc * 32 + 8 * fq, acc[ai][0][m][0] * rs, acc[ai][0][m][1] * rs, acc[ai][1][m][0] * rs, acc[ai][1][m][1] * rs);
;                     else
; #pragma unroll
;                     for (int bj = 0; bj < 2; ++bj) {
;                         const int c = col0 + bj * HALF; f32x4 v0 = acc[ai][bj][m][0], v1 = acc[ai][bj][m][1];
;                         if constexpr (Epi::RS) { v0 = v0 * rs; v1 = v1 * rs; }
;                         if constexpr (Epi::PRE) part += E.frag_pre8(cur.b, r, c, v0, v1, pre[mm][bj][0], pre[mm][bj][1]);
;                         else if constexpr (Epi::PERM) E.frag8(cur.b, r, c, v0, v1);
;                         else { E.frag(cur.b, r, c, v0); E.frag(cur.b, r, c + 16, v1); }
;                     }
;                     if constexpr (Epi::SSQ) { part += __shfl_xor(part, 16); part += __shfl_xor(part, 32); if (fq == 0) ((LAS float*)(lds + 131072))[(wr * 4 + wc) * 128 + ai * 64 + m * 16 + fr] = part; }
.LBB0_1608:
	s_or_b64 exec, exec, s[8:9]
	v_add_u32_e32 v70, 0xa0, v182
	v_ashrrev_i32_e32 v71, 31, v70
	s_waitcnt lgkmcnt(0)
	v_lshlrev_b64 v[34:35], 12, v[70:71]
	v_lshl_add_u64 v[34:35], s[30:31], 0, v[34:35]
	v_lshl_add_u64 v[72:73], v[34:35], 0, v[184:185]
	global_load_dwordx4 v[54:57], v[72:73], off
	global_load_dwordx4 v[58:61], v[72:73], off offset:16
	global_load_dwordx4 v[62:65], v[72:73], off offset:512
	global_load_dwordx4 v[66:69], v[72:73], off offset:528
	v_add_u32_e32 v52, 0xb0, v182
	v_ashrrev_i32_e32 v53, 31, v52
	v_lshlrev_b64 v[34:35], 12, v[52:53]
	v_lshl_add_u64 v[34:35], s[30:31], 0, v[34:35]
	v_lshl_add_u64 v[50:51], v[34:35], 0, v[184:185]
	global_load_dwordx4 v[42:45], v[50:51], off offset:16
	global_load_dwordx4 v[46:49], v[50:51], off
	global_load_dwordx4 v[34:37], v[50:51], off offset:528
	global_load_dwordx4 v[38:41], v[50:51], off offset:512
	v_lshlrev_b64 v[70:71], 10, v[70:71]
	v_lshl_add_u64 v[74:75], v[70:71], 0, v[180:181]
	v_lshl_add_u64 v[74:75], v[74:75], 1, s[24:25]
	v_lshl_add_u64 v[70:71], v[70:71], 0, v[178:179]
	s_waitcnt vmcnt(7)
	v_pk_add_f32 v[32:33], v[32:33], v[56:57]
	v_pk_add_f32 v[30:31], v[30:31], v[54:55]
	s_waitcnt vmcnt(6)
	v_pk_add_f32 v[28:29], v[28:29], v[60:61]
	v_pk_add_f32 v[26:27], v[26:27], v[58:59]
	s_waitcnt vmcnt(5)
	v_pk_add_f32 v[24:25], v[24:25], v[64:65]
	v_pk_add_f32 v[22:23], v[22:23], v[62:63]
	s_waitcnt vmcnt(4)
	v_pk_add_f32 v[56:57], v[20:21], v[68:69]
	v_pk_add_f32 v[54:55], v[18:19], v[66:67]
	global_store_dwordx4 v[72:73], v[30:33], off nt
	global_store_dwordx4 v[72:73], v[26:29], off offset:16 nt
	v_cvt_pk_bf16_f32 v18, v30, v31
	v_cvt_pk_bf16_f32 v19, v32, v33
	v_cvt_pk_bf16_f32 v20, v26, v27
	v_cvt_pk_bf16_f32 v21, v28, v29
	v_mul_f32_e32 v31, v31, v31
	v_mul_f32_e32 v33, v33, v33
	v_mul_f32_e32 v27, v27, v27
	v_mul_f32_e32 v29, v29, v29
	v_mul_f32_e32 v58, v23, v23
	v_mul_f32_e32 v59, v25, v25
	v_mul_f32_e32 v60, v55, v55
	v_mul_f32_e32 v61, v57, v57
	v_fmac_f32_e32 v31, v30, v30
	v_fmac_f32_e32 v33, v32, v32
	v_fmac_f32_e32 v27, v26, v26
	v_fmac_f32_e32 v29, v28, v28
	v_fmac_f32_e32 v58, v22, v22
	v_fmac_f32_e32 v59, v24, v24
	v_fmac_f32_e32 v60, v54, v54
	v_fmac_f32_e32 v61, v56, v56
	global_store_dwordx4 v[74:75], v[18:21], off
	global_store_dwordx4 v[72:73], v[22:25], off offset:512 nt
	global_store_dwordx4 v[72:73], v[54:57], off offset:528 nt
	v_add_f32_e32 v18, v31, v33
	v_add_f32_e32 v19, v27, v29
	v_add_f32_e32 v20, v58, v59
	v_add_f32_e32 v21, v60, v61
	v_add_f32_e32 v18, v18, v19
	v_add_f32_e32 v19, v20, v21
	v_add_f32_e32 v18, v18, v19
	ds_bpermute_b32 v19, v198, v18
	v_cvt_pk_bf16_f32 v20, v22, v23
	v_cvt_pk_bf16_f32 v21, v24, v25
	v_cvt_pk_bf16_f32 v22, v54, v55
	v_cvt_pk_bf16_f32 v23, v56, v57
	s_waitcnt lgkmcnt(0)
	v_add_f32_e32 v18, v18, v19
	ds_bpermute_b32 v19, v197, v18
	v_lshl_add_u64 v[24:25], v[70:71], 1, s[24:25]
	global_store_dwordx4 v[24:25], v[20:23], off
	s_and_saveexec_b64 s[8:9], s[2:3]
	s_cbranch_execz .LBB0_1610
	s_waitcnt lgkmcnt(0)
	v_add_f32_e32 v18, v18, v19
	ds_write_b32 v192, v18 offset:384
.LBB0_1610:
	s_or_b64 exec, exec, s[8:9]
	s_waitcnt vmcnt(8)
	v_pk_add_f32 v[16:17], v[16:17], v[48:49]
	v_pk_add_f32 v[14:15], v[14:15], v[46:47]
	v_pk_add_f32 v[10:11], v[10:11], v[42:43]
	v_pk_add_f32 v[12:13], v[12:13], v[44:45]
	global_store_dwordx4 v[50:51], v[14:17], off nt
	global_store_dwordx4 v[50:51], v[10:13], off offset:16 nt
	v_cvt_pk_bf16_f32 v18, v14, v15
	v_cvt_pk_bf16_f32 v20, v10, v11
	v_mul_f32_e32 v15, v15, v15
	v_mul_f32_e32 v11, v11, v11
	v_fmac_f32_e32 v15, v14, v14
	v_mul_f32_e32 v14, v17, v17
	v_fmac_f32_e32 v11, v10, v10
	v_mul_f32_e32 v10, v13, v13
	v_fmac_f32_e32 v14, v16, v16
	v_fmac_f32_e32 v10, v12, v12
	v_add_f32_e32 v14, v15, v14
	v_add_f32_e32 v10, v11, v10
	s_waitcnt vmcnt(8)
	v_pk_add_f32 v[6:7], v[6:7], v[40:41]
	v_pk_add_f32 v[4:5], v[4:5], v[38:39]
	s_waitcnt lgkmcnt(0)
	v_cvt_pk_bf16_f32 v19, v16, v17
	v_add_f32_e32 v16, v14, v10
	v_pk_add_f32 v[10:11], v[0:1], v[34:35]
	v_mul_f32_e32 v0, v5, v5
	v_mul_f32_e32 v1, v7, v7
	v_cvt_pk_bf16_f32 v21, v12, v13
	v_pk_add_f32 v[12:13], v[2:3], v[36:37]
	v_fmac_f32_e32 v0, v4, v4
	v_fmac_f32_e32 v1, v6, v6
	v_add_f32_e32 v0, v0, v1
	v_mul_f32_e32 v1, v11, v11
	v_mul_f32_e32 v2, v13, v13
	v_fmac_f32_e32 v1, v10, v10
	v_fmac_f32_e32 v2, v12, v12
	v_add_f32_e32 v1, v1, v2
	v_add_f32_e32 v0, v0, v1
	v_add_f32_e32 v0, v16, v0
	ds_bpermute_b32 v1, v198, v0
	v_lshlrev_b64 v[22:23], 10, v[52:53]
	v_lshl_add_u64 v[24:25], v[22:23], 0, v[180:181]
	v_lshl_add_u64 v[24:25], v[24:25], 1, s[24:25]
	v_lshl_add_u64 v[14:15], v[22:23], 0, v[178:179]
	s_waitcnt lgkmcnt(0)
	v_add_f32_e32 v0, v0, v1
	ds_bpermute_b32 v1, v197, v0
	global_store_dwordx4 v[24:25], v[18:21], off
	global_store_dwordx4 v[50:51], v[4:7], off offset:512 nt
	global_store_dwordx4 v[50:51], v[10:13], off offset:528 nt
	v_cvt_pk_bf16_f32 v2, v4, v5
	v_cvt_pk_bf16_f32 v3, v6, v7
	v_cvt_pk_bf16_f32 v4, v10, v11
	v_cvt_pk_bf16_f32 v5, v12, v13
	v_lshl_add_u64 v[6:7], v[14:15], 1, s[24:25]
	global_store_dwordx4 v[6:7], v[2:5], off
	s_and_saveexec_b64 s[8:9], s[2:3]
	s_cbranch_execz .LBB0_1612
	s_waitcnt lgkmcnt(0)
	v_add_f32_e32 v0, v0, v1
	ds_write_b32 v192, v0 offset:448

; #define PG8_STAGE(bufoff, gbase, voff) do { _Pragma("unroll") for (int _i = 0; _i < 2; ++_i) \
;         __builtin_amdgcn_global_load_lds((const unsigned*)((const char*)(gbase) + (voff)[_i]), (LAS unsigned*)(lds + (bufoff) + ldsw + _i * 8192), 16, 0, 0); } while (0)
; #define PG8_LDA(dst, b, h) do { _Pragma("unroll") for (int m = 0; m < 4; ++m) _Pragma("unroll") for (int k = 0; k < 2; ++k) dst[m][k] = *(const LAS bf16x8*)(lds + PG8_SA(b, h) + aoff + m * 2048 + k * 1024); } while (0)
; #define PG8_LDB(dst, b, h) do { _Pragma("unroll") for (int n = 0; n < 2; ++n) _Pragma("unroll") for (int k = 0; k < 2; ++k) dst[n][k] = *(const LAS bf16x8*)(lds + PG8_SB(b, h) + boff + n * 2048 + k * 1024); } while (0)
; #define PG8_MMA(ai, bj, At, Bt) do { __builtin_amdgcn_s_setprio(1); _Pragma("unroll") for (int m = 0; m < 4; ++m) _Pragma("unroll") for (int n = 0; n < 2; ++n) _Pragma("unroll") for (int k = 0; k < 2; ++k) \
;         acc[ai][bj][m][n] = __builtin_amdgcn_mfma_f32_16x16x32_bf16(Bt[n][k], At[m][k], acc[ai][bj][m][n], 0, 0, 0); __builtin_amdgcn_s_setprio(0); } while (0)
; #define PG8_WAIT_L(n) asm volatile("s_waitcnt lgkmcnt(" #n ")" ::: "memory")
; #define PG8_BAR __builtin_amdgcn_s_barrier()
; #define PG8_SCHED __builtin_amdgcn_sched_barrier(0)
; template <class Epi>
; DEVI void gemm_phase(LAS unsigned char* lds, const Gemm g, const Epi& E) {
;     ...
;             PG8_LDB(B0, 0, 0); PG8_SCHED; PG8_LDA(At, 0, 0); PG8_STAGE(PG8_SA(1, 1), a1 + hstepA, voffA);
;             PG8_WAIT_L(8); PG8_BAR; PG8_WAIT_L(0); PG8_MMA(0, 0, At, B0); PG8_BAR; PG8_SCHED;
;             PG8_LDB(B1, 0, 1); PG8_STAGE(PG8_SB(0, 0), b2, voffB);
;             PG8_BAR; PG8_WAIT_L(0); PG8_MMA(0, 1, At, B1); PG8_BAR;
;             PG8_LDA(At, 0, 1); PG8_STAGE(PG8_SA(0, 0), a2, voffA);
;             PG8_BAR; PG8_WAIT_L(0); PG8_MMA(1, 0, At, B0); PG8_BAR; PG8_SCHED;
.LBB0_1747:
	s_add_u32 s36, s16, 0x100
	s_addc_u32 s37, s17, 0
	s_add_i32 s19, 0, 0x10000
	v_add_u32_e32 v142, s19, v191
	ds_read_b128 v[130:133], v142
	ds_read_b128 v[134:137], v142 offset:1024
	ds_read_b128 v[138:141], v142 offset:2048
	ds_read_b128 v[142:145], v142 offset:3072
	s_cmp_eq_u32 s18, 40
	s_cselect_b32 s69, s9, s37
	s_cselect_b32 s68, s8, s36
	s_cselect_b32 s47, s11, s13
	s_cselect_b32 s46, s10, s1
	v_lshl_add_u64 v[162:163], s[16:17], 0, v[152:153]
	s_add_i32 m0, s81, 0xc000
	ds_read_b128 v[178:181], v196
	ds_read_b128 v[182:185], v196 offset:1024
	ds_read_b128 v[186:189], v196 offset:2048
	ds_read_b128 v[198:201], v196 offset:3072
	ds_read_b128 v[202:205], v196 offset:4096
	ds_read_b128 v[206:209], v196 offset:5120
	ds_read_b128 v[214:217], v196 offset:6144
	ds_read_b128 v[218:221], v196 offset:7168
	global_load_lds_dwordx4 v[162:163], off
	s_add_i32 m0, s81, 0xe000
	v_lshl_add_u64 v[162:163], s[16:17], 0, v[176:177]
	global_load_lds_dwordx4 v[162:163], off
	s_waitcnt lgkmcnt(8)
	s_barrier
	s_waitcnt lgkmcnt(0)
	v_mfma_f32_16x16x32_bf16 v[126:129], v[130:133], v[178:181], v[126:129]
	v_mfma_f32_16x16x32_bf16 v[122:125], v[138:141], v[178:181], v[122:125]
	v_mfma_f32_16x16x32_bf16 v[110:113], v[130:133], v[186:189], v[110:113]
	v_mfma_f32_16x16x32_bf16 v[106:109], v[138:141], v[186:189], v[106:109]
	v_mfma_f32_16x16x32_bf16 v[94:97], v[130:133], v[202:205], v[94:97]
	v_mfma_f32_16x16x32_bf16 v[90:93], v[138:141], v[202:205], v[90:93]
	v_mfma_f32_16x16x32_bf16 v[78:81], v[130:133], v[214:217], v[78:81]
	v_mfma_f32_16x16x32_bf16 v[74:77], v[138:141], v[214:217], v[74:77]
	v_mfma_f32_16x16x32_bf16 v[126:129], v[134:137], v[182:185], v[126:129]
	v_mfma_f32_16x16x32_bf16 v[122:125], v[142:145], v[182:185], v[122:125]
	v_mfma_f32_16x16x32_bf16 v[110:113], v[134:137], v[198:201], v[110:113]
	v_mfma_f32_16x16x32_bf16 v[106:109], v[142:145], v[198:201], v[106:109]
	v_mfma_f32_16x16x32_bf16 v[94:97], v[134:137], v[206:209], v[94:97]
	v_mfma_f32_16x16x32_bf16 v[90:93], v[142:145], v[206:209], v[90:93]
	v_mfma_f32_16x16x32_bf16 v[78:81], v[134:137], v[218:221], v[78:81]
	v_mfma_f32_16x16x32_bf16 v[74:77], v[142:145], v[218:221], v[74:77]
	s_barrier
	s_add_i32 s26, 0, 0x14000
	v_add_u32_e32 v162, s26, v191
	s_add_i32 s16, s19, s80
	ds_read_b128 v[222:225], v162
	ds_read_b128 v[226:229], v162 offset:1024
	ds_read_b128 v[230:233], v162 offset:2048
	ds_read_b128 v[234:237], v162 offset:3072
	v_lshl_add_u64 v[162:163], s[46:47], 0, v[8:9]
	s_mov_b32 m0, s16
	v_lshl_add_u64 v[164:165], s[46:47], 0, v[150:151]
	global_load_lds_dwordx4 v[162:163], off
	s_add_i32 m0, s16, 0x2000
	s_nop 0
	global_load_lds_dwordx4 v[164:165], off
	s_barrier
	s_waitcnt lgkmcnt(0)
	v_mfma_f32_16x16x32_bf16 v[118:121], v[222:225], v[178:181], v[118:121]
	v_mfma_f32_16x16x32_bf16 v[114:117], v[230:233], v[178:181], v[114:117]
	v_mfma_f32_16x16x32_bf16 v[102:105], v[222:225], v[186:189], v[102:105]
	v_mfma_f32_16x16x32_bf16 v[98:101], v[230:233], v[186:189], v[98:101]
	v_mfma_f32_16x16x32_bf16 v[86:89], v[222:225], v[202:205], v[86:89]
	v_mfma_f32_16x16x32_bf16 v[82:85], v[230:233], v[202:205], v[82:85]
	v_mfma_f32_16x16x32_bf16 v[70:73], v[222:225], v[214:217], v[70:73]
	v_mfma_f32_16x16x32_bf16 v[66:69], v[230:233], v[214:217], v[66:69]
	v_mfma_f32_16x16x32_bf16 v[118:121], v[226:229], v[182:185], v[118:121]
	v_mfma_f32_16x16x32_bf16 v[114:117], v[234:237], v[182:185], v[114:117]
	v_mfma_f32_16x16x32_bf16 v[102:105], v[226:229], v[198:201], v[102:105]
	v_mfma_f32_16x16x32_bf16 v[98:101], v[234:237], v[198:201], v[98:101]
	v_mfma_f32_16x16x32_bf16 v[86:89], v[226:229], v[206:209], v[86:89]
	v_mfma_f32_16x16x32_bf16 v[82:85], v[234:237], v[206:209], v[82:85]
	v_mfma_f32_16x16x32_bf16 v[70:73], v[226:229], v[218:221], v[70:73]
	v_mfma_f32_16x16x32_bf16 v[66:69], v[234:237], v[218:221], v[66:69]
	s_mov_b32 m0, s81
	v_lshl_add_u64 v[238:239], s[68:69], 0, v[146:147]
	s_barrier
	ds_read_b128 v[178:181], v196 offset:16384
	ds_read_b128 v[182:185], v196 offset:17408
	ds_read_b128 v[186:189], v196 offset:18432
	ds_read_b128 v[198:201], v196 offset:19456
	ds_read_b128 v[202:205], v196 offset:20480
	ds_read_b128 v[206:209], v196 offset:21504
	ds_read_b128 v[214:217], v196 offset:22528
	ds_read_b128 v[218:221], v196 offset:23552
	global_load_lds_dwordx4 v[238:239], off
	s_mov_b32 m0, s82
	v_lshl_add_u64 v[240:241], s[68:69], 0, v[148:149]
	global_load_lds_dwordx4 v[240:241], off
	s_barrier
	s_waitcnt lgkmcnt(0)
	v_mfma_f32_16x16x32_bf16 v[62:65], v[130:133], v[178:181], v[62:65]
	v_mfma_f32_16x16x32_bf16 v[58:61], v[138:141], v[178:181], v[58:61]
	v_mfma_f32_16x16x32_bf16 v[46:49], v[130:133], v[186:189], v[46:49]
	v_mfma_f32_16x16x32_bf16 v[42:45], v[138:141], v[186:189], v[42:45]
	v_mfma_f32_16x16x32_bf16 v[30:33], v[130:133], v[202:205], v[30:33]
	v_mfma_f32_16x16x32_bf16 v[26:29], v[138:141], v[202:205], v[26:29]
	v_mfma_f32_16x16x32_bf16 v[14:17], v[130:133], v[214:217], v[14:17]
	v_mfma_f32_16x16x32_bf16 v[10:13], v[138:141], v[214:217], v[10:13]
	v_mfma_f32_16x16x32_bf16 v[62:65], v[134:137], v[182:185], v[62:65]
	v_mfma_f32_16x16x32_bf16 v[58:61], v[142:145], v[182:185], v[58:61]
	v_mfma_f32_16x16x32_bf16 v[46:49], v[134:137], v[198:201], v[46:49]
	v_mfma_f32_16x16x32_bf16 v[42:45], v[142:145], v[198:201], v[42:45]
	v_mfma_f32_16x16x32_bf16 v[30:33], v[134:137], v[206:209], v[30:33]
	v_mfma_f32_16x16x32_bf16 v[26:29], v[142:145], v[206:209], v[26:29]
	v_mfma_f32_16x16x32_bf16 v[14:17], v[134:137], v[218:221], v[14:17]
	v_mfma_f32_16x16x32_bf16 v[10:13], v[142:145], v[218:221], v[10:13]
	s_barrier
; #define PG8_STAGE(bufoff, gbase, voff) do { _Pragma("unroll") for (int _i = 0; _i < 2; ++_i) \
;         __builtin_amdgcn_global_load_lds((const unsigned*)((const char*)(gbase) + (voff)[_i]), (LAS unsigned*)(lds + (bufoff) + ldsw + _i * 8192), 16, 0, 0); } while (0)
; #define PG8_LDA(dst, b, h) do { _Pragma("unroll") for (int m = 0; m < 4; ++m) _Pragma("unroll") for (int k = 0; k < 2; ++k) dst[m][k] = *(const LAS bf16x8*)(lds + PG8_SA(b, h) + aoff + m * 2048 + k * 1024); } while (0)
; #define PG8_LDB(dst, b, h) do { _Pragma("unroll") for (int n = 0; n < 2; ++n) _Pragma("unroll") for (int k = 0; k < 2; ++k) dst[n][k] = *(const LAS bf16x8*)(lds + PG8_SB(b, h) + boff + n * 2048 + k * 1024); } while (0)
; #define PG8_MMA(ai, bj, At, Bt) do { __builtin_amdgcn_s_setprio(1); _Pragma("unroll") for (int m = 0; m < 4; ++m) _Pragma("unroll") for (int n = 0; n < 2; ++n) _Pragma("unroll") for (int k = 0; k < 2; ++k) \
;         acc[ai][bj][m][n] = __builtin_amdgcn_mfma_f32_16x16x32_bf16(Bt[n][k], At[m][k], acc[ai][bj][m][n], 0, 0, 0); __builtin_amdgcn_s_setprio(0); } while (0)
; #define PG8_WAIT_V(n) asm volatile("s_waitcnt vmcnt(" #n ")" ::: "memory")
; #define PG8_WAIT_L(n) asm volatile("s_waitcnt lgkmcnt(" #n ")" ::: "memory")
; #define PG8_BAR __builtin_amdgcn_s_barrier()
; #define PG8_SCHED __builtin_amdgcn_sched_barrier(0)
; template <class Epi>
; DEVI void gemm_phase(LAS unsigned char* lds, const Gemm g, const Epi& E) {
;     ...
;             PG8_STAGE(PG8_SB(0, 1), b2 + hstepB, voffB);
;             PG8_WAIT_V(6); PG8_BAR; PG8_MMA(1, 1, At, B1); PG8_BAR;
;             PG8_LDB(B0, 1, 0); PG8_SCHED; PG8_LDA(At, 1, 0); PG8_STAGE(PG8_SA(0, 1), a2 + hstepA, voffA);
;             PG8_WAIT_L(8); PG8_BAR; PG8_WAIT_L(0); PG8_MMA(0, 0, At, B0); PG8_BAR; PG8_SCHED;
;             PG8_LDB(B1, 1, 1); PG8_STAGE(PG8_SB(1, 0), b3, voffB);
;             PG8_BAR; PG8_WAIT_L(0); PG8_MMA(0, 1, At, B1); PG8_BAR;
;             PG8_LDA(At, 1, 1); PG8_STAGE(PG8_SA(1, 0), a3, voffA);
	s_add_u32 s16, s46, 0xb0000
	s_addc_u32 s17, s47, 0
	s_add_i32 s19, s26, s80
	s_mov_b32 m0, s19
	v_lshl_add_u64 v[130:131], s[16:17], 0, v[8:9]
	global_load_lds_dwordx4 v[130:131], off
	s_add_i32 m0, s19, 0x2000
	v_lshl_add_u64 v[130:131], s[16:17], 0, v[150:151]
	global_load_lds_dwordx4 v[130:131], off
	s_waitcnt vmcnt(6)
	s_barrier
	v_mfma_f32_16x16x32_bf16 v[54:57], v[222:225], v[178:181], v[54:57]
	v_mfma_f32_16x16x32_bf16 v[50:53], v[230:233], v[178:181], v[50:53]
	v_mfma_f32_16x16x32_bf16 v[38:41], v[222:225], v[186:189], v[38:41]
	v_mfma_f32_16x16x32_bf16 v[34:37], v[230:233], v[186:189], v[34:37]
	v_mfma_f32_16x16x32_bf16 v[22:25], v[222:225], v[202:205], v[22:25]
	v_mfma_f32_16x16x32_bf16 v[18:21], v[230:233], v[202:205], v[18:21]
	v_mfma_f32_16x16x32_bf16 v[4:7], v[222:225], v[214:217], v[4:7]
	v_mfma_f32_16x16x32_bf16 v[0:3], v[230:233], v[214:217], v[0:3]
	v_mfma_f32_16x16x32_bf16 v[54:57], v[226:229], v[182:185], v[54:57]
	v_mfma_f32_16x16x32_bf16 v[50:53], v[234:237], v[182:185], v[50:53]
	v_mfma_f32_16x16x32_bf16 v[38:41], v[226:229], v[198:201], v[38:41]
	v_mfma_f32_16x16x32_bf16 v[34:37], v[234:237], v[198:201], v[34:37]
	v_mfma_f32_16x16x32_bf16 v[22:25], v[226:229], v[206:209], v[22:25]
	v_mfma_f32_16x16x32_bf16 v[18:21], v[234:237], v[206:209], v[18:21]
	v_mfma_f32_16x16x32_bf16 v[4:7], v[226:229], v[218:221], v[4:7]
	v_mfma_f32_16x16x32_bf16 v[0:3], v[234:237], v[218:221], v[0:3]
	s_add_i32 s19, 0, 0x18000
	v_add_u32_e32 v142, s19, v191
	s_barrier
	ds_read_b128 v[130:133], v142
	ds_read_b128 v[134:137], v142 offset:1024
	ds_read_b128 v[138:141], v142 offset:2048
	ds_read_b128 v[142:145], v142 offset:3072
	s_add_u32 s16, s68, 0xb0000
	s_addc_u32 s17, s69, 0
	s_mov_b32 m0, s83
	v_lshl_add_u64 v[222:223], s[16:17], 0, v[146:147]
	ds_read_b128 v[178:181], v196 offset:32768
	ds_read_b128 v[182:185], v196 offset:33792
	ds_read_b128 v[186:189], v196 offset:34816
	ds_read_b128 v[198:201], v196 offset:35840
	ds_read_b128 v[202:205], v196 offset:36864
	ds_read_b128 v[206:209], v196 offset:37888
	ds_read_b128 v[214:217], v196 offset:38912
	ds_read_b128 v[218:221], v196 offset:39936
	global_load_lds_dwordx4 v[222:223], off
	s_mov_b32 m0, s84
	v_lshl_add_u64 v[222:223], s[16:17], 0, v[148:149]
	global_load_lds_dwordx4 v[222:223], off
	s_waitcnt lgkmcnt(8)
	s_barrier
	s_waitcnt lgkmcnt(0)
	v_mfma_f32_16x16x32_bf16 v[126:129], v[130:133], v[178:181], v[126:129]
	v_mfma_f32_16x16x32_bf16 v[122:125], v[138:141], v[178:181], v[122:125]
	v_mfma_f32_16x16x32_bf16 v[110:113], v[130:133], v[186:189], v[110:113]
	v_mfma_f32_16x16x32_bf16 v[106:109], v[138:141], v[186:189], v[106:109]
	v_mfma_f32_16x16x32_bf16 v[94:97], v[130:133], v[202:205], v[94:97]
	v_mfma_f32_16x16x32_bf16 v[90:93], v[138:141], v[202:205], v[90:93]
	v_mfma_f32_16x16x32_bf16 v[78:81], v[130:133], v[214:217], v[78:81]
	v_mfma_f32_16x16x32_bf16 v[74:77], v[138:141], v[214:217], v[74:77]
	v_mfma_f32_16x16x32_bf16 v[126:129], v[134:137], v[182:185], v[126:129]
	v_mfma_f32_16x16x32_bf16 v[122:125], v[142:145], v[182:185], v[122:125]
	v_mfma_f32_16x16x32_bf16 v[110:113], v[134:137], v[198:201], v[110:113]
	v_mfma_f32_16x16x32_bf16 v[106:109], v[142:145], v[198:201], v[106:109]
	v_mfma_f32_16x16x32_bf16 v[94:97], v[134:137], v[206:209], v[94:97]
	v_mfma_f32_16x16x32_bf16 v[90:93], v[142:145], v[206:209], v[90:93]
	v_mfma_f32_16x16x32_bf16 v[78:81], v[134:137], v[218:221], v[78:81]
	v_mfma_f32_16x16x32_bf16 v[74:77], v[142:145], v[218:221], v[74:77]
	s_barrier
	s_add_i32 s26, 0, 0x1c000
	s_add_i32 s16, s19, s80
	v_add_u32_e32 v197, s26, v191
	v_lshl_add_u64 v[162:163], v[162:163], 0, s[70:71]
	s_mov_b32 m0, s16
	ds_read_b128 v[222:225], v197
	ds_read_b128 v[226:229], v197 offset:1024
	ds_read_b128 v[230:233], v197 offset:2048
	ds_read_b128 v[234:237], v197 offset:3072
	global_load_lds_dwordx4 v[162:163], off
	s_add_i32 m0, s16, 0x2000
	v_lshl_add_u64 v[162:163], v[164:165], 0, s[70:71]
	global_load_lds_dwordx4 v[162:163], off
	s_barrier
	s_waitcnt lgkmcnt(0)
	v_mfma_f32_16x16x32_bf16 v[118:121], v[222:225], v[178:181], v[118:121]
	v_mfma_f32_16x16x32_bf16 v[114:117], v[230:233], v[178:181], v[114:117]
	v_mfma_f32_16x16x32_bf16 v[102:105], v[222:225], v[186:189], v[102:105]
	v_mfma_f32_16x16x32_bf16 v[98:101], v[230:233], v[186:189], v[98:101]
	v_mfma_f32_16x16x32_bf16 v[86:89], v[222:225], v[202:205], v[86:89]
	v_mfma_f32_16x16x32_bf16 v[82:85], v[230:233], v[202:205], v[82:85]
	v_mfma_f32_16x16x32_bf16 v[70:73], v[222:225], v[214:217], v[70:73]
	v_mfma_f32_16x16x32_bf16 v[66:69], v[230:233], v[214:217], v[66:69]
	v_mfma_f32_16x16x32_bf16 v[118:121], v[226:229], v[182:185], v[118:121]
	v_mfma_f32_16x16x32_bf16 v[114:117], v[234:237], v[182:185], v[114:117]
	v_mfma_f32_16x16x32_bf16 v[102:105], v[226:229], v[198:201], v[102:105]
	v_mfma_f32_16x16x32_bf16 v[98:101], v[234:237], v[198:201], v[98:101]
	v_mfma_f32_16x16x32_bf16 v[86:89], v[226:229], v[206:209], v[86:89]
	v_mfma_f32_16x16x32_bf16 v[82:85], v[234:237], v[206:209], v[82:85]
	v_mfma_f32_16x16x32_bf16 v[70:73], v[226:229], v[218:221], v[70:73]
	v_mfma_f32_16x16x32_bf16 v[66:69], v[234:237], v[218:221], v[66:69]
	s_mov_b32 m0, s76
	v_lshl_add_u64 v[162:163], v[238:239], 0, s[70:71]
	s_barrier
	ds_read_b128 v[178:181], v196 offset:49152
	ds_read_b128 v[182:185], v196 offset:50176
	ds_read_b128 v[186:189], v196 offset:51200
	ds_read_b128 v[198:201], v196 offset:52224
	ds_read_b128 v[202:205], v196 offset:53248
	ds_read_b128 v[206:209], v196 offset:54272
	ds_read_b128 v[214:217], v196 offset:55296
	ds_read_b128 v[218:221], v196 offset:56320
	global_load_lds_dwordx4 v[162:163], off
	s_mov_b32 m0, s77
	v_lshl_add_u64 v[162:163], v[240:241], 0, s[70:71]
	global_load_lds_dwordx4 v[162:163], off
	s_barrier
; #define LAS __attribute__((address_space(3)))
; #define PG8_STAGE(bufoff, gbase, voff) do { _Pragma("unroll") for (int _i = 0; _i < 2; ++_i) \
;         __builtin_amdgcn_global_load_lds((const unsigned*)((const char*)(gbase) + (voff)[_i]), (LAS unsigned*)(lds + (bufoff) + ldsw + _i * 8192), 16, 0, 0); } while (0)
; #define PG8_WAIT_V(n) asm volatile("s_waitcnt vmcnt(" #n ")" ::: "memory")
; template <class Epi>
; DEVI void gemm_phase(LAS unsigned char* lds, const Gemm g, const Epi& E) {
;     ...
;             PG8_BAR; PG8_WAIT_L(0); PG8_MMA(1, 0, At, B0); PG8_BAR; PG8_SCHED;
;             PG8_STAGE(PG8_SB(1, 1), b3 + hstepB, voffB);
;             PG8_WAIT_V(6); PG8_BAR; PG8_MMA(1, 1, At, B1); PG8_BAR;
;     ...
;                 if constexpr (Epi::PRE) {
; #pragma unroll
;                     for (int m = 0; m < 2; ++m)
; #pragma unroll
;                         for (int bj = 0; bj < 2; ++bj)
; #pragma unroll
;                             for (int n = 0; n < 2; ++n) pre[m][bj][n] = E.load(row0 + ai * HALF + (m0 + m) * 16, col0 + bj * HALF + n * NST);
;                 }
; #pragma unroll
;                 for (int mm = 0; mm < 2; ++mm) {
;                     const int m = m0 + mm;
;                     const int r = row0 + ai * HALF + m * 16; float rs = 1.f, part = 0.f;
;                     if constexpr (Epi::RS) rs = rsv[ai * 4 + m];
;                     if constexpr (Epi::PAIR) E.pair8(cur.b, r, cur.pn * HALF + wc * 32 + 8 * fq, acc[ai][0][m][0] * rs, acc[ai][0][m][1] * rs, acc[ai][1][m][0] * rs, acc[ai][1][m][1] * rs);
;                     else
; #pragma unroll
;                     for (int bj = 0; bj < 2; ++bj) {
;                         const int c = col0 + bj * HALF; f32x4 v0 = acc[ai][bj][m][0], v1 = acc[ai][bj][m][1];
;                         if constexpr (Epi::RS) { v0 = v0 * rs; v1 = v1 * rs; }
;                         if constexpr (Epi::PRE) part += E.frag_pre8(cur.b, r, c, v0, v1, pre[mm][bj][0], pre[mm][bj][1]);
;                         else if constexpr (Epi::PERM) E.frag8(cur.b, r, c, v0, v1);
;                         else { E.frag(cur.b, r, c, v0); E.frag(cur.b, r, c + 16, v1); }
;                     }
;                     if constexpr (Epi::SSQ) { part += __shfl_xor(part, 16); part += __shfl_xor(part, 32); if (fq == 0) ((LAS float*)(lds + 131072))[(wr * 4 + wc) * 128 + ai * 64 + m * 16 + fr] = part; }
	s_waitcnt lgkmcnt(0)
	v_mfma_f32_16x16x32_bf16 v[62:65], v[130:133], v[178:181], v[62:65]
	v_mfma_f32_16x16x32_bf16 v[58:61], v[138:141], v[178:181], v[58:61]
	v_mfma_f32_16x16x32_bf16 v[46:49], v[130:133], v[186:189], v[46:49]
	v_mfma_f32_16x16x32_bf16 v[42:45], v[138:141], v[186:189], v[42:45]
	v_mfma_f32_16x16x32_bf16 v[30:33], v[130:133], v[202:205], v[30:33]
	v_mfma_f32_16x16x32_bf16 v[26:29], v[138:141], v[202:205], v[26:29]
	v_mfma_f32_16x16x32_bf16 v[14:17], v[130:133], v[214:217], v[14:17]
	v_mfma_f32_16x16x32_bf16 v[10:13], v[138:141], v[214:217], v[10:13]
	v_mfma_f32_16x16x32_bf16 v[62:65], v[134:137], v[182:185], v[62:65]
	v_mfma_f32_16x16x32_bf16 v[58:61], v[142:145], v[182:185], v[58:61]
	v_mfma_f32_16x16x32_bf16 v[46:49], v[134:137], v[198:201], v[46:49]
	v_mfma_f32_16x16x32_bf16 v[42:45], v[142:145], v[198:201], v[42:45]
	v_mfma_f32_16x16x32_bf16 v[30:33], v[134:137], v[206:209], v[30:33]
	v_mfma_f32_16x16x32_bf16 v[26:29], v[142:145], v[206:209], v[26:29]
	v_mfma_f32_16x16x32_bf16 v[14:17], v[134:137], v[218:221], v[14:17]
	v_mfma_f32_16x16x32_bf16 v[10:13], v[142:145], v[218:221], v[10:13]
	s_barrier
	s_add_u32 s16, s46, 0xb0080
	s_addc_u32 s17, s47, 0
	s_add_i32 s19, s26, s80
	s_mov_b32 m0, s19
	v_lshl_add_u64 v[130:131], s[16:17], 0, v[8:9]
	global_load_lds_dwordx4 v[130:131], off
	s_add_i32 m0, s19, 0x2000
	v_lshl_add_u64 v[130:131], s[16:17], 0, v[150:151]
	global_load_lds_dwordx4 v[130:131], off
	s_waitcnt vmcnt(6)
	s_barrier
	v_mfma_f32_16x16x32_bf16 v[54:57], v[222:225], v[178:181], v[54:57]
	v_mfma_f32_16x16x32_bf16 v[50:53], v[230:233], v[178:181], v[50:53]
	v_mfma_f32_16x16x32_bf16 v[38:41], v[222:225], v[186:189], v[38:41]
	v_mfma_f32_16x16x32_bf16 v[34:37], v[230:233], v[186:189], v[34:37]
	v_mfma_f32_16x16x32_bf16 v[22:25], v[222:225], v[202:205], v[22:25]
	v_mfma_f32_16x16x32_bf16 v[18:21], v[230:233], v[202:205], v[18:21]
	v_mfma_f32_16x16x32_bf16 v[4:7], v[222:225], v[214:217], v[4:7]
	v_mfma_f32_16x16x32_bf16 v[0:3], v[230:233], v[214:217], v[0:3]
	v_mfma_f32_16x16x32_bf16 v[54:57], v[226:229], v[182:185], v[54:57]
	v_mfma_f32_16x16x32_bf16 v[50:53], v[234:237], v[182:185], v[50:53]
	v_mfma_f32_16x16x32_bf16 v[38:41], v[226:229], v[198:201], v[38:41]
	v_mfma_f32_16x16x32_bf16 v[34:37], v[234:237], v[198:201], v[34:37]
	v_mfma_f32_16x16x32_bf16 v[22:25], v[226:229], v[206:209], v[22:25]
	v_mfma_f32_16x16x32_bf16 v[18:21], v[234:237], v[206:209], v[18:21]
	v_mfma_f32_16x16x32_bf16 v[4:7], v[226:229], v[218:221], v[4:7]
	v_mfma_f32_16x16x32_bf16 v[0:3], v[234:237], v[218:221], v[0:3]
	s_add_i32 s18, s18, 2
	s_add_u32 s1, s1, 0x100
	s_addc_u32 s13, s13, 0
	s_cmp_gt_u32 s18, 41
	s_mov_b64 s[16:17], s[36:37]
	s_barrier
	s_cbranch_scc0 .LBB0_1747
	s_setprio 0
	s_lshl_b32 s0, s0, 8
	v_add_u32_e32 v182, s0, v190
	v_lshl_or_b32 v180, s12, 8, v195
	v_ashrrev_i32_e32 v183, 31, v182
	v_lshlrev_b64 v[130:131], 12, v[182:183]
	v_ashrrev_i32_e32 v181, 31, v180
	v_lshl_add_u64 v[130:131], s[30:31], 0, v[130:131]
	v_lshlrev_b64 v[184:185], 2, v[180:181]
	v_lshl_add_u64 v[162:163], v[130:131], 0, v[184:185]
	global_load_dwordx4 v[200:203], v[162:163], off
	global_load_dwordx4 v[204:207], v[162:163], off offset:16
	global_load_dwordx4 v[214:217], v[162:163], off offset:512
	global_load_dwordx4 v[218:221], v[162:163], off offset:528
	v_or_b32_e32 v188, 16, v182
	v_ashrrev_i32_e32 v189, 31, v188
	v_lshlrev_b64 v[130:131], 12, v[188:189]
	v_lshl_add_u64 v[130:131], s[30:31], 0, v[130:131]
	v_lshl_add_u64 v[186:187], v[130:131], 0, v[184:185]
	global_load_dwordx4 v[138:141], v[186:187], off offset:16
	global_load_dwordx4 v[142:145], v[186:187], off
	global_load_dwordx4 v[130:133], v[186:187], off offset:528
	global_load_dwordx4 v[134:137], v[186:187], off offset:512
	v_and_b32_e32 v165, 64, v155
	v_xor_b32_e32 v164, 16, v155
	v_add_u32_e32 v165, 64, v165
	v_xor_b32_e32 v179, 32, v155
	v_cmp_lt_i32_e32 vcc, v164, v165
	v_or_b32_e32 v178, 0x80, v180
	s_waitcnt vmcnt(0)
	v_pk_add_f32 v[128:129], v[128:129], v[202:203]
	v_cndmask_b32_e32 v164, v155, v164, vcc
	v_cmp_lt_i32_e32 vcc, v179, v165
	v_lshlrev_b32_e32 v198, 2, v164
	v_pk_add_f32 v[126:127], v[126:127], v[200:201]
	v_cndmask_b32_e32 v165, v155, v179, vcc
	v_lshlrev_b32_e32 v197, 2, v165
	v_lshlrev_b64 v[164:165], 10, v[182:183]
	v_pk_add_f32 v[124:125], v[124:125], v[206:207]
	v_pk_add_f32 v[122:123], v[122:123], v[204:205]
	v_pk_add_f32 v[120:121], v[120:121], v[216:217]
	v_pk_add_f32 v[118:119], v[118:119], v[214:215]
	v_pk_add_f32 v[202:203], v[116:117], v[220:221]
	v_pk_add_f32 v[200:201], v[114:115], v[218:219]
	v_lshl_add_u64 v[208:209], v[164:165], 0, v[180:181]
	global_store_dwordx4 v[162:163], v[126:129], off nt
	global_store_dwordx4 v[162:163], v[122:125], off offset:16 nt
	v_cvt_pk_bf16_f32 v114, v126, v127
	v_cvt_pk_bf16_f32 v115, v128, v129
	v_cvt_pk_bf16_f32 v116, v122, v123
	v_cvt_pk_bf16_f32 v117, v124, v125
	v_mul_f32_e32 v127, v127, v127
	v_mul_f32_e32 v129, v129, v129
	v_mul_f32_e32 v123, v123, v123
	v_mul_f32_e32 v125, v125, v125
	v_mul_f32_e32 v183, v119, v119
	v_mul_f32_e32 v199, v121, v121
	v_mul_f32_e32 v204, v201, v201
	v_mul_f32_e32 v205, v203, v203
	v_lshl_add_u64 v[208:209], v[208:209], 1, s[24:25]
	v_fmac_f32_e32 v127, v126, v126
	v_fmac_f32_e32 v129, v128, v128
	v_fmac_f32_e32 v123, v122, v122
	v_fmac_f32_e32 v125, v124, v124
	v_fmac_f32_e32 v183, v118, v118
	v_fmac_f32_e32 v199, v120, v120
	v_fmac_f32_e32 v204, v200, v200
	v_fmac_f32_e32 v205, v202, v202
	global_store_dwordx4 v[208:209], v[114:117], off
	v_ashrrev_i32_e32 v179, 31, v178
	v_lshl_add_u64 v[164:165], v[164:165], 0, v[178:179]
	v_add_f32_e32 v114, v127, v129
	v_add_f32_e32 v115, v123, v125
	v_add_f32_e32 v116, v183, v199
	v_add_f32_e32 v117, v204, v205
	v_add_f32_e32 v114, v114, v115
	v_add_f32_e32 v115, v116, v117
	v_add_f32_e32 v114, v114, v115
	ds_bpermute_b32 v115, v198, v114
	global_store_dwordx4 v[162:163], v[118:121], off offset:512 nt
	global_store_dwordx4 v[162:163], v[200:203], off offset:528 nt
	v_cvt_pk_bf16_f32 v116, v118, v119
	v_cvt_pk_bf16_f32 v117, v120, v121
	v_cvt_pk_bf16_f32 v118, v200, v201
	s_waitcnt lgkmcnt(0)
	v_add_f32_e32 v114, v114, v115
	ds_bpermute_b32 v115, v197, v114
	v_cvt_pk_bf16_f32 v119, v202, v203
	v_lshl_add_u64 v[120:121], v[164:165], 1, s[24:25]
	global_store_dwordx4 v[120:121], v[116:119], off
	s_and_saveexec_b64 s[16:17], s[2:3]
	s_cbranch_execz .LBB0_1750
	s_waitcnt lgkmcnt(0)
	v_add_f32_e32 v114, v114, v115
	ds_write_b32 v192, v114
; #define LAS __attribute__((address_space(3)))
;     DEVI f32x4 load(int r, int c) const { const bf16x4 y = *(const bf16x4*)(Y + (size_t)r * DM + c); return (f32x4){bf2f((u16)y[0]), bf2f((u16)y[1]), bf2f((u16)y[2]), bf2f((u16)y[3])}; }
; template <class Epi>
; DEVI void gemm_phase(LAS unsigned char* lds, const Gemm g, const Epi& E) {
;     ...
;                             for (int n = 0; n < 2; ++n) pre[m][bj][n] = E.load(row0 + ai * HALF + (m0 + m) * 16, col0 + bj * HALF + n * NST);
;                 }
; #pragma unroll
;                 for (int mm = 0; mm < 2; ++mm) {
;                     const int m = m0 + mm;
;                     const int r = row0 + ai * HALF + m * 16; float rs = 1.f, part = 0.f;
;                     if constexpr (Epi::RS) rs = rsv[ai * 4 + m];
;                     if constexpr (Epi::PAIR) E.pair8(cur.b, r, cur.pn * HALF + wc * 32 + 8 * fq, acc[ai][0][m][0] * rs, acc[ai][0][m][1] * rs, acc[ai][1][m][0] * rs, acc[ai][1][m][1] * rs);
;                     else
; #pragma unroll
;                     for (int bj = 0; bj < 2; ++bj) {
;                         const int c = col0 + bj * HALF; f32x4 v0 = acc[ai][bj][m][0], v1 = acc[ai][bj][m][1];
;                         if constexpr (Epi::RS) { v0 = v0 * rs; v1 = v1 * rs; }
;                         if constexpr (Epi::PRE) part += E.frag_pre8(cur.b, r, c, v0, v1, pre[mm][bj][0], pre[mm][bj][1]);
;                         else if constexpr (Epi::PERM) E.frag8(cur.b, r, c, v0, v1);
;                         else { E.frag(cur.b, r, c, v0); E.frag(cur.b, r, c + 16, v1); }
;                     }
;                     if constexpr (Epi::SSQ) { part += __shfl_xor(part, 16); part += __shfl_xor(part, 32); if (fq == 0) ((LAS float*)(lds + 131072))[(wr * 4 + wc) * 128 + ai * 64 + m * 16 + fr] = part; }
.LBB0_1750:
	s_or_b64 exec, exec, s[16:17]
	v_pk_add_f32 v[112:113], v[112:113], v[144:145]
	v_pk_add_f32 v[110:111], v[110:111], v[142:143]
	v_pk_add_f32 v[106:107], v[106:107], v[138:139]
	v_pk_add_f32 v[108:109], v[108:109], v[140:141]
	global_store_dwordx4 v[186:187], v[110:113], off nt
	global_store_dwordx4 v[186:187], v[106:109], off offset:16 nt
	v_cvt_pk_bf16_f32 v114, v110, v111
	v_cvt_pk_bf16_f32 v116, v106, v107
	v_mul_f32_e32 v111, v111, v111
	v_mul_f32_e32 v107, v107, v107
	v_fmac_f32_e32 v111, v110, v110
	v_mul_f32_e32 v110, v113, v113
	v_fmac_f32_e32 v107, v106, v106
	v_mul_f32_e32 v106, v109, v109
	v_fmac_f32_e32 v110, v112, v112
	v_fmac_f32_e32 v106, v108, v108
	v_add_f32_e32 v110, v111, v110
	v_add_f32_e32 v106, v107, v106
	v_pk_add_f32 v[104:105], v[104:105], v[136:137]
	v_pk_add_f32 v[102:103], v[102:103], v[134:135]
	s_waitcnt lgkmcnt(0)
	v_cvt_pk_bf16_f32 v115, v112, v113
	v_add_f32_e32 v112, v110, v106
	v_pk_add_f32 v[106:107], v[98:99], v[130:131]
	v_mul_f32_e32 v98, v103, v103
	v_mul_f32_e32 v99, v105, v105
	v_cvt_pk_bf16_f32 v117, v108, v109
	v_pk_add_f32 v[108:109], v[100:101], v[132:133]
	v_fmac_f32_e32 v98, v102, v102
	v_fmac_f32_e32 v99, v104, v104
	v_add_f32_e32 v98, v98, v99
	v_mul_f32_e32 v99, v107, v107
	v_mul_f32_e32 v100, v109, v109
	v_fmac_f32_e32 v99, v106, v106
	v_fmac_f32_e32 v100, v108, v108
	v_add_f32_e32 v99, v99, v100
	v_add_f32_e32 v98, v98, v99
	v_add_f32_e32 v98, v112, v98
	ds_bpermute_b32 v99, v198, v98
	v_lshlrev_b64 v[118:119], 10, v[188:189]
	v_lshl_add_u64 v[120:121], v[118:119], 0, v[180:181]
	v_lshl_add_u64 v[120:121], v[120:121], 1, s[24:25]
	v_lshl_add_u64 v[110:111], v[118:119], 0, v[178:179]
	s_waitcnt lgkmcnt(0)
	v_add_f32_e32 v98, v98, v99
	ds_bpermute_b32 v99, v197, v98
	global_store_dwordx4 v[120:121], v[114:117], off
	global_store_dwordx4 v[186:187], v[102:105], off offset:512 nt
	global_store_dwordx4 v[186:187], v[106:109], off offset:528 nt
	v_cvt_pk_bf16_f32 v100, v102, v103
	v_cvt_pk_bf16_f32 v101, v104, v105
	v_cvt_pk_bf16_f32 v102, v106, v107
	v_cvt_pk_bf16_f32 v103, v108, v109
	v_lshl_add_u64 v[104:105], v[110:111], 1, s[24:25]
	global_store_dwordx4 v[104:105], v[100:103], off
	s_and_saveexec_b64 s[16:17], s[2:3]
	s_cbranch_execz .LBB0_1752
	s_waitcnt lgkmcnt(0)
	v_add_f32_e32 v98, v98, v99
	ds_write_b32 v192, v98 offset:64
.LBB0_1752:
	s_or_b64 exec, exec, s[16:17]
	v_or_b32_e32 v134, 32, v182
	v_ashrrev_i32_e32 v135, 31, v134
	s_waitcnt lgkmcnt(0)
	v_lshlrev_b64 v[98:99], 12, v[134:135]
	v_lshl_add_u64 v[98:99], s[30:31], 0, v[98:99]
	v_lshl_add_u64 v[136:137], v[98:99], 0, v[184:185]
	global_load_dwordx4 v[118:121], v[136:137], off
	global_load_dwordx4 v[122:125], v[136:137], off offset:16
	global_load_dwordx4 v[126:129], v[136:137], off offset:512
	global_load_dwordx4 v[130:133], v[136:137], off offset:528
	v_or_b32_e32 v116, 48, v182
	v_ashrrev_i32_e32 v117, 31, v116
	v_lshlrev_b64 v[98:99], 12, v[116:117]
	v_lshl_add_u64 v[98:99], s[30:31], 0, v[98:99]
	v_lshl_add_u64 v[114:115], v[98:99], 0, v[184:185]
	global_load_dwordx4 v[106:109], v[114:115], off offset:16
	global_load_dwordx4 v[110:113], v[114:115], off
	global_load_dwordx4 v[98:101], v[114:115], off offset:528
	global_load_dwordx4 v[102:105], v[114:115], off offset:512
	v_lshlrev_b64 v[134:135], 10, v[134:135]
	v_lshl_add_u64 v[138:139], v[134:135], 0, v[180:181]
	v_lshl_add_u64 v[138:139], v[138:139], 1, s[24:25]
	v_lshl_add_u64 v[134:135], v[134:135], 0, v[178:179]
	s_waitcnt vmcnt(7)
	v_pk_add_f32 v[96:97], v[96:97], v[120:121]
	v_pk_add_f32 v[94:95], v[94:95], v[118:119]
	s_waitcnt vmcnt(6)
	v_pk_add_f32 v[92:93], v[92:93], v[124:125]
	v_pk_add_f32 v[90:91], v[90:91], v[122:123]
	s_waitcnt vmcnt(5)
	v_pk_add_f32 v[88:89], v[88:89], v[128:129]
	v_pk_add_f32 v[86:87], v[86:87], v[126:127]
	s_waitcnt vmcnt(4)
	v_pk_add_f32 v[120:121], v[84:85], v[132:133]
	v_pk_add_f32 v[118:119], v[82:83], v[130:131]
	global_store_dwordx4 v[136:137], v[94:97], off nt
	global_store_dwordx4 v[136:137], v[90:93], off offset:16 nt
	v_cvt_pk_bf16_f32 v82, v94, v95
	v_cvt_pk_bf16_f32 v83, v96, v97
	v_cvt_pk_bf16_f32 v84, v90, v91
	v_cvt_pk_bf16_f32 v85, v92, v93
	v_mul_f32_e32 v95, v95, v95
	v_mul_f32_e32 v97, v97, v97
	v_mul_f32_e32 v91, v91, v91
	v_mul_f32_e32 v93, v93, v93
	v_mul_f32_e32 v122, v87, v87
	v_mul_f32_e32 v123, v89, v89
	v_mul_f32_e32 v124, v119, v119
	v_mul_f32_e32 v125, v121, v121
	v_fmac_f32_e32 v95, v94, v94
	v_fmac_f32_e32 v97, v96, v96
	v_fmac_f32_e32 v91, v90, v90
	v_fmac_f32_e32 v93, v92, v92
	v_fmac_f32_e32 v122, v86, v86
	v_fmac_f32_e32 v123, v88, v88
	v_fmac_f32_e32 v124, v118, v118
	v_fmac_f32_e32 v125, v120, v120
	global_store_dwordx4 v[138:139], v[82:85], off
	global_store_dwordx4 v[136:137], v[86:89], off offset:512 nt
	global_store_dwordx4 v[136:137], v[118:121], off offset:528 nt
	v_add_f32_e32 v82, v95, v97
	v_add_f32_e32 v83, v91, v93
	v_add_f32_e32 v84, v122, v123
	v_add_f32_e32 v85, v124, v125
	v_add_f32_e32 v82, v82, v83
	v_add_f32_e32 v83, v84, v85
	v_add_f32_e32 v82, v82, v83
	ds_bpermute_b32 v83, v198, v82
	v_cvt_pk_bf16_f32 v84, v86, v87
	v_cvt_pk_bf16_f32 v85, v88, v89
	v_cvt_pk_bf16_f32 v86, v118, v119
	v_cvt_pk_bf16_f32 v87, v120, v121
	s_waitcnt lgkmcnt(0)
	v_add_f32_e32 v82, v82, v83
	ds_bpermute_b32 v83, v197, v82
	v_lshl_add_u64 v[88:89], v[134:135], 1, s[24:25]
	global_store_dwordx4 v[88:89], v[84:87], off
	s_and_saveexec_b64 s[16:17], s[2:3]
	s_cbranch_execz .LBB0_1754
	s_waitcnt lgkmcnt(0)
	v_add_f32_e32 v82, v82, v83
	ds_write_b32 v192, v82 offset:128
; #define LAS __attribute__((address_space(3)))
;     DEVI f32x4 load(int r, int c) const { const bf16x4 y = *(const bf16x4*)(Y + (size_t)r * DM + c); return (f32x4){bf2f((u16)y[0]), bf2f((u16)y[1]), bf2f((u16)y[2]), bf2f((u16)y[3])}; }
; template <class Epi>
; DEVI void gemm_phase(LAS unsigned char* lds, const Gemm g, const Epi& E) {
;     ...
;                             for (int n = 0; n < 2; ++n) pre[m][bj][n] = E.load(row0 + ai * HALF + (m0 + m) * 16, col0 + bj * HALF + n * NST);
;                 }
; #pragma unroll
;                 for (int mm = 0; mm < 2; ++mm) {
;                     const int m = m0 + mm;
;                     const int r = row0 + ai * HALF + m * 16; float rs = 1.f, part = 0.f;
;                     if constexpr (Epi::RS) rs = rsv[ai * 4 + m];
;                     if constexpr (Epi::PAIR) E.pair8(cur.b, r, cur.pn * HALF + wc * 32 + 8 * fq, acc[ai][0][m][0] * rs, acc[ai][0][m][1] * rs, acc[ai][1][m][0] * rs, acc[ai][1][m][1] * rs);
;                     else
; #pragma unroll
;                     for (int bj = 0; bj < 2; ++bj) {
;                         const int c = col0 + bj * HALF; f32x4 v0 = acc[ai][bj][m][0], v1 = acc[ai][bj][m][1];
;                         if constexpr (Epi::RS) { v0 = v0 * rs; v1 = v1 * rs; }
;                         if constexpr (Epi::PRE) part += E.frag_pre8(cur.b, r, c, v0, v1, pre[mm][bj][0], pre[mm][bj][1]);
;                         else if constexpr (Epi::PERM) E.frag8(cur.b, r, c, v0, v1);
;                         else { E.frag(cur.b, r, c, v0); E.frag(cur.b, r, c + 16, v1); }
;                     }
;                     if constexpr (Epi::SSQ) { part += __shfl_xor(part, 16); part += __shfl_xor(part, 32); if (fq == 0) ((LAS float*)(lds + 131072))[(wr * 4 + wc) * 128 + ai * 64 + m * 16 + fr] = part; }
.LBB0_1754:
	s_or_b64 exec, exec, s[16:17]
	s_waitcnt vmcnt(8)
	v_pk_add_f32 v[80:81], v[80:81], v[112:113]
	v_pk_add_f32 v[78:79], v[78:79], v[110:111]
	v_pk_add_f32 v[74:75], v[74:75], v[106:107]
	v_pk_add_f32 v[76:77], v[76:77], v[108:109]
	global_store_dwordx4 v[114:115], v[78:81], off nt
	global_store_dwordx4 v[114:115], v[74:77], off offset:16 nt
	v_cvt_pk_bf16_f32 v82, v78, v79
	v_cvt_pk_bf16_f32 v84, v74, v75
	v_mul_f32_e32 v79, v79, v79
	v_mul_f32_e32 v75, v75, v75
	v_fmac_f32_e32 v79, v78, v78
	v_mul_f32_e32 v78, v81, v81
	v_fmac_f32_e32 v75, v74, v74
	v_mul_f32_e32 v74, v77, v77
	v_fmac_f32_e32 v78, v80, v80
	v_fmac_f32_e32 v74, v76, v76
	v_add_f32_e32 v78, v79, v78
	v_add_f32_e32 v74, v75, v74
	s_waitcnt vmcnt(8)
	v_pk_add_f32 v[72:73], v[72:73], v[104:105]
	v_pk_add_f32 v[70:71], v[70:71], v[102:103]
	s_waitcnt lgkmcnt(0)
	v_cvt_pk_bf16_f32 v83, v80, v81
	v_add_f32_e32 v80, v78, v74
	v_pk_add_f32 v[74:75], v[66:67], v[98:99]
	v_mul_f32_e32 v66, v71, v71
	v_mul_f32_e32 v67, v73, v73
	v_cvt_pk_bf16_f32 v85, v76, v77
	v_pk_add_f32 v[76:77], v[68:69], v[100:101]
	v_fmac_f32_e32 v66, v70, v70
	v_fmac_f32_e32 v67, v72, v72
	v_add_f32_e32 v66, v66, v67
	v_mul_f32_e32 v67, v75, v75
	v_mul_f32_e32 v68, v77, v77
	v_fmac_f32_e32 v67, v74, v74
	v_fmac_f32_e32 v68, v76, v76
	v_add_f32_e32 v67, v67, v68
	v_add_f32_e32 v66, v66, v67
	v_add_f32_e32 v66, v80, v66
	ds_bpermute_b32 v67, v198, v66
	v_lshlrev_b64 v[86:87], 10, v[116:117]
	v_lshl_add_u64 v[88:89], v[86:87], 0, v[180:181]
	v_lshl_add_u64 v[88:89], v[88:89], 1, s[24:25]
	v_lshl_add_u64 v[78:79], v[86:87], 0, v[178:179]
	s_waitcnt lgkmcnt(0)
	v_add_f32_e32 v66, v66, v67
	ds_bpermute_b32 v67, v197, v66
	global_store_dwordx4 v[88:89], v[82:85], off
	global_store_dwordx4 v[114:115], v[70:73], off offset:512 nt
	global_store_dwordx4 v[114:115], v[74:77], off offset:528 nt
	v_cvt_pk_bf16_f32 v68, v70, v71
	v_cvt_pk_bf16_f32 v69, v72, v73
	v_cvt_pk_bf16_f32 v70, v74, v75
	v_cvt_pk_bf16_f32 v71, v76, v77
	v_lshl_add_u64 v[72:73], v[78:79], 1, s[24:25]
	global_store_dwordx4 v[72:73], v[68:71], off
	s_and_saveexec_b64 s[16:17], s[2:3]
	s_cbranch_execz .LBB0_1756
	s_waitcnt lgkmcnt(0)
	v_add_f32_e32 v66, v66, v67
	ds_write_b32 v192, v66 offset:192
.LBB0_1756:
	s_or_b64 exec, exec, s[16:17]
	v_add_u32_e32 v102, 0x80, v182
	v_ashrrev_i32_e32 v103, 31, v102
	s_waitcnt lgkmcnt(0)
	v_lshlrev_b64 v[66:67], 12, v[102:103]
	v_lshl_add_u64 v[66:67], s[30:31], 0, v[66:67]
	v_lshl_add_u64 v[104:105], v[66:67], 0, v[184:185]
	global_load_dwordx4 v[86:89], v[104:105], off
	global_load_dwordx4 v[90:93], v[104:105], off offset:16
	global_load_dwordx4 v[94:97], v[104:105], off offset:512
	global_load_dwordx4 v[98:101], v[104:105], off offset:528
	v_add_u32_e32 v84, 0x90, v182
	v_ashrrev_i32_e32 v85, 31, v84
	v_lshlrev_b64 v[66:67], 12, v[84:85]
	v_lshl_add_u64 v[66:67], s[30:31], 0, v[66:67]
	v_lshl_add_u64 v[82:83], v[66:67], 0, v[184:185]
	global_load_dwordx4 v[74:77], v[82:83], off offset:16
	global_load_dwordx4 v[78:81], v[82:83], off
	global_load_dwordx4 v[66:69], v[82:83], off offset:528
	global_load_dwordx4 v[70:73], v[82:83], off offset:512
	v_lshlrev_b64 v[102:103], 10, v[102:103]
	v_lshl_add_u64 v[106:107], v[102:103], 0, v[180:181]
	v_lshl_add_u64 v[106:107], v[106:107], 1, s[24:25]
	v_lshl_add_u64 v[102:103], v[102:103], 0, v[178:179]
	s_waitcnt vmcnt(7)
	v_pk_add_f32 v[64:65], v[64:65], v[88:89]
	v_pk_add_f32 v[62:63], v[62:63], v[86:87]
	s_waitcnt vmcnt(6)
	v_pk_add_f32 v[60:61], v[60:61], v[92:93]
	v_pk_add_f32 v[58:59], v[58:59], v[90:91]
	s_waitcnt vmcnt(5)
	v_pk_add_f32 v[56:57], v[56:57], v[96:97]
	v_pk_add_f32 v[54:55], v[54:55], v[94:95]
	s_waitcnt vmcnt(4)
	v_pk_add_f32 v[88:89], v[52:53], v[100:101]
	v_pk_add_f32 v[86:87], v[50:51], v[98:99]
	global_store_dwordx4 v[104:105], v[62:65], off nt
	global_store_dwordx4 v[104:105], v[58:61], off offset:16 nt
	v_cvt_pk_bf16_f32 v50, v62, v63
	v_cvt_pk_bf16_f32 v51, v64, v65
	v_cvt_pk_bf16_f32 v52, v58, v59
	v_cvt_pk_bf16_f32 v53, v60, v61
	v_mul_f32_e32 v63, v63, v63
	v_mul_f32_e32 v65, v65, v65
	v_mul_f32_e32 v59, v59, v59
	v_mul_f32_e32 v61, v61, v61
	v_mul_f32_e32 v90, v55, v55
	v_mul_f32_e32 v91, v57, v57
	v_mul_f32_e32 v92, v87, v87
	v_mul_f32_e32 v93, v89, v89
	v_fmac_f32_e32 v63, v62, v62
	v_fmac_f32_e32 v65, v64, v64
	v_fmac_f32_e32 v59, v58, v58
	v_fmac_f32_e32 v61, v60, v60
	v_fmac_f32_e32 v90, v54, v54
	v_fmac_f32_e32 v91, v56, v56
	v_fmac_f32_e32 v92, v86, v86
	v_fmac_f32_e32 v93, v88, v88
	global_store_dwordx4 v[106:107], v[50:53], off
	global_store_dwordx4 v[104:105], v[54:57], off offset:512 nt
	global_store_dwordx4 v[104:105], v[86:89], off offset:528 nt
	v_add_f32_e32 v50, v63, v65
	v_add_f32_e32 v51, v59, v61
	v_add_f32_e32 v52, v90, v91
	v_add_f32_e32 v53, v92, v93
	v_add_f32_e32 v50, v50, v51
	v_add_f32_e32 v51, v52, v53
	v_add_f32_e32 v50, v50, v51
	ds_bpermute_b32 v51, v198, v50
	v_cvt_pk_bf16_f32 v52, v54, v55
	v_cvt_pk_bf16_f32 v53, v56, v57
	v_cvt_pk_bf16_f32 v54, v86, v87
	v_cvt_pk_bf16_f32 v55, v88, v89
	s_waitcnt lgkmcnt(0)
	v_add_f32_e32 v50, v50, v51
	ds_bpermute_b32 v51, v197, v50
	v_lshl_add_u64 v[56:57], v[102:103], 1, s[24:25]
	global_store_dwordx4 v[56:57], v[52:55], off
	s_and_saveexec_b64 s[16:17], s[2:3]
	s_cbranch_execz .LBB0_1758
	s_waitcnt lgkmcnt(0)
	v_add_f32_e32 v50, v50, v51
	ds_write_b32 v192, v50 offset:256
; #define LAS __attribute__((address_space(3)))
; template <class Epi>
; DEVI void gemm_phase(LAS unsigned char* lds, const Gemm g, const Epi& E) {
;     ...
;                 for (int mm = 0; mm < 2; ++mm) {
;                     const int m = m0 + mm;
;                     const int r = row0 + ai * HALF + m * 16; float rs = 1.f, part = 0.f;
;                     if constexpr (Epi::RS) rs = rsv[ai * 4 + m];
;                     if constexpr (Epi::PAIR) E.pair8(cur.b, r, cur.pn * HALF + wc * 32 + 8 * fq, acc[ai][0][m][0] * rs, acc[ai][0][m][1] * rs, acc[ai][1][m][0] * rs, acc[ai][1][m][1] * rs);
;                     else
; #pragma unroll
;                     for (int bj = 0; bj < 2; ++bj) {
;                         const int c = col0 + bj * HALF; f32x4 v0 = acc[ai][bj][m][0], v1 = acc[ai][bj][m][1];
;                         if constexpr (Epi::RS) { v0 = v0 * rs; v1 = v1 * rs; }
;                         if constexpr (Epi::PRE) part += E.frag_pre8(cur.b, r, c, v0, v1, pre[mm][bj][0], pre[mm][bj][1]);
;                         else if constexpr (Epi::PERM) E.frag8(cur.b, r, c, v0, v1);
;                         else { E.frag(cur.b, r, c, v0); E.frag(cur.b, r, c + 16, v1); }
;                     }
;                     if constexpr (Epi::SSQ) { part += __shfl_xor(part, 16); part += __shfl_xor(part, 32); if (fq == 0) ((LAS float*)(lds + 131072))[(wr * 4 + wc) * 128 + ai * 64 + m * 16 + fr] = part; }
.LBB0_1758:
	s_or_b64 exec, exec, s[16:17]
	s_waitcnt vmcnt(8)
	v_pk_add_f32 v[48:49], v[48:49], v[80:81]
	v_pk_add_f32 v[46:47], v[46:47], v[78:79]
	v_pk_add_f32 v[42:43], v[42:43], v[74:75]
	v_pk_add_f32 v[44:45], v[44:45], v[76:77]
	global_store_dwordx4 v[82:83], v[46:49], off nt
	global_store_dwordx4 v[82:83], v[42:45], off offset:16 nt
	v_cvt_pk_bf16_f32 v50, v46, v47
	v_cvt_pk_bf16_f32 v52, v42, v43
	v_mul_f32_e32 v47, v47, v47
	v_mul_f32_e32 v43, v43, v43
	v_fmac_f32_e32 v47, v46, v46
	v_mul_f32_e32 v46, v49, v49
	v_fmac_f32_e32 v43, v42, v42
	v_mul_f32_e32 v42, v45, v45
	v_fmac_f32_e32 v46, v48, v48
	v_fmac_f32_e32 v42, v44, v44
	v_add_f32_e32 v46, v47, v46
	v_add_f32_e32 v42, v43, v42
	s_waitcnt vmcnt(8)
	v_pk_add_f32 v[40:41], v[40:41], v[72:73]
	v_pk_add_f32 v[38:39], v[38:39], v[70:71]
	s_waitcnt lgkmcnt(0)
	v_cvt_pk_bf16_f32 v51, v48, v49
	v_add_f32_e32 v48, v46, v42
	v_pk_add_f32 v[42:43], v[34:35], v[66:67]
	v_mul_f32_e32 v34, v39, v39
	v_mul_f32_e32 v35, v41, v41
	v_cvt_pk_bf16_f32 v53, v44, v45
	v_pk_add_f32 v[44:45], v[36:37], v[68:69]
	v_fmac_f32_e32 v34, v38, v38
	v_fmac_f32_e32 v35, v40, v40
	v_add_f32_e32 v34, v34, v35
	v_mul_f32_e32 v35, v43, v43
	v_mul_f32_e32 v36, v45, v45
	v_fmac_f32_e32 v35, v42, v42
	v_fmac_f32_e32 v36, v44, v44
	v_add_f32_e32 v35, v35, v36
	v_add_f32_e32 v34, v34, v35
	v_add_f32_e32 v34, v48, v34
	ds_bpermute_b32 v35, v198, v34
	v_lshlrev_b64 v[54:55], 10, v[84:85]
	v_lshl_add_u64 v[56:57], v[54:55], 0, v[180:181]
	v_lshl_add_u64 v[56:57], v[56:57], 1, s[24:25]
	v_lshl_add_u64 v[46:47], v[54:55], 0, v[178:179]
	s_waitcnt lgkmcnt(0)
	v_add_f32_e32 v34, v34, v35
	ds_bpermute_b32 v35, v197, v34
	global_store_dwordx4 v[56:57], v[50:53], off
	global_store_dwordx4 v[82:83], v[38:41], off offset:512 nt
	global_store_dwordx4 v[82:83], v[42:45], off offset:528 nt
	v_cvt_pk_bf16_f32 v36, v38, v39
	v_cvt_pk_bf16_f32 v37, v40, v41
	v_cvt_pk_bf16_f32 v38, v42, v43
	v_cvt_pk_bf16_f32 v39, v44, v45
	v_lshl_add_u64 v[40:41], v[46:47], 1, s[24:25]
	global_store_dwordx4 v[40:41], v[36:39], off
	s_and_saveexec_b64 s[16:17], s[2:3]
	s_cbranch_execz .LBB0_1760
	s_waitcnt lgkmcnt(0)
	v_add_f32_e32 v34, v34, v35
	ds_write_b32 v192, v34 offset:320
; #define LAS __attribute__((address_space(3)))
;     DEVI f32x4 load(int r, int c) const { const bf16x4 y = *(const bf16x4*)(Y + (size_t)r * DM + c); return (f32x4){bf2f((u16)y[0]), bf2f((u16)y[1]), bf2f((u16)y[2]), bf2f((u16)y[3])}; }
; template <class Epi>
; DEVI void gemm_phase(LAS unsigned char* lds, const Gemm g, const Epi& E) {
;     ...
;                 if constexpr (Epi::PRE) {
; #pragma unroll
;                     for (int m = 0; m < 2; ++m)
; #pragma unroll
;                         for (int bj = 0; bj < 2; ++bj)
; #pragma unroll
;                             for (int n = 0; n < 2; ++n) pre[m][bj][n] = E.load(row0 + ai * HALF + (m0 + m) * 16, col0 + bj * HALF + n * NST);
;                 }
; #pragma unroll
;                 for (int mm = 0; mm < 2; ++mm) {
;                     const int m = m0 + mm;
;                     const int r = row0 + ai * HALF + m * 16; float rs = 1.f, part = 0.f;
;                     if constexpr (Epi::RS) rs = rsv[ai * 4 + m];
;                     if constexpr (Epi::PAIR) E.pair8(cur.b, r, cur.pn * HALF + wc * 32 + 8 * fq, acc[ai][0][m][0] * rs, acc[ai][0][m][1] * rs, acc[ai][1][m][0] * rs, acc[ai][1][m][1] * rs);
;                     else
; #pragma unroll
;                     for (int bj = 0; bj < 2; ++bj) {
;                         const int c = col0 + bj * HALF; f32x4 v0 = acc[ai][bj][m][0], v1 = acc[ai][bj][m][1];
;                         if constexpr (Epi::RS) { v0 = v0 * rs; v1 = v1 * rs; }
;                         if constexpr (Epi::PRE) part += E.frag_pre8(cur.b, r, c, v0, v1, pre[mm][bj][0], pre[mm][bj][1]);
;                         else if constexpr (Epi::PERM) E.frag8(cur.b, r, c, v0, v1);
;                         else { E.frag(cur.b, r, c, v0); E.frag(cur.b, r, c + 16, v1); }
;                     }
;                     if constexpr (Epi::SSQ) { part += __shfl_xor(part, 16); part += __shfl_xor(part, 32); if (fq == 0) ((LAS float*)(lds + 131072))[(wr * 4 + wc) * 128 + ai * 64 + m * 16 + fr] = part; }
.LBB0_1760:
	s_or_b64 exec, exec, s[16:17]
	v_add_u32_e32 v70, 0xa0, v182
	v_ashrrev_i32_e32 v71, 31, v70
	s_waitcnt lgkmcnt(0)
	v_lshlrev_b64 v[34:35], 12, v[70:71]
	v_lshl_add_u64 v[34:35], s[30:31], 0, v[34:35]
	v_lshl_add_u64 v[72:73], v[34:35], 0, v[184:185]
	global_load_dwordx4 v[54:57], v[72:73], off
	global_load_dwordx4 v[58:61], v[72:73], off offset:16
	global_load_dwordx4 v[62:65], v[72:73], off offset:512
	global_load_dwordx4 v[66:69], v[72:73], off offset:528
	v_add_u32_e32 v52, 0xb0, v182
	v_ashrrev_i32_e32 v53, 31, v52
	v_lshlrev_b64 v[34:35], 12, v[52:53]
	v_lshl_add_u64 v[34:35], s[30:31], 0, v[34:35]
	v_lshl_add_u64 v[50:51], v[34:35], 0, v[184:185]
	global_load_dwordx4 v[42:45], v[50:51], off offset:16
	global_load_dwordx4 v[46:49], v[50:51], off
	global_load_dwordx4 v[34:37], v[50:51], off offset:528
	global_load_dwordx4 v[38:41], v[50:51], off offset:512
	v_lshlrev_b64 v[70:71], 10, v[70:71]
	v_lshl_add_u64 v[74:75], v[70:71], 0, v[180:181]
	v_lshl_add_u64 v[74:75], v[74:75], 1, s[24:25]
	v_lshl_add_u64 v[70:71], v[70:71], 0, v[178:179]
	s_waitcnt vmcnt(7)
	v_pk_add_f32 v[32:33], v[32:33], v[56:57]
	v_pk_add_f32 v[30:31], v[30:31], v[54:55]
	s_waitcnt vmcnt(6)
	v_pk_add_f32 v[28:29], v[28:29], v[60:61]
	v_pk_add_f32 v[26:27], v[26:27], v[58:59]
	s_waitcnt vmcnt(5)
	v_pk_add_f32 v[24:25], v[24:25], v[64:65]
	v_pk_add_f32 v[22:23], v[22:23], v[62:63]
	s_waitcnt vmcnt(4)
	v_pk_add_f32 v[56:57], v[20:21], v[68:69]
	v_pk_add_f32 v[54:55], v[18:19], v[66:67]
	global_store_dwordx4 v[72:73], v[30:33], off nt
	global_store_dwordx4 v[72:73], v[26:29], off offset:16 nt
	v_cvt_pk_bf16_f32 v18, v30, v31
	v_cvt_pk_bf16_f32 v19, v32, v33
	v_cvt_pk_bf16_f32 v20, v26, v27
	v_cvt_pk_bf16_f32 v21, v28, v29
	v_mul_f32_e32 v31, v31, v31
	v_mul_f32_e32 v33, v33, v33
	v_mul_f32_e32 v27, v27, v27
	v_mul_f32_e32 v29, v29, v29
	v_mul_f32_e32 v58, v23, v23
	v_mul_f32_e32 v59, v25, v25
	v_mul_f32_e32 v60, v55, v55
	v_mul_f32_e32 v61, v57, v57
	v_fmac_f32_e32 v31, v30, v30
	v_fmac_f32_e32 v33, v32, v32
	v_fmac_f32_e32 v27, v26, v26
	v_fmac_f32_e32 v29, v28, v28
	v_fmac_f32_e32 v58, v22, v22
	v_fmac_f32_e32 v59, v24, v24
	v_fmac_f32_e32 v60, v54, v54
	v_fmac_f32_e32 v61, v56, v56
	global_store_dwordx4 v[74:75], v[18:21], off
	global_store_dwordx4 v[72:73], v[22:25], off offset:512 nt
	global_store_dwordx4 v[72:73], v[54:57], off offset:528 nt
	v_add_f32_e32 v18, v31, v33
	v_add_f32_e32 v19, v27, v29
	v_add_f32_e32 v20, v58, v59
	v_add_f32_e32 v21, v60, v61
	v_add_f32_e32 v18, v18, v19
	v_add_f32_e32 v19, v20, v21
	v_add_f32_e32 v18, v18, v19
	ds_bpermute_b32 v19, v198, v18
	v_cvt_pk_bf16_f32 v20, v22, v23
	v_cvt_pk_bf16_f32 v21, v24, v25
	v_cvt_pk_bf16_f32 v22, v54, v55
	v_cvt_pk_bf16_f32 v23, v56, v57
	s_waitcnt lgkmcnt(0)
	v_add_f32_e32 v18, v18, v19
	ds_bpermute_b32 v19, v197, v18
	v_lshl_add_u64 v[24:25], v[70:71], 1, s[24:25]
	global_store_dwordx4 v[24:25], v[20:23], off
	s_and_saveexec_b64 s[16:17], s[2:3]
	s_cbranch_execz .LBB0_1762
	s_waitcnt lgkmcnt(0)
	v_add_f32_e32 v18, v18, v19
	ds_write_b32 v192, v18 offset:384
.LBB0_1762:
	s_or_b64 exec, exec, s[16:17]
	s_waitcnt vmcnt(8)
	v_pk_add_f32 v[16:17], v[16:17], v[48:49]
	v_pk_add_f32 v[14:15], v[14:15], v[46:47]
	v_pk_add_f32 v[10:11], v[10:11], v[42:43]
	v_pk_add_f32 v[12:13], v[12:13], v[44:45]
	global_store_dwordx4 v[50:51], v[14:17], off nt
	global_store_dwordx4 v[50:51], v[10:13], off offset:16 nt
	v_cvt_pk_bf16_f32 v18, v14, v15
	v_cvt_pk_bf16_f32 v20, v10, v11
	v_mul_f32_e32 v15, v15, v15
	v_mul_f32_e32 v11, v11, v11
	v_fmac_f32_e32 v15, v14, v14
	v_mul_f32_e32 v14, v17, v17
	v_fmac_f32_e32 v11, v10, v10
	v_mul_f32_e32 v10, v13, v13
	v_fmac_f32_e32 v14, v16, v16
	v_fmac_f32_e32 v10, v12, v12
	v_add_f32_e32 v14, v15, v14
	v_add_f32_e32 v10, v11, v10
	s_waitcnt vmcnt(8)
	v_pk_add_f32 v[6:7], v[6:7], v[40:41]
	v_pk_add_f32 v[4:5], v[4:5], v[38:39]
	s_waitcnt lgkmcnt(0)
	v_cvt_pk_bf16_f32 v19, v16, v17
	v_add_f32_e32 v16, v14, v10
	v_pk_add_f32 v[10:11], v[0:1], v[34:35]
	v_mul_f32_e32 v0, v5, v5
	v_mul_f32_e32 v1, v7, v7
	v_cvt_pk_bf16_f32 v21, v12, v13
	v_pk_add_f32 v[12:13], v[2:3], v[36:37]
	v_fmac_f32_e32 v0, v4, v4
	v_fmac_f32_e32 v1, v6, v6
	v_add_f32_e32 v0, v0, v1
	v_mul_f32_e32 v1, v11, v11
	v_mul_f32_e32 v2, v13, v13
	v_fmac_f32_e32 v1, v10, v10
	v_fmac_f32_e32 v2, v12, v12
	v_add_f32_e32 v1, v1, v2
	v_add_f32_e32 v0, v0, v1
	v_add_f32_e32 v0, v16, v0
	ds_bpermute_b32 v1, v198, v0
	v_lshlrev_b64 v[22:23], 10, v[52:53]
	v_lshl_add_u64 v[24:25], v[22:23], 0, v[180:181]
	v_lshl_add_u64 v[24:25], v[24:25], 1, s[24:25]
	v_lshl_add_u64 v[14:15], v[22:23], 0, v[178:179]
	s_waitcnt lgkmcnt(0)
	v_add_f32_e32 v0, v0, v1
	ds_bpermute_b32 v1, v197, v0
	global_store_dwordx4 v[24:25], v[18:21], off
	global_store_dwordx4 v[50:51], v[4:7], off offset:512 nt
	global_store_dwordx4 v[50:51], v[10:13], off offset:528 nt
	v_cvt_pk_bf16_f32 v2, v4, v5
	v_cvt_pk_bf16_f32 v3, v6, v7
	v_cvt_pk_bf16_f32 v4, v10, v11
	v_cvt_pk_bf16_f32 v5, v12, v13
	v_lshl_add_u64 v[6:7], v[14:15], 1, s[24:25]
	global_store_dwordx4 v[6:7], v[2:5], off
	s_and_saveexec_b64 s[16:17], s[2:3]
	s_cbranch_execz .LBB0_1764
	s_waitcnt lgkmcnt(0)
	v_add_f32_e32 v0, v0, v1
	ds_write_b32 v192, v0 offset:448
